# skip redundant layer-1 P0 grid barrier; converter set generalized to any grid size
# speedup vs baseline: 1.0045x; 1.0045x over previous
; #define LAS __attribute__((address_space(3)))
; #define PHASE_ENV unsigned char* ws = opq_ptr(p.ws); const int G = opq_int((int)gridDim.x), ngw = G * 8; (void)ws; (void)ngw
; __global__ void __launch_bounds__(512, 2) mega_fwd(Params p) {
;     ...
;         GSYNC;
;         { PHASE_ENV; pg8::StaticOrder SO; pg8::Gemm g{P_XB, P_W(WS_WGU1), M, 2 * DFF, D}; SO.init(M, 2 * DFF, G, blockIdx.x); stage_row_ss(lds, P_SS + (size_t)(3 * l) * 8 * M, SO); EpiSwiGLU E{P_HID, (const LAS float*)(lds + LDS_RS)}; pg8::gemm_phase(lds, g, SO, E); }
.LBB0_96:
	s_cmp_lg_u32 s36, 0
	s_cbranch_scc0 .Lp0sync_do
	s_mov_b32 s95, 0x60000
	s_branch .Lp0sync_skip

; #define LAS __attribute__((address_space(3)))
; __device__ __forceinline__ int otid() { int x = threadIdx.x; asm volatile("" : "+v"(x)); return x; }
; __device__ __forceinline__ void stage_row_ss(LAS unsigned char* lds, const float* SS, const pg8::StaticOrder& S) {
;     LAS float* RS = (LAS float*)(lds + LDS_RS);
;     const int tid = otid(), wave = __builtin_amdgcn_readfirstlane(tid >> 6), lane = tid & 63;
;     pg8::Unit u;
;     if (S.next(wave, u)) {
;         const float* sp = SS + u.pm * 256 + lane;
;         float a[4];
; #pragma unroll
;         for (int j = 0; j < 4; ++j) a[j] = 0.f;
; #pragma unroll
;         for (int t = 0; t < 8; ++t)
; #pragma unroll
;             for (int j = 0; j < 4; ++j) a[j] += sp[(size_t)t * M + 64 * j];
; #pragma unroll
;         for (int j = 0; j < 4; ++j) { RS[wave * 256 + lane + 64 * j] = a[j]; RS[2048 + wave * 256 + lane + 64 * j] = 0.f; }
;     }
;     __syncthreads();
; }
.Lp0sync_skip:
	s_mov_b32 s0, s91
	s_xor_b64 s[60:61], s[38:39], -1
	s_waitcnt lgkmcnt(0)
	s_barrier
	s_ashr_i32 s1, s0, 31
	s_mov_b32 s30, s78
	s_waitcnt vmcnt(0)
	v_mov_b32_e32 v0, v234
	s_add_u32 s28, s76, s0
	s_addc_u32 s29, s77, s1
	v_readfirstlane_b32 s0, v0
	s_ashr_i32 s4, s0, 6
	s_mul_i32 s0, s4, s30
	s_mul_hi_i32 s1, s4, s30
	s_add_u32 s0, s0, s2
	s_addc_u32 s1, s1, s47
	v_mov_b64_e32 v[2:3], 0x57f
	v_cmp_gt_i64_e32 vcc, s[0:1], v[2:3]
	s_mul_i32 s62, s36, 0x30000
	s_mov_b32 s63, s91
	s_cbranch_vccnz .LBB0_142
	s_lshl_b64 s[6:7], s[62:63], 2
	s_add_u32 s5, s28, s6
	s_addc_u32 s6, s29, s7
	s_ashr_i32 s1, s0, 31
	s_lshr_b32 s1, s1, 29
	s_add_i32 s1, s0, s1
	s_ashr_i32 s7, s1, 3
	s_and_b32 s1, s1, -8
	s_sub_i32 s0, s0, s1
	s_cmp_lt_i32 s0, 0
	s_cselect_b32 s1, s56, 0xb0
	s_mul_i32 s0, s0, s1
	s_add_i32 s0, s0, s7
	s_mul_hi_i32 s1, s0, 0x2e8ba2e9
	s_lshr_b32 s7, s1, 31
	s_ashr_i32 s1, s1, 6
	s_add_i32 s1, s1, s7
	s_mul_i32 s7, s1, 0x160
	s_lshl_b32 s1, s1, 3
	s_sub_i32 s0, s0, s7
	s_sub_i32 s7, 32, s1
	s_min_i32 s7, s7, 8
	s_abs_i32 s7, s7
	v_cvt_f32_u32_e32 v1, s7
	s_sub_i32 s9, 0, s7
	s_ashr_i32 s8, s0, 31
	s_abs_i32 s0, s0
	v_rcp_iflag_f32_e32 v1, v1
	v_lshlrev_b32_e32 v0, 2, v0
	v_and_b32_e32 v192, 0xfc, v0
	v_mul_f32_e32 v1, 0x4f7ffffe, v1
	v_cvt_u32_f32_e32 v1, v1
	s_nop 0
	v_readfirstlane_b32 s10, v1
	s_mul_i32 s9, s9, s10
	s_mul_hi_u32 s9, s10, s9
	s_add_i32 s10, s10, s9
	s_mul_hi_u32 s9, s0, s10
	s_mul_i32 s9, s9, s7
	s_sub_i32 s0, s0, s9
	s_sub_i32 s9, s0, s7
	s_cmp_ge_u32 s0, s7
	s_cselect_b32 s0, s9, s0
	s_sub_i32 s9, s0, s7
	s_cmp_ge_u32 s0, s7
	s_cselect_b32 s0, s9, s0
	s_xor_b32 s0, s0, s8
	s_sub_i32 s0, s0, s8
	s_add_i32 s1, s1, s0
	s_lshl_b32 s0, s1, 8
	s_ashr_i32 s1, s0, 31
	s_lshl_b64 s[0:1], s[0:1], 2
	s_add_u32 s0, s5, s0
	s_addc_u32 s1, s6, s1
	v_lshl_add_u64 v[0:1], s[0:1], 0, v[192:193]
	s_mov_b64 s[0:1], 0x2a840000
	v_lshl_add_u64 v[2:3], v[0:1], 0, s[0:1]
	s_mov_b32 s0, 0x2a840000
	v_add_co_u32_e32 v4, vcc, s0, v0
	global_load_dword v6, v[2:3], off offset:512
	s_nop 0
	v_addc_co_u32_e32 v5, vcc, 0, v1, vcc
	global_load_dword v4, v[4:5], off
	s_mov_b32 s0, 0x2a848000
	global_load_dword v5, v[2:3], off offset:256
	s_waitcnt vmcnt(2)
	v_add_f32_e32 v6, 0, v6
	global_load_dword v2, v[2:3], off offset:768
	s_waitcnt vmcnt(2)
	v_add_f32_e32 v4, 0, v4
	s_waitcnt vmcnt(1)
	v_add_f32_e32 v5, 0, v5
	s_waitcnt vmcnt(0)
	v_add_f32_e32 v7, 0, v2
	v_add_co_u32_e32 v2, vcc, s0, v0
	s_mov_b32 s0, 0x2a850000
	s_nop 0
	v_addc_co_u32_e32 v3, vcc, 0, v1, vcc
	global_load_dword v8, v[2:3], off
	s_waitcnt vmcnt(0)
	v_add_f32_e32 v4, v4, v8
	global_load_dword v8, v[2:3], off offset:256
	s_waitcnt vmcnt(0)
	v_add_f32_e32 v5, v5, v8
	global_load_dword v8, v[2:3], off offset:512
	s_waitcnt vmcnt(0)
	v_add_f32_e32 v6, v6, v8
	global_load_dword v2, v[2:3], off offset:768
	s_waitcnt vmcnt(0)
	v_add_f32_e32 v7, v7, v2
	v_add_co_u32_e32 v2, vcc, s0, v0
	s_mov_b32 s0, 0x2a858000
	s_nop 0
	v_addc_co_u32_e32 v3, vcc, 0, v1, vcc
	global_load_dword v8, v[2:3], off
	s_waitcnt vmcnt(0)
	v_add_f32_e32 v4, v4, v8
	global_load_dword v8, v[2:3], off offset:256
	s_waitcnt vmcnt(0)
	v_add_f32_e32 v5, v5, v8
	global_load_dword v8, v[2:3], off offset:512
	s_waitcnt vmcnt(0)
	v_add_f32_e32 v6, v6, v8
	global_load_dword v2, v[2:3], off offset:768
	s_waitcnt vmcnt(0)
	v_add_f32_e32 v7, v7, v2
	v_add_co_u32_e32 v2, vcc, s0, v0
	s_mov_b32 s0, 0x2a860000
	s_nop 0
	v_addc_co_u32_e32 v3, vcc, 0, v1, vcc
	global_load_dword v8, v[2:3], off
	s_waitcnt vmcnt(0)
	v_add_f32_e32 v4, v4, v8
	global_load_dword v8, v[2:3], off offset:256
	s_waitcnt vmcnt(0)
	v_add_f32_e32 v5, v5, v8
	global_load_dword v8, v[2:3], off offset:512
	s_waitcnt vmcnt(0)
	v_add_f32_e32 v6, v6, v8
	global_load_dword v2, v[2:3], off offset:768
	s_waitcnt vmcnt(0)
	v_add_f32_e32 v7, v7, v2
	v_add_co_u32_e32 v2, vcc, s0, v0
	s_mov_b32 s0, 0x2a868000
	s_nop 0
	v_addc_co_u32_e32 v3, vcc, 0, v1, vcc
	global_load_dword v8, v[2:3], off
	s_waitcnt vmcnt(0)
	v_add_f32_e32 v4, v4, v8
	global_load_dword v8, v[2:3], off offset:256
	s_waitcnt vmcnt(0)
	v_add_f32_e32 v5, v5, v8
	global_load_dword v8, v[2:3], off offset:512
	s_waitcnt vmcnt(0)
	v_add_f32_e32 v6, v6, v8
	global_load_dword v2, v[2:3], off offset:768
	s_waitcnt vmcnt(0)
	v_add_f32_e32 v7, v7, v2
	v_add_co_u32_e32 v2, vcc, s0, v0
	s_mov_b32 s0, 0x2a870000
	s_nop 0
	v_addc_co_u32_e32 v3, vcc, 0, v1, vcc
	global_load_dword v8, v[2:3], off
	s_waitcnt vmcnt(0)
	v_add_f32_e32 v4, v4, v8
	global_load_dword v8, v[2:3], off offset:256
	s_waitcnt vmcnt(0)
	v_add_f32_e32 v5, v5, v8
	global_load_dword v8, v[2:3], off offset:512
	s_waitcnt vmcnt(0)
	v_add_f32_e32 v6, v6, v8
	global_load_dword v2, v[2:3], off offset:768
	s_waitcnt vmcnt(0)
	v_add_f32_e32 v7, v7, v2
	v_add_co_u32_e32 v2, vcc, s0, v0
	s_mov_b32 s0, 0x2a878000
	s_nop 0
	v_addc_co_u32_e32 v3, vcc, 0, v1, vcc
	global_load_dword v8, v[2:3], off
	v_add_co_u32_e32 v0, vcc, s0, v0
	s_lshl_b32 s0, s4, 10
	s_nop 0
	v_addc_co_u32_e32 v1, vcc, 0, v1, vcc
	s_add_i32 s0, s0, 0
	s_waitcnt vmcnt(0)
	v_add_f32_e32 v4, v4, v8
	global_load_dword v8, v[2:3], off offset:256
	s_waitcnt vmcnt(0)
	v_add_f32_e32 v5, v5, v8
	global_load_dword v8, v[2:3], off offset:512
	s_waitcnt vmcnt(0)
	v_add_f32_e32 v6, v6, v8
	global_load_dword v2, v[2:3], off offset:768
	s_waitcnt vmcnt(0)
	v_add_f32_e32 v2, v7, v2
	global_load_dword v3, v[0:1], off
	s_waitcnt vmcnt(0)
	v_add_f32_e32 v3, v4, v3
	global_load_dword v4, v[0:1], off offset:256
	s_waitcnt vmcnt(0)
	v_add_f32_e32 v4, v5, v4
	global_load_dword v5, v[0:1], off offset:512
	s_waitcnt vmcnt(0)
	v_add_f32_e32 v5, v6, v5
	global_load_dword v0, v[0:1], off offset:768
	v_add_u32_e32 v1, s0, v192
	v_add_u32_e32 v1, 0x20000, v1
	s_waitcnt vmcnt(0)
	v_add_f32_e32 v0, v2, v0
	ds_write2st64_b32 v1, v3, v4 offset1:1
	ds_write2st64_b32 v1, v193, v193 offset0:32 offset1:33
	ds_write2st64_b32 v1, v5, v0 offset0:2 offset1:3
	ds_write2st64_b32 v1, v193, v193 offset0:34 offset1:35

; __device__ __forceinline__ void tr_load(const float* W, int N, int item, int lane, float (&wv)[32]) {
;     const int nblk = N / 32, kb = item / nblk, nb = item % nblk, k0 = 64 * kb, n0 = 32 * nb;
; #pragma unroll
;     for (int i = 0; i < 32; ++i) { const int kk = 2 * i + (lane >> 5); wv[i] = __builtin_nontemporal_load(W + (size_t)(k0 + kk) * N + n0 + (lane & 31)); }
; }
; template <int MAP, bool HASG, bool PERMW>
; __device__ __forceinline__ void tr_store(int K, int N, bf16_t* WT, LAS float* scr, int item, int lane, const float* gk) {
;     const int nblk = N / 32, kb = item / nblk, nb = item % nblk, k0 = 64 * kb, n0 = 32 * nb;
;     asm volatile("s_waitcnt lgkmcnt(0)" ::: "memory");
;     const int c = lane & 7;
;     f32x4 g0 = {1.f, 1.f, 1.f, 1.f}, g1 = {1.f, 1.f, 1.f, 1.f};
;     if (HASG) { g0 = *(const f32x4*)(gk + k0 + 8 * c); g1 = *(const f32x4*)(gk + k0 + 8 * c + 4); }
; #pragma unroll
;     for (int j = 0; j < 4; ++j) { const int n = (lane >> 3) + 8 * j; const LAS float* s = scr + (8 * c) * 33 + n;
;         u32x4 o; o.x = pk2(s[0 * 33] * g0[0], s[1 * 33] * g0[1]); o.y = pk2(s[2 * 33] * g0[2], s[3 * 33] * g0[3]); o.z = pk2(s[4 * 33] * g1[0], s[5 * 33] * g1[1]); o.w = pk2(s[6 * 33] * g1[2], s[7 * 33] * g1[3]);
;         const int wr_ = rowmap<MAP>(n0 + n), slot_ = PERMW ? ((wr_ & ~31) + invperm32(wr_ & 31)) : wr_;
;         *(u32x4*)((char*)WT + tiled_off(slot_, k0 + 8 * c, K / 64)) = o; }
;     asm volatile("s_waitcnt lgkmcnt(0)" ::: "memory");
; }
; template <int MAP, bool HASG = false, bool PERMW = false>
; __device__ __forceinline__ void transpose_mat(const float* W, int K, int N, bf16_t* WT, LAS float* scr, int gw, int ngw, int lane, const float* gk = nullptr) {
;     const int nitems = (K / 64) * (N / 32);
;     int it = gw;
;     if (it >= nitems) return;
;     float wv[32];
;     tr_load(W, N, it, lane, wv);
;     for (;;) {
;         __builtin_amdgcn_sched_barrier(0);
; #pragma unroll
;         for (int i = 0; i < 32; ++i) { const int kk = 2 * i + (lane >> 5); scr[kk * 33 + (lane & 31)] = wv[i]; }
;         __builtin_amdgcn_sched_barrier(0);
;         const int nx = it + ngw;
;         if (nx < nitems) tr_load(W, N, nx, lane, wv);
;         __builtin_amdgcn_sched_barrier(0);
;         tr_store<MAP, HASG, PERMW>(K, N, WT, scr, it, lane, gk);
;         if (nx >= nitems) break;
;         it = nx;
;     }
; }
.LBB0_158:
	s_lshr_b32 vcc_lo, s78, 1
	s_cmp_lt_u32 s2, vcc_lo
	s_cbranch_scc1 .Ltc1_done
	v_writelane_b32 v255, s4, 24
	v_writelane_b32 v255, s5, 25
	v_writelane_b32 v255, s6, 26
	v_writelane_b32 v255, s7, 27
	v_writelane_b32 v255, s8, 28
	v_writelane_b32 v255, s9, 29
	v_writelane_b32 v255, s10, 30
	v_writelane_b32 v255, s11, 31
	v_writelane_b32 v255, s12, 32
	v_writelane_b32 v255, s13, 33
	v_writelane_b32 v255, s14, 34
	v_writelane_b32 v255, s15, 35
	v_writelane_b32 v255, s16, 36
	v_writelane_b32 v255, s17, 37
	v_writelane_b32 v255, s18, 38
	v_writelane_b32 v255, s19, 39
	v_writelane_b32 v255, s20, 40
	v_writelane_b32 v255, s21, 41
	v_writelane_b32 v255, s22, 42
	v_writelane_b32 v255, s23, 43
	v_writelane_b32 v255, s24, 44
	v_writelane_b32 v255, s25, 45
	v_writelane_b32 v255, s26, 46
	v_writelane_b32 v255, s27, 47
	v_writelane_b32 v255, s28, 48
	v_writelane_b32 v255, s29, 49
	v_readfirstlane_b32 s8, v234
	s_nop 3
	s_lshr_b32 s8, s8, 6
	s_lshr_b32 s19, s78, 1
	s_sub_u32 s18, s2, s19
	s_lshl_b32 s18, s18, 3
	s_add_u32 s18, s18, s8
	s_sub_u32 s19, s78, s19
	s_lshl_b32 s19, s19, 3
	s_mul_i32 s10, s8, 0x2100
	v_and_b32_e32 v0, 63, v234
	v_and_b32_e32 v1, 31, v0
	v_lshrrev_b32_e32 v2, 5, v0
	v_lshlrev_b32_e32 v3, 13, v2
	v_lshl_add_u32 v3, v1, 2, v3
	v_mul_u32_u24_e32 v4, 33, v2
	v_add_u32_e32 v4, v4, v1
	v_lshl_add_u32 v4, v4, 2, s10
	v_and_b32_e32 v5, 7, v0
	v_lshrrev_b32_e32 v6, 3, v0
	v_mul_u32_u24_e32 v7, 0x108, v5
	v_add_u32_e32 v7, v7, v6
	v_lshl_add_u32 v7, v7, 2, s10
	v_lshrrev_b32_e32 v12, 2, v5
	v_lshlrev_b32_e32 v12, 10, v12
	v_and_b32_e32 v13, 3, v5
	v_lshl_add_u32 v12, v13, 4, v12
	v_lshl_add_u32 v8, v6, 6, v12
	v_xor_b32_e32 v9, 32, v8
	v_add_u32_e32 v9, 0x200, v9
	v_and_b32_e32 v13, 3, v6
	v_lshl_add_u32 v10, v13, 6, v12
	v_bfe_u32 v13, v6, 2, 1
	v_lshl_add_u32 v10, v13, 11, v10
	v_xor_b32_e32 v11, 32, v10
	v_lshlrev_b32_e32 v14, 5, v5
	v_mul_u32_u24_e32 v15, 0x5800, v2
	v_lshl_add_u32 v15, v1, 2, v15
	v_mul_u32_u24_e32 v12, 0xd000, v2
	v_lshl_add_u32 v12, v1, 2, v12
	v_readlane_b32 s4, v255, 4
	v_readlane_b32 s5, v255, 5
	s_nop 3
	s_and_b32 s6, s60, 0x2c00000
	s_add_u32 s4, s4, s6
	s_addc_u32 s5, s5, 0
	s_add_u32 s6, s76, 0x2c00000
	s_addc_u32 s7, s77, 0
	s_mov_b32 s9, s18
	s_cmpk_ge_u32 s9, 0x1600
	s_cbranch_scc1 .Ltc1a_exit
	s_lshr_b32 s11, s9, 6
	s_and_b32 s12, s9, 63
	s_lshl_b32 s13, s11, 19
	s_lshl_b32 s14, s12, 7
	s_add_u32 s13, s13, s14
	s_add_u32 s14, s4, s13
	s_addc_u32 s15, s5, 0
	global_load_dword v16, v3, s[14:15] nt
	s_add_u32 s14, s14, 0x4000
	s_addc_u32 s15, s15, 0
	global_load_dword v17, v3, s[14:15] nt
	s_add_u32 s14, s14, 0x4000
	s_addc_u32 s15, s15, 0
	global_load_dword v18, v3, s[14:15] nt
	s_add_u32 s14, s14, 0x4000
	s_addc_u32 s15, s15, 0
	global_load_dword v19, v3, s[14:15] nt
	s_add_u32 s14, s14, 0x4000
	s_addc_u32 s15, s15, 0
	global_load_dword v20, v3, s[14:15] nt
	s_add_u32 s14, s14, 0x4000
	s_addc_u32 s15, s15, 0
	global_load_dword v21, v3, s[14:15] nt
	s_add_u32 s14, s14, 0x4000
	s_addc_u32 s15, s15, 0
	global_load_dword v22, v3, s[14:15] nt
	s_add_u32 s14, s14, 0x4000
	s_addc_u32 s15, s15, 0
	global_load_dword v23, v3, s[14:15] nt
	s_add_u32 s14, s14, 0x4000
	s_addc_u32 s15, s15, 0
	global_load_dword v24, v3, s[14:15] nt
	s_add_u32 s14, s14, 0x4000
	s_addc_u32 s15, s15, 0
	global_load_dword v25, v3, s[14:15] nt
	s_add_u32 s14, s14, 0x4000
	s_addc_u32 s15, s15, 0
	global_load_dword v26, v3, s[14:15] nt
	s_add_u32 s14, s14, 0x4000
	s_addc_u32 s15, s15, 0
	global_load_dword v27, v3, s[14:15] nt
	s_add_u32 s14, s14, 0x4000
	s_addc_u32 s15, s15, 0
	global_load_dword v28, v3, s[14:15] nt
	s_add_u32 s14, s14, 0x4000
	s_addc_u32 s15, s15, 0
	global_load_dword v29, v3, s[14:15] nt
	s_add_u32 s14, s14, 0x4000
	s_addc_u32 s15, s15, 0
	global_load_dword v30, v3, s[14:15] nt
	s_add_u32 s14, s14, 0x4000
	s_addc_u32 s15, s15, 0
	global_load_dword v31, v3, s[14:15] nt
	s_add_u32 s14, s14, 0x4000
	s_addc_u32 s15, s15, 0
	global_load_dword v32, v3, s[14:15] nt
	s_add_u32 s14, s14, 0x4000
	s_addc_u32 s15, s15, 0
	global_load_dword v33, v3, s[14:15] nt
	s_add_u32 s14, s14, 0x4000
	s_addc_u32 s15, s15, 0
	global_load_dword v34, v3, s[14:15] nt
	s_add_u32 s14, s14, 0x4000
	s_addc_u32 s15, s15, 0
	global_load_dword v35, v3, s[14:15] nt
	s_add_u32 s14, s14, 0x4000
	s_addc_u32 s15, s15, 0
	global_load_dword v36, v3, s[14:15] nt
	s_add_u32 s14, s14, 0x4000
	s_addc_u32 s15, s15, 0
	global_load_dword v37, v3, s[14:15] nt
	s_add_u32 s14, s14, 0x4000
	s_addc_u32 s15, s15, 0
	global_load_dword v38, v3, s[14:15] nt
	s_add_u32 s14, s14, 0x4000
	s_addc_u32 s15, s15, 0
	global_load_dword v39, v3, s[14:15] nt
	s_add_u32 s14, s14, 0x4000
	s_addc_u32 s15, s15, 0
	global_load_dword v40, v3, s[14:15] nt
	s_add_u32 s14, s14, 0x4000
	s_addc_u32 s15, s15, 0
	global_load_dword v41, v3, s[14:15] nt
	s_add_u32 s14, s14, 0x4000
	s_addc_u32 s15, s15, 0
	global_load_dword v42, v3, s[14:15] nt
	s_add_u32 s14, s14, 0x4000
	s_addc_u32 s15, s15, 0
	global_load_dword v43, v3, s[14:15] nt
	s_add_u32 s14, s14, 0x4000
	s_addc_u32 s15, s15, 0
	global_load_dword v44, v3, s[14:15] nt
	s_add_u32 s14, s14, 0x4000
	s_addc_u32 s15, s15, 0
	global_load_dword v45, v3, s[14:15] nt
	s_add_u32 s14, s14, 0x4000
	s_addc_u32 s15, s15, 0
	global_load_dword v46, v3, s[14:15] nt
	s_add_u32 s14, s14, 0x4000
	s_addc_u32 s15, s15, 0
	global_load_dword v47, v3, s[14:15] nt
	s_lshr_b32 s16, s12, 2
	s_mul_i32 s16, s16, 0x58
	s_add_u32 s16, s16, s11
	s_lshl_b32 s16, s16, 14
	s_and_b32 s17, s12, 3
	s_lshl_b32 s17, s17, 12
	s_add_u32 s16, s16, s17
	s_add_u32 s16, s6, s16
	s_addc_u32 s17, s7, 0
; __device__ __forceinline__ void tr_load(const float* W, int N, int item, int lane, float (&wv)[32]) {
;     const int nblk = N / 32, kb = item / nblk, nb = item % nblk, k0 = 64 * kb, n0 = 32 * nb;
; #pragma unroll
;     for (int i = 0; i < 32; ++i) { const int kk = 2 * i + (lane >> 5); wv[i] = __builtin_nontemporal_load(W + (size_t)(k0 + kk) * N + n0 + (lane & 31)); }
; }
; template <int MAP, bool HASG, bool PERMW>
; __device__ __forceinline__ void tr_store(int K, int N, bf16_t* WT, LAS float* scr, int item, int lane, const float* gk) {
;     const int nblk = N / 32, kb = item / nblk, nb = item % nblk, k0 = 64 * kb, n0 = 32 * nb;
;     asm volatile("s_waitcnt lgkmcnt(0)" ::: "memory");
;     const int c = lane & 7;
;     f32x4 g0 = {1.f, 1.f, 1.f, 1.f}, g1 = {1.f, 1.f, 1.f, 1.f};
;     if (HASG) { g0 = *(const f32x4*)(gk + k0 + 8 * c); g1 = *(const f32x4*)(gk + k0 + 8 * c + 4); }
; #pragma unroll
;     for (int j = 0; j < 4; ++j) { const int n = (lane >> 3) + 8 * j; const LAS float* s = scr + (8 * c) * 33 + n;
;         u32x4 o; o.x = pk2(s[0 * 33] * g0[0], s[1 * 33] * g0[1]); o.y = pk2(s[2 * 33] * g0[2], s[3 * 33] * g0[3]); o.z = pk2(s[4 * 33] * g1[0], s[5 * 33] * g1[1]); o.w = pk2(s[6 * 33] * g1[2], s[7 * 33] * g1[3]);
;         const int wr_ = rowmap<MAP>(n0 + n), slot_ = PERMW ? ((wr_ & ~31) + invperm32(wr_ & 31)) : wr_;
;         *(u32x4*)((char*)WT + tiled_off(slot_, k0 + 8 * c, K / 64)) = o; }
;     asm volatile("s_waitcnt lgkmcnt(0)" ::: "memory");
; }
; template <int MAP, bool HASG = false, bool PERMW = false>
; __device__ __forceinline__ void transpose_mat(const float* W, int K, int N, bf16_t* WT, LAS float* scr, int gw, int ngw, int lane, const float* gk = nullptr) {
;     const int nitems = (K / 64) * (N / 32);
;     int it = gw;
;     if (it >= nitems) return;
;     float wv[32];
;     tr_load(W, N, it, lane, wv);
;     for (;;) {
;         __builtin_amdgcn_sched_barrier(0);
; #pragma unroll
;         for (int i = 0; i < 32; ++i) { const int kk = 2 * i + (lane >> 5); scr[kk * 33 + (lane & 31)] = wv[i]; }
;         __builtin_amdgcn_sched_barrier(0);
;         const int nx = it + ngw;
;         if (nx < nitems) tr_load(W, N, nx, lane, wv);
;         __builtin_amdgcn_sched_barrier(0);
;         tr_store<MAP, HASG, PERMW>(K, N, WT, scr, it, lane, gk);
;         if (nx >= nitems) break;
;         it = nx;
;     }
; }
.Ltc1a_loop:
	s_add_u32 s9, s9, s19
	s_cmpk_ge_u32 s9, 0x1600
	s_cbranch_scc1 .Ltc1a_lastA
	s_lshr_b32 s11, s9, 6
	s_and_b32 s12, s9, 63
	s_lshl_b32 s13, s11, 19
	s_lshl_b32 s14, s12, 7
	s_add_u32 s13, s13, s14
	s_add_u32 s14, s4, s13
	s_addc_u32 s15, s5, 0
	global_load_dword v88, v3, s[14:15] nt
	s_add_u32 s14, s14, 0x4000
	s_addc_u32 s15, s15, 0
	global_load_dword v89, v3, s[14:15] nt
	s_add_u32 s14, s14, 0x4000
	s_addc_u32 s15, s15, 0
	global_load_dword v90, v3, s[14:15] nt
	s_add_u32 s14, s14, 0x4000
	s_addc_u32 s15, s15, 0
	global_load_dword v91, v3, s[14:15] nt
	s_add_u32 s14, s14, 0x4000
	s_addc_u32 s15, s15, 0
	global_load_dword v92, v3, s[14:15] nt
	s_add_u32 s14, s14, 0x4000
	s_addc_u32 s15, s15, 0
	global_load_dword v93, v3, s[14:15] nt
	s_add_u32 s14, s14, 0x4000
	s_addc_u32 s15, s15, 0
	global_load_dword v94, v3, s[14:15] nt
	s_add_u32 s14, s14, 0x4000
	s_addc_u32 s15, s15, 0
	global_load_dword v95, v3, s[14:15] nt
	s_add_u32 s14, s14, 0x4000
	s_addc_u32 s15, s15, 0
	global_load_dword v96, v3, s[14:15] nt
	s_add_u32 s14, s14, 0x4000
	s_addc_u32 s15, s15, 0
	global_load_dword v97, v3, s[14:15] nt
	s_add_u32 s14, s14, 0x4000
	s_addc_u32 s15, s15, 0
	global_load_dword v98, v3, s[14:15] nt
	s_add_u32 s14, s14, 0x4000
	s_addc_u32 s15, s15, 0
	global_load_dword v99, v3, s[14:15] nt
	s_add_u32 s14, s14, 0x4000
	s_addc_u32 s15, s15, 0
	global_load_dword v100, v3, s[14:15] nt
	s_add_u32 s14, s14, 0x4000
	s_addc_u32 s15, s15, 0
	global_load_dword v101, v3, s[14:15] nt
	s_add_u32 s14, s14, 0x4000
	s_addc_u32 s15, s15, 0
	global_load_dword v102, v3, s[14:15] nt
	s_add_u32 s14, s14, 0x4000
	s_addc_u32 s15, s15, 0
	global_load_dword v103, v3, s[14:15] nt
	s_add_u32 s14, s14, 0x4000
	s_addc_u32 s15, s15, 0
	global_load_dword v104, v3, s[14:15] nt
	s_add_u32 s14, s14, 0x4000
	s_addc_u32 s15, s15, 0
	global_load_dword v105, v3, s[14:15] nt
	s_add_u32 s14, s14, 0x4000
	s_addc_u32 s15, s15, 0
	global_load_dword v106, v3, s[14:15] nt
	s_add_u32 s14, s14, 0x4000
	s_addc_u32 s15, s15, 0
	global_load_dword v107, v3, s[14:15] nt
	s_add_u32 s14, s14, 0x4000
	s_addc_u32 s15, s15, 0
	global_load_dword v108, v3, s[14:15] nt
	s_add_u32 s14, s14, 0x4000
	s_addc_u32 s15, s15, 0
	global_load_dword v109, v3, s[14:15] nt
	s_add_u32 s14, s14, 0x4000
	s_addc_u32 s15, s15, 0
	global_load_dword v110, v3, s[14:15] nt
	s_add_u32 s14, s14, 0x4000
	s_addc_u32 s15, s15, 0
	global_load_dword v111, v3, s[14:15] nt
	s_add_u32 s14, s14, 0x4000
	s_addc_u32 s15, s15, 0
	global_load_dword v112, v3, s[14:15] nt
	s_add_u32 s14, s14, 0x4000
	s_addc_u32 s15, s15, 0
	global_load_dword v113, v3, s[14:15] nt
	s_add_u32 s14, s14, 0x4000
	s_addc_u32 s15, s15, 0
	global_load_dword v114, v3, s[14:15] nt
	s_add_u32 s14, s14, 0x4000
	s_addc_u32 s15, s15, 0
	global_load_dword v115, v3, s[14:15] nt
	s_add_u32 s14, s14, 0x4000
	s_addc_u32 s15, s15, 0
	global_load_dword v116, v3, s[14:15] nt
	s_add_u32 s14, s14, 0x4000
	s_addc_u32 s15, s15, 0
	global_load_dword v117, v3, s[14:15] nt
	s_add_u32 s14, s14, 0x4000
	s_addc_u32 s15, s15, 0
	global_load_dword v118, v3, s[14:15] nt
	s_add_u32 s14, s14, 0x4000
	s_addc_u32 s15, s15, 0
	global_load_dword v119, v3, s[14:15] nt
	s_lshr_b32 s24, s12, 2
	s_mul_i32 s24, s24, 0x58
	s_add_u32 s24, s24, s11
	s_lshl_b32 s24, s24, 14
	s_and_b32 s25, s12, 3
	s_lshl_b32 s25, s25, 12
	s_add_u32 s24, s24, s25
	s_add_u32 s24, s6, s24
	s_addc_u32 s25, s7, 0
	s_waitcnt vmcnt(32)
	ds_write_b32 v4, v16
	ds_write_b32 v4, v17 offset:264
	ds_write_b32 v4, v18 offset:528
	ds_write_b32 v4, v19 offset:792
	ds_write_b32 v4, v20 offset:1056
	ds_write_b32 v4, v21 offset:1320
	ds_write_b32 v4, v22 offset:1584
	ds_write_b32 v4, v23 offset:1848
	ds_write_b32 v4, v24 offset:2112
	ds_write_b32 v4, v25 offset:2376
	ds_write_b32 v4, v26 offset:2640
	ds_write_b32 v4, v27 offset:2904
	ds_write_b32 v4, v28 offset:3168
	ds_write_b32 v4, v29 offset:3432
	ds_write_b32 v4, v30 offset:3696
	ds_write_b32 v4, v31 offset:3960
	ds_write_b32 v4, v32 offset:4224
	ds_write_b32 v4, v33 offset:4488
	ds_write_b32 v4, v34 offset:4752
	ds_write_b32 v4, v35 offset:5016
	ds_write_b32 v4, v36 offset:5280
	ds_write_b32 v4, v37 offset:5544
	ds_write_b32 v4, v38 offset:5808
	ds_write_b32 v4, v39 offset:6072
	ds_write_b32 v4, v40 offset:6336
	ds_write_b32 v4, v41 offset:6600
	ds_write_b32 v4, v42 offset:6864
	ds_write_b32 v4, v43 offset:7128
	ds_write_b32 v4, v44 offset:7392
	ds_write_b32 v4, v45 offset:7656
	ds_write_b32 v4, v46 offset:7920
	ds_write_b32 v4, v47 offset:8184
	s_waitcnt lgkmcnt(0)
	ds_read_b32 v48, v7
	ds_read_b32 v49, v7 offset:132
	ds_read_b32 v50, v7 offset:264
	ds_read_b32 v51, v7 offset:396
	ds_read_b32 v52, v7 offset:528
	ds_read_b32 v53, v7 offset:660
	ds_read_b32 v54, v7 offset:792
	ds_read_b32 v55, v7 offset:924
	ds_read_b32 v56, v7 offset:32
	ds_read_b32 v57, v7 offset:164
	ds_read_b32 v58, v7 offset:296
	ds_read_b32 v59, v7 offset:428
	ds_read_b32 v60, v7 offset:560
	ds_read_b32 v61, v7 offset:692
	ds_read_b32 v62, v7 offset:824
	ds_read_b32 v63, v7 offset:956
	ds_read_b32 v64, v7 offset:64
	ds_read_b32 v65, v7 offset:196
	ds_read_b32 v66, v7 offset:328
	ds_read_b32 v67, v7 offset:460
	ds_read_b32 v68, v7 offset:592
	ds_read_b32 v69, v7 offset:724
	ds_read_b32 v70, v7 offset:856
	ds_read_b32 v71, v7 offset:988
	ds_read_b32 v72, v7 offset:96
	ds_read_b32 v73, v7 offset:228
	ds_read_b32 v74, v7 offset:360
	ds_read_b32 v75, v7 offset:492
	ds_read_b32 v76, v7 offset:624
	ds_read_b32 v77, v7 offset:756
	ds_read_b32 v78, v7 offset:888
	ds_read_b32 v79, v7 offset:1020
	s_waitcnt lgkmcnt(0)
	v_cvt_pk_bf16_f32 v48, v48, v49
	v_cvt_pk_bf16_f32 v49, v50, v51
	v_cvt_pk_bf16_f32 v50, v52, v53
	v_cvt_pk_bf16_f32 v51, v54, v55
	global_store_dwordx4 v8, v[48:51], s[16:17]
	v_cvt_pk_bf16_f32 v56, v56, v57
	v_cvt_pk_bf16_f32 v57, v58, v59
	v_cvt_pk_bf16_f32 v58, v60, v61
	v_cvt_pk_bf16_f32 v59, v62, v63
	global_store_dwordx4 v9, v[56:59], s[16:17]
	v_cvt_pk_bf16_f32 v64, v64, v65
	v_cvt_pk_bf16_f32 v65, v66, v67
	v_cvt_pk_bf16_f32 v66, v68, v69
	v_cvt_pk_bf16_f32 v67, v70, v71
	global_store_dwordx4 v8, v[64:67], s[16:17] offset:2048
	v_cvt_pk_bf16_f32 v72, v72, v73
	v_cvt_pk_bf16_f32 v73, v74, v75
	v_cvt_pk_bf16_f32 v74, v76, v77
	v_cvt_pk_bf16_f32 v75, v78, v79
	global_store_dwordx4 v9, v[72:75], s[16:17] offset:2048
	s_add_u32 s9, s9, s19
	s_cmpk_ge_u32 s9, 0x1600
	s_cbranch_scc1 .Ltc1a_lastB
; __device__ __forceinline__ void tr_load(const float* W, int N, int item, int lane, float (&wv)[32]) {
;     const int nblk = N / 32, kb = item / nblk, nb = item % nblk, k0 = 64 * kb, n0 = 32 * nb;
; #pragma unroll
;     for (int i = 0; i < 32; ++i) { const int kk = 2 * i + (lane >> 5); wv[i] = __builtin_nontemporal_load(W + (size_t)(k0 + kk) * N + n0 + (lane & 31)); }
; }
; template <int MAP, bool HASG, bool PERMW>
; __device__ __forceinline__ void tr_store(int K, int N, bf16_t* WT, LAS float* scr, int item, int lane, const float* gk) {
;     const int nblk = N / 32, kb = item / nblk, nb = item % nblk, k0 = 64 * kb, n0 = 32 * nb;
;     asm volatile("s_waitcnt lgkmcnt(0)" ::: "memory");
;     const int c = lane & 7;
;     f32x4 g0 = {1.f, 1.f, 1.f, 1.f}, g1 = {1.f, 1.f, 1.f, 1.f};
;     if (HASG) { g0 = *(const f32x4*)(gk + k0 + 8 * c); g1 = *(const f32x4*)(gk + k0 + 8 * c + 4); }
; #pragma unroll
;     for (int j = 0; j < 4; ++j) { const int n = (lane >> 3) + 8 * j; const LAS float* s = scr + (8 * c) * 33 + n;
;         u32x4 o; o.x = pk2(s[0 * 33] * g0[0], s[1 * 33] * g0[1]); o.y = pk2(s[2 * 33] * g0[2], s[3 * 33] * g0[3]); o.z = pk2(s[4 * 33] * g1[0], s[5 * 33] * g1[1]); o.w = pk2(s[6 * 33] * g1[2], s[7 * 33] * g1[3]);
;         const int wr_ = rowmap<MAP>(n0 + n), slot_ = PERMW ? ((wr_ & ~31) + invperm32(wr_ & 31)) : wr_;
;         *(u32x4*)((char*)WT + tiled_off(slot_, k0 + 8 * c, K / 64)) = o; }
;     asm volatile("s_waitcnt lgkmcnt(0)" ::: "memory");
; }
; template <int MAP, bool HASG = false, bool PERMW = false>
; __device__ __forceinline__ void transpose_mat(const float* W, int K, int N, bf16_t* WT, LAS float* scr, int gw, int ngw, int lane, const float* gk = nullptr) {
;     const int nitems = (K / 64) * (N / 32);
;     int it = gw;
;     if (it >= nitems) return;
;     float wv[32];
;     tr_load(W, N, it, lane, wv);
;     for (;;) {
;         __builtin_amdgcn_sched_barrier(0);
; #pragma unroll
;         for (int i = 0; i < 32; ++i) { const int kk = 2 * i + (lane >> 5); scr[kk * 33 + (lane & 31)] = wv[i]; }
;         __builtin_amdgcn_sched_barrier(0);
;         const int nx = it + ngw;
;         if (nx < nitems) tr_load(W, N, nx, lane, wv);
;         __builtin_amdgcn_sched_barrier(0);
;         tr_store<MAP, HASG, PERMW>(K, N, WT, scr, it, lane, gk);
;         if (nx >= nitems) break;
;         it = nx;
;     }
; }
	s_lshr_b32 s11, s9, 6
	s_and_b32 s12, s9, 63
	s_lshl_b32 s13, s11, 19
	s_lshl_b32 s14, s12, 7
	s_add_u32 s13, s13, s14
	s_add_u32 s14, s4, s13
	s_addc_u32 s15, s5, 0
	global_load_dword v16, v3, s[14:15] nt
	s_add_u32 s14, s14, 0x4000
	s_addc_u32 s15, s15, 0
	global_load_dword v17, v3, s[14:15] nt
	s_add_u32 s14, s14, 0x4000
	s_addc_u32 s15, s15, 0
	global_load_dword v18, v3, s[14:15] nt
	s_add_u32 s14, s14, 0x4000
	s_addc_u32 s15, s15, 0
	global_load_dword v19, v3, s[14:15] nt
	s_add_u32 s14, s14, 0x4000
	s_addc_u32 s15, s15, 0
	global_load_dword v20, v3, s[14:15] nt
	s_add_u32 s14, s14, 0x4000
	s_addc_u32 s15, s15, 0
	global_load_dword v21, v3, s[14:15] nt
	s_add_u32 s14, s14, 0x4000
	s_addc_u32 s15, s15, 0
	global_load_dword v22, v3, s[14:15] nt
	s_add_u32 s14, s14, 0x4000
	s_addc_u32 s15, s15, 0
	global_load_dword v23, v3, s[14:15] nt
	s_add_u32 s14, s14, 0x4000
	s_addc_u32 s15, s15, 0
	global_load_dword v24, v3, s[14:15] nt
	s_add_u32 s14, s14, 0x4000
	s_addc_u32 s15, s15, 0
	global_load_dword v25, v3, s[14:15] nt
	s_add_u32 s14, s14, 0x4000
	s_addc_u32 s15, s15, 0
	global_load_dword v26, v3, s[14:15] nt
	s_add_u32 s14, s14, 0x4000
	s_addc_u32 s15, s15, 0
	global_load_dword v27, v3, s[14:15] nt
	s_add_u32 s14, s14, 0x4000
	s_addc_u32 s15, s15, 0
	global_load_dword v28, v3, s[14:15] nt
	s_add_u32 s14, s14, 0x4000
	s_addc_u32 s15, s15, 0
	global_load_dword v29, v3, s[14:15] nt
	s_add_u32 s14, s14, 0x4000
	s_addc_u32 s15, s15, 0
	global_load_dword v30, v3, s[14:15] nt
	s_add_u32 s14, s14, 0x4000
	s_addc_u32 s15, s15, 0
	global_load_dword v31, v3, s[14:15] nt
	s_add_u32 s14, s14, 0x4000
	s_addc_u32 s15, s15, 0
	global_load_dword v32, v3, s[14:15] nt
	s_add_u32 s14, s14, 0x4000
	s_addc_u32 s15, s15, 0
	global_load_dword v33, v3, s[14:15] nt
	s_add_u32 s14, s14, 0x4000
	s_addc_u32 s15, s15, 0
	global_load_dword v34, v3, s[14:15] nt
	s_add_u32 s14, s14, 0x4000
	s_addc_u32 s15, s15, 0
	global_load_dword v35, v3, s[14:15] nt
	s_add_u32 s14, s14, 0x4000
	s_addc_u32 s15, s15, 0
	global_load_dword v36, v3, s[14:15] nt
	s_add_u32 s14, s14, 0x4000
	s_addc_u32 s15, s15, 0
	global_load_dword v37, v3, s[14:15] nt
	s_add_u32 s14, s14, 0x4000
	s_addc_u32 s15, s15, 0
	global_load_dword v38, v3, s[14:15] nt
	s_add_u32 s14, s14, 0x4000
	s_addc_u32 s15, s15, 0
	global_load_dword v39, v3, s[14:15] nt
	s_add_u32 s14, s14, 0x4000
	s_addc_u32 s15, s15, 0
	global_load_dword v40, v3, s[14:15] nt
	s_add_u32 s14, s14, 0x4000
	s_addc_u32 s15, s15, 0
	global_load_dword v41, v3, s[14:15] nt
	s_add_u32 s14, s14, 0x4000
	s_addc_u32 s15, s15, 0
	global_load_dword v42, v3, s[14:15] nt
	s_add_u32 s14, s14, 0x4000
	s_addc_u32 s15, s15, 0
	global_load_dword v43, v3, s[14:15] nt
	s_add_u32 s14, s14, 0x4000
	s_addc_u32 s15, s15, 0
	global_load_dword v44, v3, s[14:15] nt
	s_add_u32 s14, s14, 0x4000
	s_addc_u32 s15, s15, 0
	global_load_dword v45, v3, s[14:15] nt
	s_add_u32 s14, s14, 0x4000
	s_addc_u32 s15, s15, 0
	global_load_dword v46, v3, s[14:15] nt
	s_add_u32 s14, s14, 0x4000
	s_addc_u32 s15, s15, 0
	global_load_dword v47, v3, s[14:15] nt
	s_lshr_b32 s16, s12, 2
	s_mul_i32 s16, s16, 0x58
	s_add_u32 s16, s16, s11
	s_lshl_b32 s16, s16, 14
	s_and_b32 s17, s12, 3
	s_lshl_b32 s17, s17, 12
	s_add_u32 s16, s16, s17
	s_add_u32 s16, s6, s16
	s_addc_u32 s17, s7, 0
	s_waitcnt vmcnt(32)
	ds_write_b32 v4, v88
	ds_write_b32 v4, v89 offset:264
	ds_write_b32 v4, v90 offset:528
	ds_write_b32 v4, v91 offset:792
	ds_write_b32 v4, v92 offset:1056
	ds_write_b32 v4, v93 offset:1320
	ds_write_b32 v4, v94 offset:1584
	ds_write_b32 v4, v95 offset:1848
	ds_write_b32 v4, v96 offset:2112
	ds_write_b32 v4, v97 offset:2376
	ds_write_b32 v4, v98 offset:2640
	ds_write_b32 v4, v99 offset:2904
	ds_write_b32 v4, v100 offset:3168
	ds_write_b32 v4, v101 offset:3432
	ds_write_b32 v4, v102 offset:3696
	ds_write_b32 v4, v103 offset:3960
	ds_write_b32 v4, v104 offset:4224
	ds_write_b32 v4, v105 offset:4488
	ds_write_b32 v4, v106 offset:4752
	ds_write_b32 v4, v107 offset:5016
	ds_write_b32 v4, v108 offset:5280
	ds_write_b32 v4, v109 offset:5544
	ds_write_b32 v4, v110 offset:5808
	ds_write_b32 v4, v111 offset:6072
	ds_write_b32 v4, v112 offset:6336
	ds_write_b32 v4, v113 offset:6600
	ds_write_b32 v4, v114 offset:6864
	ds_write_b32 v4, v115 offset:7128
	ds_write_b32 v4, v116 offset:7392
	ds_write_b32 v4, v117 offset:7656
	ds_write_b32 v4, v118 offset:7920
	ds_write_b32 v4, v119 offset:8184
	s_waitcnt lgkmcnt(0)
	ds_read_b32 v48, v7
	ds_read_b32 v49, v7 offset:132
	ds_read_b32 v50, v7 offset:264
	ds_read_b32 v51, v7 offset:396
	ds_read_b32 v52, v7 offset:528
	ds_read_b32 v53, v7 offset:660
	ds_read_b32 v54, v7 offset:792
	ds_read_b32 v55, v7 offset:924
	ds_read_b32 v56, v7 offset:32
	ds_read_b32 v57, v7 offset:164
	ds_read_b32 v58, v7 offset:296
	ds_read_b32 v59, v7 offset:428
	ds_read_b32 v60, v7 offset:560
	ds_read_b32 v61, v7 offset:692
	ds_read_b32 v62, v7 offset:824
	ds_read_b32 v63, v7 offset:956
	ds_read_b32 v64, v7 offset:64
	ds_read_b32 v65, v7 offset:196
	ds_read_b32 v66, v7 offset:328
	ds_read_b32 v67, v7 offset:460
	ds_read_b32 v68, v7 offset:592
	ds_read_b32 v69, v7 offset:724
	ds_read_b32 v70, v7 offset:856
	ds_read_b32 v71, v7 offset:988
	ds_read_b32 v72, v7 offset:96
	ds_read_b32 v73, v7 offset:228
	ds_read_b32 v74, v7 offset:360
	ds_read_b32 v75, v7 offset:492
	ds_read_b32 v76, v7 offset:624
	ds_read_b32 v77, v7 offset:756
	ds_read_b32 v78, v7 offset:888
	ds_read_b32 v79, v7 offset:1020
	s_waitcnt lgkmcnt(0)
	v_cvt_pk_bf16_f32 v48, v48, v49
	v_cvt_pk_bf16_f32 v49, v50, v51
	v_cvt_pk_bf16_f32 v50, v52, v53
	v_cvt_pk_bf16_f32 v51, v54, v55
	global_store_dwordx4 v8, v[48:51], s[24:25]
	v_cvt_pk_bf16_f32 v56, v56, v57
	v_cvt_pk_bf16_f32 v57, v58, v59
	v_cvt_pk_bf16_f32 v58, v60, v61
	v_cvt_pk_bf16_f32 v59, v62, v63
	global_store_dwordx4 v9, v[56:59], s[24:25]
	v_cvt_pk_bf16_f32 v64, v64, v65
	v_cvt_pk_bf16_f32 v65, v66, v67
	v_cvt_pk_bf16_f32 v66, v68, v69
	v_cvt_pk_bf16_f32 v67, v70, v71
	global_store_dwordx4 v8, v[64:67], s[24:25] offset:2048
	v_cvt_pk_bf16_f32 v72, v72, v73
	v_cvt_pk_bf16_f32 v73, v74, v75
	v_cvt_pk_bf16_f32 v74, v76, v77
	v_cvt_pk_bf16_f32 v75, v78, v79
	global_store_dwordx4 v9, v[72:75], s[24:25] offset:2048
	s_branch .Ltc1a_loop

; __device__ __forceinline__ void tr_load(const float* W, int N, int item, int lane, float (&wv)[32]) {
;     const int nblk = N / 32, kb = item / nblk, nb = item % nblk, k0 = 64 * kb, n0 = 32 * nb;
; #pragma unroll
;     for (int i = 0; i < 32; ++i) { const int kk = 2 * i + (lane >> 5); wv[i] = __builtin_nontemporal_load(W + (size_t)(k0 + kk) * N + n0 + (lane & 31)); }
; }
; template <int MAP, bool HASG, bool PERMW>
; __device__ __forceinline__ void tr_store(int K, int N, bf16_t* WT, LAS float* scr, int item, int lane, const float* gk) {
;     const int nblk = N / 32, kb = item / nblk, nb = item % nblk, k0 = 64 * kb, n0 = 32 * nb;
;     asm volatile("s_waitcnt lgkmcnt(0)" ::: "memory");
;     const int c = lane & 7;
;     f32x4 g0 = {1.f, 1.f, 1.f, 1.f}, g1 = {1.f, 1.f, 1.f, 1.f};
;     if (HASG) { g0 = *(const f32x4*)(gk + k0 + 8 * c); g1 = *(const f32x4*)(gk + k0 + 8 * c + 4); }
; #pragma unroll
;     for (int j = 0; j < 4; ++j) { const int n = (lane >> 3) + 8 * j; const LAS float* s = scr + (8 * c) * 33 + n;
;         u32x4 o; o.x = pk2(s[0 * 33] * g0[0], s[1 * 33] * g0[1]); o.y = pk2(s[2 * 33] * g0[2], s[3 * 33] * g0[3]); o.z = pk2(s[4 * 33] * g1[0], s[5 * 33] * g1[1]); o.w = pk2(s[6 * 33] * g1[2], s[7 * 33] * g1[3]);
;         const int wr_ = rowmap<MAP>(n0 + n), slot_ = PERMW ? ((wr_ & ~31) + invperm32(wr_ & 31)) : wr_;
;         *(u32x4*)((char*)WT + tiled_off(slot_, k0 + 8 * c, K / 64)) = o; }
;     asm volatile("s_waitcnt lgkmcnt(0)" ::: "memory");
; }
; template <int MAP, bool HASG = false, bool PERMW = false>
; __device__ __forceinline__ void transpose_mat(const float* W, int K, int N, bf16_t* WT, LAS float* scr, int gw, int ngw, int lane, const float* gk = nullptr) {
;     const int nitems = (K / 64) * (N / 32);
;     int it = gw;
;     if (it >= nitems) return;
;     float wv[32];
;     tr_load(W, N, it, lane, wv);
;     for (;;) {
;         __builtin_amdgcn_sched_barrier(0);
; #pragma unroll
;         for (int i = 0; i < 32; ++i) { const int kk = 2 * i + (lane >> 5); scr[kk * 33 + (lane & 31)] = wv[i]; }
;         __builtin_amdgcn_sched_barrier(0);
;         const int nx = it + ngw;
;         if (nx < nitems) tr_load(W, N, nx, lane, wv);
;         __builtin_amdgcn_sched_barrier(0);
;         tr_store<MAP, HASG, PERMW>(K, N, WT, scr, it, lane, gk);
;         if (nx >= nitems) break;
;         it = nx;
;     }
; }
.Ltc1b_loop:
	s_add_u32 s9, s9, s19
	s_cmpk_ge_u32 s9, 0x1600
	s_cbranch_scc1 .Ltc1b_lastA
	s_mul_hi_u32 s11, s9, 0x2e8ba2e9
	s_lshr_b32 s11, s11, 5
	s_mul_i32 s12, s11, 0xb0
	s_sub_u32 s12, s9, s12
	s_mul_i32 s13, s11, 0x160000
	s_lshl_b32 s14, s12, 7
	s_add_u32 s13, s13, s14
	s_add_u32 s14, s4, s13
	s_addc_u32 s15, s5, 0
	global_load_dword v88, v15, s[14:15] nt
	s_add_u32 s14, s14, 0xb000
	s_addc_u32 s15, s15, 0
	global_load_dword v89, v15, s[14:15] nt
	s_add_u32 s14, s14, 0xb000
	s_addc_u32 s15, s15, 0
	global_load_dword v90, v15, s[14:15] nt
	s_add_u32 s14, s14, 0xb000
	s_addc_u32 s15, s15, 0
	global_load_dword v91, v15, s[14:15] nt
	s_add_u32 s14, s14, 0xb000
	s_addc_u32 s15, s15, 0
	global_load_dword v92, v15, s[14:15] nt
	s_add_u32 s14, s14, 0xb000
	s_addc_u32 s15, s15, 0
	global_load_dword v93, v15, s[14:15] nt
	s_add_u32 s14, s14, 0xb000
	s_addc_u32 s15, s15, 0
	global_load_dword v94, v15, s[14:15] nt
	s_add_u32 s14, s14, 0xb000
	s_addc_u32 s15, s15, 0
	global_load_dword v95, v15, s[14:15] nt
	s_add_u32 s14, s14, 0xb000
	s_addc_u32 s15, s15, 0
	global_load_dword v96, v15, s[14:15] nt
	s_add_u32 s14, s14, 0xb000
	s_addc_u32 s15, s15, 0
	global_load_dword v97, v15, s[14:15] nt
	s_add_u32 s14, s14, 0xb000
	s_addc_u32 s15, s15, 0
	global_load_dword v98, v15, s[14:15] nt
	s_add_u32 s14, s14, 0xb000
	s_addc_u32 s15, s15, 0
	global_load_dword v99, v15, s[14:15] nt
	s_add_u32 s14, s14, 0xb000
	s_addc_u32 s15, s15, 0
	global_load_dword v100, v15, s[14:15] nt
	s_add_u32 s14, s14, 0xb000
	s_addc_u32 s15, s15, 0
	global_load_dword v101, v15, s[14:15] nt
	s_add_u32 s14, s14, 0xb000
	s_addc_u32 s15, s15, 0
	global_load_dword v102, v15, s[14:15] nt
	s_add_u32 s14, s14, 0xb000
	s_addc_u32 s15, s15, 0
	global_load_dword v103, v15, s[14:15] nt
	s_add_u32 s14, s14, 0xb000
	s_addc_u32 s15, s15, 0
	global_load_dword v104, v15, s[14:15] nt
	s_add_u32 s14, s14, 0xb000
	s_addc_u32 s15, s15, 0
	global_load_dword v105, v15, s[14:15] nt
	s_add_u32 s14, s14, 0xb000
	s_addc_u32 s15, s15, 0
	global_load_dword v106, v15, s[14:15] nt
	s_add_u32 s14, s14, 0xb000
	s_addc_u32 s15, s15, 0
	global_load_dword v107, v15, s[14:15] nt
	s_add_u32 s14, s14, 0xb000
	s_addc_u32 s15, s15, 0
	global_load_dword v108, v15, s[14:15] nt
	s_add_u32 s14, s14, 0xb000
	s_addc_u32 s15, s15, 0
	global_load_dword v109, v15, s[14:15] nt
	s_add_u32 s14, s14, 0xb000
	s_addc_u32 s15, s15, 0
	global_load_dword v110, v15, s[14:15] nt
	s_add_u32 s14, s14, 0xb000
	s_addc_u32 s15, s15, 0
	global_load_dword v111, v15, s[14:15] nt
	s_add_u32 s14, s14, 0xb000
	s_addc_u32 s15, s15, 0
	global_load_dword v112, v15, s[14:15] nt
	s_add_u32 s14, s14, 0xb000
	s_addc_u32 s15, s15, 0
	global_load_dword v113, v15, s[14:15] nt
	s_add_u32 s14, s14, 0xb000
	s_addc_u32 s15, s15, 0
	global_load_dword v114, v15, s[14:15] nt
	s_add_u32 s14, s14, 0xb000
	s_addc_u32 s15, s15, 0
	global_load_dword v115, v15, s[14:15] nt
	s_add_u32 s14, s14, 0xb000
	s_addc_u32 s15, s15, 0
	global_load_dword v116, v15, s[14:15] nt
	s_add_u32 s14, s14, 0xb000
	s_addc_u32 s15, s15, 0
	global_load_dword v117, v15, s[14:15] nt
	s_add_u32 s14, s14, 0xb000
	s_addc_u32 s15, s15, 0
	global_load_dword v118, v15, s[14:15] nt
	s_add_u32 s14, s14, 0xb000
	s_addc_u32 s15, s15, 0
	global_load_dword v119, v15, s[14:15] nt
	s_lshl_b32 s14, s11, 8
	s_add_u32 s14, s20, s14
	s_addc_u32 s15, s21, 0
	global_load_dwordx4 v[120:123], v14, s[14:15]
	global_load_dwordx4 v[124:127], v14, s[14:15] offset:16
	s_lshr_b32 s24, s12, 2
	s_lshl_b32 s24, s24, 1
	s_lshl_b32 s24, s24, 5
	s_add_u32 s24, s24, s11
	s_lshl_b32 s24, s24, 14
	s_and_b32 s25, s12, 3
	s_lshl_b32 s25, s25, 12
	s_add_u32 s24, s24, s25
	s_add_u32 s24, s6, s24
	s_addc_u32 s25, s7, 0
	s_waitcnt vmcnt(34)
	ds_write_b32 v4, v16
	ds_write_b32 v4, v17 offset:264
	ds_write_b32 v4, v18 offset:528
	ds_write_b32 v4, v19 offset:792
	ds_write_b32 v4, v20 offset:1056
	ds_write_b32 v4, v21 offset:1320
	ds_write_b32 v4, v22 offset:1584
	ds_write_b32 v4, v23 offset:1848
	ds_write_b32 v4, v24 offset:2112
	ds_write_b32 v4, v25 offset:2376
	ds_write_b32 v4, v26 offset:2640
	ds_write_b32 v4, v27 offset:2904
	ds_write_b32 v4, v28 offset:3168
	ds_write_b32 v4, v29 offset:3432
	ds_write_b32 v4, v30 offset:3696
	ds_write_b32 v4, v31 offset:3960
	ds_write_b32 v4, v32 offset:4224
	ds_write_b32 v4, v33 offset:4488
	ds_write_b32 v4, v34 offset:4752
	ds_write_b32 v4, v35 offset:5016
	ds_write_b32 v4, v36 offset:5280
	ds_write_b32 v4, v37 offset:5544
	ds_write_b32 v4, v38 offset:5808
	ds_write_b32 v4, v39 offset:6072
	ds_write_b32 v4, v40 offset:6336
	ds_write_b32 v4, v41 offset:6600
	ds_write_b32 v4, v42 offset:6864
	ds_write_b32 v4, v43 offset:7128
	ds_write_b32 v4, v44 offset:7392
	ds_write_b32 v4, v45 offset:7656
	ds_write_b32 v4, v46 offset:7920
	ds_write_b32 v4, v47 offset:8184
	s_waitcnt lgkmcnt(0)
	ds_read_b32 v48, v7
	ds_read_b32 v49, v7 offset:132
	ds_read_b32 v50, v7 offset:264
	ds_read_b32 v51, v7 offset:396
	ds_read_b32 v52, v7 offset:528
	ds_read_b32 v53, v7 offset:660
	ds_read_b32 v54, v7 offset:792
	ds_read_b32 v55, v7 offset:924
	ds_read_b32 v56, v7 offset:32
	ds_read_b32 v57, v7 offset:164
	ds_read_b32 v58, v7 offset:296
	ds_read_b32 v59, v7 offset:428
	ds_read_b32 v60, v7 offset:560
	ds_read_b32 v61, v7 offset:692
	ds_read_b32 v62, v7 offset:824
	ds_read_b32 v63, v7 offset:956
	ds_read_b32 v64, v7 offset:64
	ds_read_b32 v65, v7 offset:196
	ds_read_b32 v66, v7 offset:328
	ds_read_b32 v67, v7 offset:460
	ds_read_b32 v68, v7 offset:592
	ds_read_b32 v69, v7 offset:724
	ds_read_b32 v70, v7 offset:856
	ds_read_b32 v71, v7 offset:988
	ds_read_b32 v72, v7 offset:96
	ds_read_b32 v73, v7 offset:228
	ds_read_b32 v74, v7 offset:360
	ds_read_b32 v75, v7 offset:492
	ds_read_b32 v76, v7 offset:624
	ds_read_b32 v77, v7 offset:756
	ds_read_b32 v78, v7 offset:888
	ds_read_b32 v79, v7 offset:1020
	s_waitcnt lgkmcnt(0)
; __device__ __forceinline__ void tr_load(const float* W, int N, int item, int lane, float (&wv)[32]) {
;     const int nblk = N / 32, kb = item / nblk, nb = item % nblk, k0 = 64 * kb, n0 = 32 * nb;
; #pragma unroll
;     for (int i = 0; i < 32; ++i) { const int kk = 2 * i + (lane >> 5); wv[i] = __builtin_nontemporal_load(W + (size_t)(k0 + kk) * N + n0 + (lane & 31)); }
; }
; template <int MAP, bool HASG, bool PERMW>
; __device__ __forceinline__ void tr_store(int K, int N, bf16_t* WT, LAS float* scr, int item, int lane, const float* gk) {
;     const int nblk = N / 32, kb = item / nblk, nb = item % nblk, k0 = 64 * kb, n0 = 32 * nb;
;     asm volatile("s_waitcnt lgkmcnt(0)" ::: "memory");
;     const int c = lane & 7;
;     f32x4 g0 = {1.f, 1.f, 1.f, 1.f}, g1 = {1.f, 1.f, 1.f, 1.f};
;     if (HASG) { g0 = *(const f32x4*)(gk + k0 + 8 * c); g1 = *(const f32x4*)(gk + k0 + 8 * c + 4); }
; #pragma unroll
;     for (int j = 0; j < 4; ++j) { const int n = (lane >> 3) + 8 * j; const LAS float* s = scr + (8 * c) * 33 + n;
;         u32x4 o; o.x = pk2(s[0 * 33] * g0[0], s[1 * 33] * g0[1]); o.y = pk2(s[2 * 33] * g0[2], s[3 * 33] * g0[3]); o.z = pk2(s[4 * 33] * g1[0], s[5 * 33] * g1[1]); o.w = pk2(s[6 * 33] * g1[2], s[7 * 33] * g1[3]);
;         const int wr_ = rowmap<MAP>(n0 + n), slot_ = PERMW ? ((wr_ & ~31) + invperm32(wr_ & 31)) : wr_;
;         *(u32x4*)((char*)WT + tiled_off(slot_, k0 + 8 * c, K / 64)) = o; }
;     asm volatile("s_waitcnt lgkmcnt(0)" ::: "memory");
; }
; template <int MAP, bool HASG = false, bool PERMW = false>
; __device__ __forceinline__ void transpose_mat(const float* W, int K, int N, bf16_t* WT, LAS float* scr, int gw, int ngw, int lane, const float* gk = nullptr) {
;     const int nitems = (K / 64) * (N / 32);
;     int it = gw;
;     if (it >= nitems) return;
;     float wv[32];
;     tr_load(W, N, it, lane, wv);
;     for (;;) {
;         __builtin_amdgcn_sched_barrier(0);
; #pragma unroll
;         for (int i = 0; i < 32; ++i) { const int kk = 2 * i + (lane >> 5); scr[kk * 33 + (lane & 31)] = wv[i]; }
;         __builtin_amdgcn_sched_barrier(0);
;         const int nx = it + ngw;
;         if (nx < nitems) tr_load(W, N, nx, lane, wv);
;         __builtin_amdgcn_sched_barrier(0);
;         tr_store<MAP, HASG, PERMW>(K, N, WT, scr, it, lane, gk);
;         if (nx >= nitems) break;
;         it = nx;
;     }
; }
	v_mul_f32_e32 v48, v48, v80
	v_mul_f32_e32 v49, v49, v81
	v_mul_f32_e32 v50, v50, v82
	v_mul_f32_e32 v51, v51, v83
	v_mul_f32_e32 v52, v52, v84
	v_mul_f32_e32 v53, v53, v85
	v_mul_f32_e32 v54, v54, v86
	v_mul_f32_e32 v55, v55, v87
	v_cvt_pk_bf16_f32 v48, v48, v49
	v_cvt_pk_bf16_f32 v49, v50, v51
	v_cvt_pk_bf16_f32 v50, v52, v53
	v_cvt_pk_bf16_f32 v51, v54, v55
	global_store_dwordx4 v10, v[48:51], s[16:17]
	v_mul_f32_e32 v56, v56, v80
	v_mul_f32_e32 v57, v57, v81
	v_mul_f32_e32 v58, v58, v82
	v_mul_f32_e32 v59, v59, v83
	v_mul_f32_e32 v60, v60, v84
	v_mul_f32_e32 v61, v61, v85
	v_mul_f32_e32 v62, v62, v86
	v_mul_f32_e32 v63, v63, v87
	v_cvt_pk_bf16_f32 v56, v56, v57
	v_cvt_pk_bf16_f32 v57, v58, v59
	v_cvt_pk_bf16_f32 v58, v60, v61
	v_cvt_pk_bf16_f32 v59, v62, v63
	global_store_dwordx4 v10, v[56:59], s[16:17] offset:256
	v_mul_f32_e32 v64, v64, v80
	v_mul_f32_e32 v65, v65, v81
	v_mul_f32_e32 v66, v66, v82
	v_mul_f32_e32 v67, v67, v83
	v_mul_f32_e32 v68, v68, v84
	v_mul_f32_e32 v69, v69, v85
	v_mul_f32_e32 v70, v70, v86
	v_mul_f32_e32 v71, v71, v87
	v_cvt_pk_bf16_f32 v64, v64, v65
	v_cvt_pk_bf16_f32 v65, v66, v67
	v_cvt_pk_bf16_f32 v66, v68, v69
	v_cvt_pk_bf16_f32 v67, v70, v71
	global_store_dwordx4 v11, v[64:67], s[16:17] offset:512
	v_mul_f32_e32 v72, v72, v80
	v_mul_f32_e32 v73, v73, v81
	v_mul_f32_e32 v74, v74, v82
	v_mul_f32_e32 v75, v75, v83
	v_mul_f32_e32 v76, v76, v84
	v_mul_f32_e32 v77, v77, v85
	v_mul_f32_e32 v78, v78, v86
	v_mul_f32_e32 v79, v79, v87
	v_cvt_pk_bf16_f32 v72, v72, v73
	v_cvt_pk_bf16_f32 v73, v74, v75
	v_cvt_pk_bf16_f32 v74, v76, v77
	v_cvt_pk_bf16_f32 v75, v78, v79
	global_store_dwordx4 v11, v[72:75], s[16:17] offset:768
	s_add_u32 s9, s9, s19
	s_cmpk_ge_u32 s9, 0x1600
	s_cbranch_scc1 .Ltc1b_lastB
	s_mul_hi_u32 s11, s9, 0x2e8ba2e9
	s_lshr_b32 s11, s11, 5
	s_mul_i32 s12, s11, 0xb0
	s_sub_u32 s12, s9, s12
	s_mul_i32 s13, s11, 0x160000
	s_lshl_b32 s14, s12, 7
	s_add_u32 s13, s13, s14
	s_add_u32 s14, s4, s13
	s_addc_u32 s15, s5, 0
	global_load_dword v16, v15, s[14:15] nt
	s_add_u32 s14, s14, 0xb000
	s_addc_u32 s15, s15, 0
	global_load_dword v17, v15, s[14:15] nt
	s_add_u32 s14, s14, 0xb000
	s_addc_u32 s15, s15, 0
	global_load_dword v18, v15, s[14:15] nt
	s_add_u32 s14, s14, 0xb000
	s_addc_u32 s15, s15, 0
	global_load_dword v19, v15, s[14:15] nt
	s_add_u32 s14, s14, 0xb000
	s_addc_u32 s15, s15, 0
	global_load_dword v20, v15, s[14:15] nt
	s_add_u32 s14, s14, 0xb000
	s_addc_u32 s15, s15, 0
	global_load_dword v21, v15, s[14:15] nt
	s_add_u32 s14, s14, 0xb000
	s_addc_u32 s15, s15, 0
	global_load_dword v22, v15, s[14:15] nt
	s_add_u32 s14, s14, 0xb000
	s_addc_u32 s15, s15, 0
	global_load_dword v23, v15, s[14:15] nt
	s_add_u32 s14, s14, 0xb000
	s_addc_u32 s15, s15, 0
	global_load_dword v24, v15, s[14:15] nt
	s_add_u32 s14, s14, 0xb000
	s_addc_u32 s15, s15, 0
	global_load_dword v25, v15, s[14:15] nt
	s_add_u32 s14, s14, 0xb000
	s_addc_u32 s15, s15, 0
	global_load_dword v26, v15, s[14:15] nt
	s_add_u32 s14, s14, 0xb000
	s_addc_u32 s15, s15, 0
	global_load_dword v27, v15, s[14:15] nt
	s_add_u32 s14, s14, 0xb000
	s_addc_u32 s15, s15, 0
	global_load_dword v28, v15, s[14:15] nt
	s_add_u32 s14, s14, 0xb000
	s_addc_u32 s15, s15, 0
	global_load_dword v29, v15, s[14:15] nt
	s_add_u32 s14, s14, 0xb000
	s_addc_u32 s15, s15, 0
	global_load_dword v30, v15, s[14:15] nt
	s_add_u32 s14, s14, 0xb000
	s_addc_u32 s15, s15, 0
	global_load_dword v31, v15, s[14:15] nt
	s_add_u32 s14, s14, 0xb000
	s_addc_u32 s15, s15, 0
	global_load_dword v32, v15, s[14:15] nt
	s_add_u32 s14, s14, 0xb000
	s_addc_u32 s15, s15, 0
	global_load_dword v33, v15, s[14:15] nt
	s_add_u32 s14, s14, 0xb000
	s_addc_u32 s15, s15, 0
	global_load_dword v34, v15, s[14:15] nt
	s_add_u32 s14, s14, 0xb000
	s_addc_u32 s15, s15, 0
	global_load_dword v35, v15, s[14:15] nt
	s_add_u32 s14, s14, 0xb000
	s_addc_u32 s15, s15, 0
	global_load_dword v36, v15, s[14:15] nt
	s_add_u32 s14, s14, 0xb000
	s_addc_u32 s15, s15, 0
	global_load_dword v37, v15, s[14:15] nt
	s_add_u32 s14, s14, 0xb000
	s_addc_u32 s15, s15, 0
	global_load_dword v38, v15, s[14:15] nt
	s_add_u32 s14, s14, 0xb000
	s_addc_u32 s15, s15, 0
	global_load_dword v39, v15, s[14:15] nt
	s_add_u32 s14, s14, 0xb000
	s_addc_u32 s15, s15, 0
	global_load_dword v40, v15, s[14:15] nt
	s_add_u32 s14, s14, 0xb000
	s_addc_u32 s15, s15, 0
	global_load_dword v41, v15, s[14:15] nt
	s_add_u32 s14, s14, 0xb000
	s_addc_u32 s15, s15, 0
	global_load_dword v42, v15, s[14:15] nt
	s_add_u32 s14, s14, 0xb000
	s_addc_u32 s15, s15, 0
	global_load_dword v43, v15, s[14:15] nt
	s_add_u32 s14, s14, 0xb000
	s_addc_u32 s15, s15, 0
	global_load_dword v44, v15, s[14:15] nt
	s_add_u32 s14, s14, 0xb000
	s_addc_u32 s15, s15, 0
	global_load_dword v45, v15, s[14:15] nt
	s_add_u32 s14, s14, 0xb000
	s_addc_u32 s15, s15, 0
	global_load_dword v46, v15, s[14:15] nt
	s_add_u32 s14, s14, 0xb000
	s_addc_u32 s15, s15, 0
	global_load_dword v47, v15, s[14:15] nt
	s_lshl_b32 s14, s11, 8
	s_add_u32 s14, s20, s14
	s_addc_u32 s15, s21, 0
	global_load_dwordx4 v[80:83], v14, s[14:15]
	global_load_dwordx4 v[84:87], v14, s[14:15] offset:16
	s_lshr_b32 s16, s12, 2
	s_lshl_b32 s16, s16, 1
	s_lshl_b32 s16, s16, 5
	s_add_u32 s16, s16, s11
	s_lshl_b32 s16, s16, 14
	s_and_b32 s17, s12, 3
	s_lshl_b32 s17, s17, 12
	s_add_u32 s16, s16, s17
	s_add_u32 s16, s6, s16
	s_addc_u32 s17, s7, 0
	s_waitcnt vmcnt(34)
; #define LAS __attribute__((address_space(3)))
; __device__ __forceinline__ unsigned pk2(float lo, float hi) { f32x2 f = {lo, hi}; bf16x2_t b = __builtin_convertvector(f, bf16x2_t); return __builtin_bit_cast(unsigned, b); }
; template <int MAP, bool HASG, bool PERMW>
; __device__ __forceinline__ void tr_store(int K, int N, bf16_t* WT, LAS float* scr, int item, int lane, const float* gk) {
;     const int nblk = N / 32, kb = item / nblk, nb = item % nblk, k0 = 64 * kb, n0 = 32 * nb;
;     asm volatile("s_waitcnt lgkmcnt(0)" ::: "memory");
;     const int c = lane & 7;
;     f32x4 g0 = {1.f, 1.f, 1.f, 1.f}, g1 = {1.f, 1.f, 1.f, 1.f};
;     if (HASG) { g0 = *(const f32x4*)(gk + k0 + 8 * c); g1 = *(const f32x4*)(gk + k0 + 8 * c + 4); }
; #pragma unroll
;     for (int j = 0; j < 4; ++j) { const int n = (lane >> 3) + 8 * j; const LAS float* s = scr + (8 * c) * 33 + n;
;         u32x4 o; o.x = pk2(s[0 * 33] * g0[0], s[1 * 33] * g0[1]); o.y = pk2(s[2 * 33] * g0[2], s[3 * 33] * g0[3]); o.z = pk2(s[4 * 33] * g1[0], s[5 * 33] * g1[1]); o.w = pk2(s[6 * 33] * g1[2], s[7 * 33] * g1[3]);
;         const int wr_ = rowmap<MAP>(n0 + n), slot_ = PERMW ? ((wr_ & ~31) + invperm32(wr_ & 31)) : wr_;
;         *(u32x4*)((char*)WT + tiled_off(slot_, k0 + 8 * c, K / 64)) = o; }
;     asm volatile("s_waitcnt lgkmcnt(0)" ::: "memory");
; }
	ds_write_b32 v4, v88
	ds_write_b32 v4, v89 offset:264
	ds_write_b32 v4, v90 offset:528
	ds_write_b32 v4, v91 offset:792
	ds_write_b32 v4, v92 offset:1056
	ds_write_b32 v4, v93 offset:1320
	ds_write_b32 v4, v94 offset:1584
	ds_write_b32 v4, v95 offset:1848
	ds_write_b32 v4, v96 offset:2112
	ds_write_b32 v4, v97 offset:2376
	ds_write_b32 v4, v98 offset:2640
	ds_write_b32 v4, v99 offset:2904
	ds_write_b32 v4, v100 offset:3168
	ds_write_b32 v4, v101 offset:3432
	ds_write_b32 v4, v102 offset:3696
	ds_write_b32 v4, v103 offset:3960
	ds_write_b32 v4, v104 offset:4224
	ds_write_b32 v4, v105 offset:4488
	ds_write_b32 v4, v106 offset:4752
	ds_write_b32 v4, v107 offset:5016
	ds_write_b32 v4, v108 offset:5280
	ds_write_b32 v4, v109 offset:5544
	ds_write_b32 v4, v110 offset:5808
	ds_write_b32 v4, v111 offset:6072
	ds_write_b32 v4, v112 offset:6336
	ds_write_b32 v4, v113 offset:6600
	ds_write_b32 v4, v114 offset:6864
	ds_write_b32 v4, v115 offset:7128
	ds_write_b32 v4, v116 offset:7392
	ds_write_b32 v4, v117 offset:7656
	ds_write_b32 v4, v118 offset:7920
	ds_write_b32 v4, v119 offset:8184
	s_waitcnt lgkmcnt(0)
	ds_read_b32 v48, v7
	ds_read_b32 v49, v7 offset:132
	ds_read_b32 v50, v7 offset:264
	ds_read_b32 v51, v7 offset:396
	ds_read_b32 v52, v7 offset:528
	ds_read_b32 v53, v7 offset:660
	ds_read_b32 v54, v7 offset:792
	ds_read_b32 v55, v7 offset:924
	ds_read_b32 v56, v7 offset:32
	ds_read_b32 v57, v7 offset:164
	ds_read_b32 v58, v7 offset:296
	ds_read_b32 v59, v7 offset:428
	ds_read_b32 v60, v7 offset:560
	ds_read_b32 v61, v7 offset:692
	ds_read_b32 v62, v7 offset:824
	ds_read_b32 v63, v7 offset:956
	ds_read_b32 v64, v7 offset:64
	ds_read_b32 v65, v7 offset:196
	ds_read_b32 v66, v7 offset:328
	ds_read_b32 v67, v7 offset:460
	ds_read_b32 v68, v7 offset:592
	ds_read_b32 v69, v7 offset:724
	ds_read_b32 v70, v7 offset:856
	ds_read_b32 v71, v7 offset:988
	ds_read_b32 v72, v7 offset:96
	ds_read_b32 v73, v7 offset:228
	ds_read_b32 v74, v7 offset:360
	ds_read_b32 v75, v7 offset:492
	ds_read_b32 v76, v7 offset:624
	ds_read_b32 v77, v7 offset:756
	ds_read_b32 v78, v7 offset:888
	ds_read_b32 v79, v7 offset:1020
	s_waitcnt lgkmcnt(0)
	v_mul_f32_e32 v48, v48, v120
	v_mul_f32_e32 v49, v49, v121
	v_mul_f32_e32 v50, v50, v122
	v_mul_f32_e32 v51, v51, v123
	v_mul_f32_e32 v52, v52, v124
	v_mul_f32_e32 v53, v53, v125
	v_mul_f32_e32 v54, v54, v126
	v_mul_f32_e32 v55, v55, v127
	v_cvt_pk_bf16_f32 v48, v48, v49
	v_cvt_pk_bf16_f32 v49, v50, v51
	v_cvt_pk_bf16_f32 v50, v52, v53
	v_cvt_pk_bf16_f32 v51, v54, v55
	global_store_dwordx4 v10, v[48:51], s[24:25]
	v_mul_f32_e32 v56, v56, v120
	v_mul_f32_e32 v57, v57, v121
	v_mul_f32_e32 v58, v58, v122
	v_mul_f32_e32 v59, v59, v123
	v_mul_f32_e32 v60, v60, v124
	v_mul_f32_e32 v61, v61, v125
	v_mul_f32_e32 v62, v62, v126
	v_mul_f32_e32 v63, v63, v127
	v_cvt_pk_bf16_f32 v56, v56, v57
	v_cvt_pk_bf16_f32 v57, v58, v59
	v_cvt_pk_bf16_f32 v58, v60, v61
	v_cvt_pk_bf16_f32 v59, v62, v63
	global_store_dwordx4 v10, v[56:59], s[24:25] offset:256
	v_mul_f32_e32 v64, v64, v120
	v_mul_f32_e32 v65, v65, v121
	v_mul_f32_e32 v66, v66, v122
	v_mul_f32_e32 v67, v67, v123
	v_mul_f32_e32 v68, v68, v124
	v_mul_f32_e32 v69, v69, v125
	v_mul_f32_e32 v70, v70, v126
	v_mul_f32_e32 v71, v71, v127
	v_cvt_pk_bf16_f32 v64, v64, v65
	v_cvt_pk_bf16_f32 v65, v66, v67
	v_cvt_pk_bf16_f32 v66, v68, v69
	v_cvt_pk_bf16_f32 v67, v70, v71
	global_store_dwordx4 v11, v[64:67], s[24:25] offset:512
	v_mul_f32_e32 v72, v72, v120
	v_mul_f32_e32 v73, v73, v121
	v_mul_f32_e32 v74, v74, v122
	v_mul_f32_e32 v75, v75, v123
	v_mul_f32_e32 v76, v76, v124
	v_mul_f32_e32 v77, v77, v125
	v_mul_f32_e32 v78, v78, v126
	v_mul_f32_e32 v79, v79, v127
	v_cvt_pk_bf16_f32 v72, v72, v73
	v_cvt_pk_bf16_f32 v73, v74, v75
	v_cvt_pk_bf16_f32 v74, v76, v77
	v_cvt_pk_bf16_f32 v75, v78, v79
	global_store_dwordx4 v11, v[72:75], s[24:25] offset:768
	s_branch .Ltc1b_loop

; __device__ __forceinline__ void tr_load(const float* W, int N, int item, int lane, float (&wv)[32]) {
;     const int nblk = N / 32, kb = item / nblk, nb = item % nblk, k0 = 64 * kb, n0 = 32 * nb;
; #pragma unroll
;     for (int i = 0; i < 32; ++i) { const int kk = 2 * i + (lane >> 5); wv[i] = __builtin_nontemporal_load(W + (size_t)(k0 + kk) * N + n0 + (lane & 31)); }
; }
; template <int MAP, bool HASG, bool PERMW>
; __device__ __forceinline__ void tr_store(int K, int N, bf16_t* WT, LAS float* scr, int item, int lane, const float* gk) {
;     const int nblk = N / 32, kb = item / nblk, nb = item % nblk, k0 = 64 * kb, n0 = 32 * nb;
;     asm volatile("s_waitcnt lgkmcnt(0)" ::: "memory");
;     const int c = lane & 7;
;     f32x4 g0 = {1.f, 1.f, 1.f, 1.f}, g1 = {1.f, 1.f, 1.f, 1.f};
;     if (HASG) { g0 = *(const f32x4*)(gk + k0 + 8 * c); g1 = *(const f32x4*)(gk + k0 + 8 * c + 4); }
; #pragma unroll
;     for (int j = 0; j < 4; ++j) { const int n = (lane >> 3) + 8 * j; const LAS float* s = scr + (8 * c) * 33 + n;
;         u32x4 o; o.x = pk2(s[0 * 33] * g0[0], s[1 * 33] * g0[1]); o.y = pk2(s[2 * 33] * g0[2], s[3 * 33] * g0[3]); o.z = pk2(s[4 * 33] * g1[0], s[5 * 33] * g1[1]); o.w = pk2(s[6 * 33] * g1[2], s[7 * 33] * g1[3]);
;         const int wr_ = rowmap<MAP>(n0 + n), slot_ = PERMW ? ((wr_ & ~31) + invperm32(wr_ & 31)) : wr_;
;         *(u32x4*)((char*)WT + tiled_off(slot_, k0 + 8 * c, K / 64)) = o; }
;     asm volatile("s_waitcnt lgkmcnt(0)" ::: "memory");
; }
; template <int MAP, bool HASG = false, bool PERMW = false>
; __device__ __forceinline__ void transpose_mat(const float* W, int K, int N, bf16_t* WT, LAS float* scr, int gw, int ngw, int lane, const float* gk = nullptr) {
;     const int nitems = (K / 64) * (N / 32);
;     int it = gw;
;     if (it >= nitems) return;
;     float wv[32];
;     tr_load(W, N, it, lane, wv);
;     for (;;) {
;         __builtin_amdgcn_sched_barrier(0);
; #pragma unroll
;         for (int i = 0; i < 32; ++i) { const int kk = 2 * i + (lane >> 5); scr[kk * 33 + (lane & 31)] = wv[i]; }
;         __builtin_amdgcn_sched_barrier(0);
;         const int nx = it + ngw;
;         if (nx < nitems) tr_load(W, N, nx, lane, wv);
;         __builtin_amdgcn_sched_barrier(0);
;         tr_store<MAP, HASG, PERMW>(K, N, WT, scr, it, lane, gk);
;         if (nx >= nitems) break;
;         it = nx;
;     }
; }
.Ltc1c_loop:
	s_add_u32 s9, s9, s19
	s_cmpk_ge_u32 s9, 0x3400
	s_cbranch_scc1 .Ltc1c_lastA
	s_mul_hi_u32 s11, s9, 0x4ec4ec4f
	s_lshr_b32 s11, s11, 7
	s_mul_i32 s12, s11, 0x1a0
	s_sub_u32 s12, s9, s12
	s_mul_i32 s13, s11, 0x340000
	s_lshl_b32 s14, s12, 7
	s_add_u32 s13, s13, s14
	s_add_u32 s14, s4, s13
	s_addc_u32 s15, s5, 0
	global_load_dword v88, v12, s[14:15] nt
	s_add_u32 s14, s14, 0x1a000
	s_addc_u32 s15, s15, 0
	global_load_dword v89, v12, s[14:15] nt
	s_add_u32 s14, s14, 0x1a000
	s_addc_u32 s15, s15, 0
	global_load_dword v90, v12, s[14:15] nt
	s_add_u32 s14, s14, 0x1a000
	s_addc_u32 s15, s15, 0
	global_load_dword v91, v12, s[14:15] nt
	s_add_u32 s14, s14, 0x1a000
	s_addc_u32 s15, s15, 0
	global_load_dword v92, v12, s[14:15] nt
	s_add_u32 s14, s14, 0x1a000
	s_addc_u32 s15, s15, 0
	global_load_dword v93, v12, s[14:15] nt
	s_add_u32 s14, s14, 0x1a000
	s_addc_u32 s15, s15, 0
	global_load_dword v94, v12, s[14:15] nt
	s_add_u32 s14, s14, 0x1a000
	s_addc_u32 s15, s15, 0
	global_load_dword v95, v12, s[14:15] nt
	s_add_u32 s14, s14, 0x1a000
	s_addc_u32 s15, s15, 0
	global_load_dword v96, v12, s[14:15] nt
	s_add_u32 s14, s14, 0x1a000
	s_addc_u32 s15, s15, 0
	global_load_dword v97, v12, s[14:15] nt
	s_add_u32 s14, s14, 0x1a000
	s_addc_u32 s15, s15, 0
	global_load_dword v98, v12, s[14:15] nt
	s_add_u32 s14, s14, 0x1a000
	s_addc_u32 s15, s15, 0
	global_load_dword v99, v12, s[14:15] nt
	s_add_u32 s14, s14, 0x1a000
	s_addc_u32 s15, s15, 0
	global_load_dword v100, v12, s[14:15] nt
	s_add_u32 s14, s14, 0x1a000
	s_addc_u32 s15, s15, 0
	global_load_dword v101, v12, s[14:15] nt
	s_add_u32 s14, s14, 0x1a000
	s_addc_u32 s15, s15, 0
	global_load_dword v102, v12, s[14:15] nt
	s_add_u32 s14, s14, 0x1a000
	s_addc_u32 s15, s15, 0
	global_load_dword v103, v12, s[14:15] nt
	s_add_u32 s14, s14, 0x1a000
	s_addc_u32 s15, s15, 0
	global_load_dword v104, v12, s[14:15] nt
	s_add_u32 s14, s14, 0x1a000
	s_addc_u32 s15, s15, 0
	global_load_dword v105, v12, s[14:15] nt
	s_add_u32 s14, s14, 0x1a000
	s_addc_u32 s15, s15, 0
	global_load_dword v106, v12, s[14:15] nt
	s_add_u32 s14, s14, 0x1a000
	s_addc_u32 s15, s15, 0
	global_load_dword v107, v12, s[14:15] nt
	s_add_u32 s14, s14, 0x1a000
	s_addc_u32 s15, s15, 0
	global_load_dword v108, v12, s[14:15] nt
	s_add_u32 s14, s14, 0x1a000
	s_addc_u32 s15, s15, 0
	global_load_dword v109, v12, s[14:15] nt
	s_add_u32 s14, s14, 0x1a000
	s_addc_u32 s15, s15, 0
	global_load_dword v110, v12, s[14:15] nt
	s_add_u32 s14, s14, 0x1a000
	s_addc_u32 s15, s15, 0
	global_load_dword v111, v12, s[14:15] nt
	s_add_u32 s14, s14, 0x1a000
	s_addc_u32 s15, s15, 0
	global_load_dword v112, v12, s[14:15] nt
	s_add_u32 s14, s14, 0x1a000
	s_addc_u32 s15, s15, 0
	global_load_dword v113, v12, s[14:15] nt
	s_add_u32 s14, s14, 0x1a000
	s_addc_u32 s15, s15, 0
	global_load_dword v114, v12, s[14:15] nt
	s_add_u32 s14, s14, 0x1a000
	s_addc_u32 s15, s15, 0
	global_load_dword v115, v12, s[14:15] nt
	s_add_u32 s14, s14, 0x1a000
	s_addc_u32 s15, s15, 0
	global_load_dword v116, v12, s[14:15] nt
	s_add_u32 s14, s14, 0x1a000
	s_addc_u32 s15, s15, 0
	global_load_dword v117, v12, s[14:15] nt
	s_add_u32 s14, s14, 0x1a000
	s_addc_u32 s15, s15, 0
	global_load_dword v118, v12, s[14:15] nt
	s_add_u32 s14, s14, 0x1a000
	s_addc_u32 s15, s15, 0
	global_load_dword v119, v12, s[14:15] nt
	s_lshl_b32 s14, s11, 8
	s_add_u32 s14, s20, s14
	s_addc_u32 s15, s21, 0
	global_load_dwordx4 v[120:123], v14, s[14:15]
	global_load_dwordx4 v[124:127], v14, s[14:15] offset:16
	s_sub_u32 s13, s12, 0x60
	s_cmp_lt_u32 s13, 0x40
	s_cselect_b32 s29, 1, 0
	s_cmp_lt_u32 s12, 0x40
	s_cselect_b32 s13, 1, 0
	s_or_b32 s29, s29, s13
	s_lshr_b32 s24, s12, 2
	s_lshl_b32 s24, s24, 5
	s_add_u32 s24, s24, s11
	s_lshl_b32 s24, s24, 14
	s_and_b32 s13, s12, 1
	s_lshl_b32 s13, s13, 13
	s_bfe_u32 s14, s12, 0x10001
	s_lshl_b32 s14, s14, 11
	s_add_u32 s13, s13, s14
	s_and_b32 s14, s12, 3
	s_lshl_b32 s14, s14, 12
	s_cmp_lg_u32 s29, 0
	s_cselect_b32 s13, s13, s14
	s_add_u32 s24, s24, s13
	s_add_u32 s24, s6, s24
	s_addc_u32 s25, s7, 0
	s_add_u32 s26, s24, 0x1000
	s_addc_u32 s27, s25, 0
	s_waitcnt vmcnt(34)
; #define LAS __attribute__((address_space(3)))
; __device__ __forceinline__ unsigned pk2(float lo, float hi) { f32x2 f = {lo, hi}; bf16x2_t b = __builtin_convertvector(f, bf16x2_t); return __builtin_bit_cast(unsigned, b); }
; template <int MAP, bool HASG, bool PERMW>
; __device__ __forceinline__ void tr_store(int K, int N, bf16_t* WT, LAS float* scr, int item, int lane, const float* gk) {
;     const int nblk = N / 32, kb = item / nblk, nb = item % nblk, k0 = 64 * kb, n0 = 32 * nb;
;     asm volatile("s_waitcnt lgkmcnt(0)" ::: "memory");
;     const int c = lane & 7;
;     f32x4 g0 = {1.f, 1.f, 1.f, 1.f}, g1 = {1.f, 1.f, 1.f, 1.f};
;     if (HASG) { g0 = *(const f32x4*)(gk + k0 + 8 * c); g1 = *(const f32x4*)(gk + k0 + 8 * c + 4); }
; #pragma unroll
;     for (int j = 0; j < 4; ++j) { const int n = (lane >> 3) + 8 * j; const LAS float* s = scr + (8 * c) * 33 + n;
;         u32x4 o; o.x = pk2(s[0 * 33] * g0[0], s[1 * 33] * g0[1]); o.y = pk2(s[2 * 33] * g0[2], s[3 * 33] * g0[3]); o.z = pk2(s[4 * 33] * g1[0], s[5 * 33] * g1[1]); o.w = pk2(s[6 * 33] * g1[2], s[7 * 33] * g1[3]);
;         const int wr_ = rowmap<MAP>(n0 + n), slot_ = PERMW ? ((wr_ & ~31) + invperm32(wr_ & 31)) : wr_;
;         *(u32x4*)((char*)WT + tiled_off(slot_, k0 + 8 * c, K / 64)) = o; }
;     asm volatile("s_waitcnt lgkmcnt(0)" ::: "memory");
; }
	ds_write_b32 v4, v16
	ds_write_b32 v4, v17 offset:264
	ds_write_b32 v4, v18 offset:528
	ds_write_b32 v4, v19 offset:792
	ds_write_b32 v4, v20 offset:1056
	ds_write_b32 v4, v21 offset:1320
	ds_write_b32 v4, v22 offset:1584
	ds_write_b32 v4, v23 offset:1848
	ds_write_b32 v4, v24 offset:2112
	ds_write_b32 v4, v25 offset:2376
	ds_write_b32 v4, v26 offset:2640
	ds_write_b32 v4, v27 offset:2904
	ds_write_b32 v4, v28 offset:3168
	ds_write_b32 v4, v29 offset:3432
	ds_write_b32 v4, v30 offset:3696
	ds_write_b32 v4, v31 offset:3960
	ds_write_b32 v4, v32 offset:4224
	ds_write_b32 v4, v33 offset:4488
	ds_write_b32 v4, v34 offset:4752
	ds_write_b32 v4, v35 offset:5016
	ds_write_b32 v4, v36 offset:5280
	ds_write_b32 v4, v37 offset:5544
	ds_write_b32 v4, v38 offset:5808
	ds_write_b32 v4, v39 offset:6072
	ds_write_b32 v4, v40 offset:6336
	ds_write_b32 v4, v41 offset:6600
	ds_write_b32 v4, v42 offset:6864
	ds_write_b32 v4, v43 offset:7128
	ds_write_b32 v4, v44 offset:7392
	ds_write_b32 v4, v45 offset:7656
	ds_write_b32 v4, v46 offset:7920
	ds_write_b32 v4, v47 offset:8184
	s_waitcnt lgkmcnt(0)
	ds_read_b32 v48, v7
	ds_read_b32 v49, v7 offset:132
	ds_read_b32 v50, v7 offset:264
	ds_read_b32 v51, v7 offset:396
	ds_read_b32 v52, v7 offset:528
	ds_read_b32 v53, v7 offset:660
	ds_read_b32 v54, v7 offset:792
	ds_read_b32 v55, v7 offset:924
	ds_read_b32 v56, v7 offset:32
	ds_read_b32 v57, v7 offset:164
	ds_read_b32 v58, v7 offset:296
	ds_read_b32 v59, v7 offset:428
	ds_read_b32 v60, v7 offset:560
	ds_read_b32 v61, v7 offset:692
	ds_read_b32 v62, v7 offset:824
	ds_read_b32 v63, v7 offset:956
	ds_read_b32 v64, v7 offset:64
	ds_read_b32 v65, v7 offset:196
	ds_read_b32 v66, v7 offset:328
	ds_read_b32 v67, v7 offset:460
	ds_read_b32 v68, v7 offset:592
	ds_read_b32 v69, v7 offset:724
	ds_read_b32 v70, v7 offset:856
	ds_read_b32 v71, v7 offset:988
	ds_read_b32 v72, v7 offset:96
	ds_read_b32 v73, v7 offset:228
	ds_read_b32 v74, v7 offset:360
	ds_read_b32 v75, v7 offset:492
	ds_read_b32 v76, v7 offset:624
	ds_read_b32 v77, v7 offset:756
	ds_read_b32 v78, v7 offset:888
	ds_read_b32 v79, v7 offset:1020
	s_waitcnt lgkmcnt(0)
	v_mul_f32_e32 v48, v48, v80
	v_mul_f32_e32 v49, v49, v81
	v_mul_f32_e32 v50, v50, v82
	v_mul_f32_e32 v51, v51, v83
	v_mul_f32_e32 v52, v52, v84
	v_mul_f32_e32 v53, v53, v85
	v_mul_f32_e32 v54, v54, v86
	v_mul_f32_e32 v55, v55, v87
	v_cvt_pk_bf16_f32 v48, v48, v49
	v_cvt_pk_bf16_f32 v49, v50, v51
	v_cvt_pk_bf16_f32 v50, v52, v53
	v_cvt_pk_bf16_f32 v51, v54, v55
	v_mul_f32_e32 v56, v56, v80
	v_mul_f32_e32 v57, v57, v81
	v_mul_f32_e32 v58, v58, v82
	v_mul_f32_e32 v59, v59, v83
	v_mul_f32_e32 v60, v60, v84
	v_mul_f32_e32 v61, v61, v85
	v_mul_f32_e32 v62, v62, v86
	v_mul_f32_e32 v63, v63, v87
	v_cvt_pk_bf16_f32 v56, v56, v57
	v_cvt_pk_bf16_f32 v57, v58, v59
	v_cvt_pk_bf16_f32 v58, v60, v61
	v_cvt_pk_bf16_f32 v59, v62, v63
	v_mul_f32_e32 v64, v64, v80
	v_mul_f32_e32 v65, v65, v81
	v_mul_f32_e32 v66, v66, v82
	v_mul_f32_e32 v67, v67, v83
	v_mul_f32_e32 v68, v68, v84
	v_mul_f32_e32 v69, v69, v85
	v_mul_f32_e32 v70, v70, v86
	v_mul_f32_e32 v71, v71, v87
	v_cvt_pk_bf16_f32 v64, v64, v65
	v_cvt_pk_bf16_f32 v65, v66, v67
	v_cvt_pk_bf16_f32 v66, v68, v69
	v_cvt_pk_bf16_f32 v67, v70, v71
	v_mul_f32_e32 v72, v72, v80
	v_mul_f32_e32 v73, v73, v81
	v_mul_f32_e32 v74, v74, v82
	v_mul_f32_e32 v75, v75, v83
	v_mul_f32_e32 v76, v76, v84
	v_mul_f32_e32 v77, v77, v85
	v_mul_f32_e32 v78, v78, v86
	v_mul_f32_e32 v79, v79, v87
	v_cvt_pk_bf16_f32 v72, v72, v73
	v_cvt_pk_bf16_f32 v73, v74, v75
	v_cvt_pk_bf16_f32 v74, v76, v77
	v_cvt_pk_bf16_f32 v75, v78, v79
	s_cmp_lg_u32 s28, 0
	s_cbranch_scc1 .Ltcw1_rot
	global_store_dwordx4 v10, v[48:51], s[16:17]
	global_store_dwordx4 v10, v[56:59], s[16:17] offset:256
	global_store_dwordx4 v11, v[64:67], s[16:17] offset:512
	global_store_dwordx4 v11, v[72:75], s[16:17] offset:768
	s_branch .Ltcw1_done

; __device__ __forceinline__ void tr_load(const float* W, int N, int item, int lane, float (&wv)[32]) {
;     const int nblk = N / 32, kb = item / nblk, nb = item % nblk, k0 = 64 * kb, n0 = 32 * nb;
; #pragma unroll
;     for (int i = 0; i < 32; ++i) { const int kk = 2 * i + (lane >> 5); wv[i] = __builtin_nontemporal_load(W + (size_t)(k0 + kk) * N + n0 + (lane & 31)); }
; }
; template <int MAP, bool HASG, bool PERMW>
; __device__ __forceinline__ void tr_store(int K, int N, bf16_t* WT, LAS float* scr, int item, int lane, const float* gk) {
;     const int nblk = N / 32, kb = item / nblk, nb = item % nblk, k0 = 64 * kb, n0 = 32 * nb;
;     asm volatile("s_waitcnt lgkmcnt(0)" ::: "memory");
;     const int c = lane & 7;
;     f32x4 g0 = {1.f, 1.f, 1.f, 1.f}, g1 = {1.f, 1.f, 1.f, 1.f};
;     if (HASG) { g0 = *(const f32x4*)(gk + k0 + 8 * c); g1 = *(const f32x4*)(gk + k0 + 8 * c + 4); }
; #pragma unroll
;     for (int j = 0; j < 4; ++j) { const int n = (lane >> 3) + 8 * j; const LAS float* s = scr + (8 * c) * 33 + n;
;         u32x4 o; o.x = pk2(s[0 * 33] * g0[0], s[1 * 33] * g0[1]); o.y = pk2(s[2 * 33] * g0[2], s[3 * 33] * g0[3]); o.z = pk2(s[4 * 33] * g1[0], s[5 * 33] * g1[1]); o.w = pk2(s[6 * 33] * g1[2], s[7 * 33] * g1[3]);
;         const int wr_ = rowmap<MAP>(n0 + n), slot_ = PERMW ? ((wr_ & ~31) + invperm32(wr_ & 31)) : wr_;
;         *(u32x4*)((char*)WT + tiled_off(slot_, k0 + 8 * c, K / 64)) = o; }
;     asm volatile("s_waitcnt lgkmcnt(0)" ::: "memory");
; }
; template <int MAP, bool HASG = false, bool PERMW = false>
; __device__ __forceinline__ void transpose_mat(const float* W, int K, int N, bf16_t* WT, LAS float* scr, int gw, int ngw, int lane, const float* gk = nullptr) {
;     const int nitems = (K / 64) * (N / 32);
;     int it = gw;
;     if (it >= nitems) return;
;     float wv[32];
;     tr_load(W, N, it, lane, wv);
;     for (;;) {
;         __builtin_amdgcn_sched_barrier(0);
; #pragma unroll
;         for (int i = 0; i < 32; ++i) { const int kk = 2 * i + (lane >> 5); scr[kk * 33 + (lane & 31)] = wv[i]; }
;         __builtin_amdgcn_sched_barrier(0);
;         const int nx = it + ngw;
;         if (nx < nitems) tr_load(W, N, nx, lane, wv);
;         __builtin_amdgcn_sched_barrier(0);
;         tr_store<MAP, HASG, PERMW>(K, N, WT, scr, it, lane, gk);
;         if (nx >= nitems) break;
;         it = nx;
;     }
; }
.Ltcw1_done:
	s_add_u32 s9, s9, s19
	s_cmpk_ge_u32 s9, 0x3400
	s_cbranch_scc1 .Ltc1c_lastB
	s_mul_hi_u32 s11, s9, 0x4ec4ec4f
	s_lshr_b32 s11, s11, 7
	s_mul_i32 s12, s11, 0x1a0
	s_sub_u32 s12, s9, s12
	s_mul_i32 s13, s11, 0x340000
	s_lshl_b32 s14, s12, 7
	s_add_u32 s13, s13, s14
	s_add_u32 s14, s4, s13
	s_addc_u32 s15, s5, 0
	global_load_dword v16, v12, s[14:15] nt
	s_add_u32 s14, s14, 0x1a000
	s_addc_u32 s15, s15, 0
	global_load_dword v17, v12, s[14:15] nt
	s_add_u32 s14, s14, 0x1a000
	s_addc_u32 s15, s15, 0
	global_load_dword v18, v12, s[14:15] nt
	s_add_u32 s14, s14, 0x1a000
	s_addc_u32 s15, s15, 0
	global_load_dword v19, v12, s[14:15] nt
	s_add_u32 s14, s14, 0x1a000
	s_addc_u32 s15, s15, 0
	global_load_dword v20, v12, s[14:15] nt
	s_add_u32 s14, s14, 0x1a000
	s_addc_u32 s15, s15, 0
	global_load_dword v21, v12, s[14:15] nt
	s_add_u32 s14, s14, 0x1a000
	s_addc_u32 s15, s15, 0
	global_load_dword v22, v12, s[14:15] nt
	s_add_u32 s14, s14, 0x1a000
	s_addc_u32 s15, s15, 0
	global_load_dword v23, v12, s[14:15] nt
	s_add_u32 s14, s14, 0x1a000
	s_addc_u32 s15, s15, 0
	global_load_dword v24, v12, s[14:15] nt
	s_add_u32 s14, s14, 0x1a000
	s_addc_u32 s15, s15, 0
	global_load_dword v25, v12, s[14:15] nt
	s_add_u32 s14, s14, 0x1a000
	s_addc_u32 s15, s15, 0
	global_load_dword v26, v12, s[14:15] nt
	s_add_u32 s14, s14, 0x1a000
	s_addc_u32 s15, s15, 0
	global_load_dword v27, v12, s[14:15] nt
	s_add_u32 s14, s14, 0x1a000
	s_addc_u32 s15, s15, 0
	global_load_dword v28, v12, s[14:15] nt
	s_add_u32 s14, s14, 0x1a000
	s_addc_u32 s15, s15, 0
	global_load_dword v29, v12, s[14:15] nt
	s_add_u32 s14, s14, 0x1a000
	s_addc_u32 s15, s15, 0
	global_load_dword v30, v12, s[14:15] nt
	s_add_u32 s14, s14, 0x1a000
	s_addc_u32 s15, s15, 0
	global_load_dword v31, v12, s[14:15] nt
	s_add_u32 s14, s14, 0x1a000
	s_addc_u32 s15, s15, 0
	global_load_dword v32, v12, s[14:15] nt
	s_add_u32 s14, s14, 0x1a000
	s_addc_u32 s15, s15, 0
	global_load_dword v33, v12, s[14:15] nt
	s_add_u32 s14, s14, 0x1a000
	s_addc_u32 s15, s15, 0
	global_load_dword v34, v12, s[14:15] nt
	s_add_u32 s14, s14, 0x1a000
	s_addc_u32 s15, s15, 0
	global_load_dword v35, v12, s[14:15] nt
	s_add_u32 s14, s14, 0x1a000
	s_addc_u32 s15, s15, 0
	global_load_dword v36, v12, s[14:15] nt
	s_add_u32 s14, s14, 0x1a000
	s_addc_u32 s15, s15, 0
	global_load_dword v37, v12, s[14:15] nt
	s_add_u32 s14, s14, 0x1a000
	s_addc_u32 s15, s15, 0
	global_load_dword v38, v12, s[14:15] nt
	s_add_u32 s14, s14, 0x1a000
	s_addc_u32 s15, s15, 0
	global_load_dword v39, v12, s[14:15] nt
	s_add_u32 s14, s14, 0x1a000
	s_addc_u32 s15, s15, 0
	global_load_dword v40, v12, s[14:15] nt
	s_add_u32 s14, s14, 0x1a000
	s_addc_u32 s15, s15, 0
	global_load_dword v41, v12, s[14:15] nt
	s_add_u32 s14, s14, 0x1a000
	s_addc_u32 s15, s15, 0
	global_load_dword v42, v12, s[14:15] nt
	s_add_u32 s14, s14, 0x1a000
	s_addc_u32 s15, s15, 0
	global_load_dword v43, v12, s[14:15] nt
	s_add_u32 s14, s14, 0x1a000
	s_addc_u32 s15, s15, 0
	global_load_dword v44, v12, s[14:15] nt
	s_add_u32 s14, s14, 0x1a000
	s_addc_u32 s15, s15, 0
	global_load_dword v45, v12, s[14:15] nt
	s_add_u32 s14, s14, 0x1a000
	s_addc_u32 s15, s15, 0
	global_load_dword v46, v12, s[14:15] nt
	s_add_u32 s14, s14, 0x1a000
	s_addc_u32 s15, s15, 0
	global_load_dword v47, v12, s[14:15] nt
	s_lshl_b32 s14, s11, 8
	s_add_u32 s14, s20, s14
	s_addc_u32 s15, s21, 0
	global_load_dwordx4 v[80:83], v14, s[14:15]
	global_load_dwordx4 v[84:87], v14, s[14:15] offset:16
	s_sub_u32 s13, s12, 0x60
	s_cmp_lt_u32 s13, 0x40
	s_cselect_b32 s28, 1, 0
	s_cmp_lt_u32 s12, 0x40
	s_cselect_b32 s13, 1, 0
	s_or_b32 s28, s28, s13
	s_lshr_b32 s16, s12, 2
	s_lshl_b32 s16, s16, 5
	s_add_u32 s16, s16, s11
	s_lshl_b32 s16, s16, 14
	s_and_b32 s13, s12, 1
	s_lshl_b32 s13, s13, 13
	s_bfe_u32 s14, s12, 0x10001
	s_lshl_b32 s14, s14, 11
	s_add_u32 s13, s13, s14
	s_and_b32 s14, s12, 3
	s_lshl_b32 s14, s14, 12
	s_cmp_lg_u32 s28, 0
	s_cselect_b32 s13, s13, s14
	s_add_u32 s16, s16, s13
	s_add_u32 s16, s6, s16
	s_addc_u32 s17, s7, 0
	s_add_u32 s22, s16, 0x1000
	s_addc_u32 s23, s17, 0
	s_waitcnt vmcnt(34)
; #define LAS __attribute__((address_space(3)))
; __device__ __forceinline__ unsigned pk2(float lo, float hi) { f32x2 f = {lo, hi}; bf16x2_t b = __builtin_convertvector(f, bf16x2_t); return __builtin_bit_cast(unsigned, b); }
; template <int MAP, bool HASG, bool PERMW>
; __device__ __forceinline__ void tr_store(int K, int N, bf16_t* WT, LAS float* scr, int item, int lane, const float* gk) {
;     ...
;     asm volatile("s_waitcnt lgkmcnt(0)" ::: "memory");
;     const int c = lane & 7;
;     f32x4 g0 = {1.f, 1.f, 1.f, 1.f}, g1 = {1.f, 1.f, 1.f, 1.f};
;     if (HASG) { g0 = *(const f32x4*)(gk + k0 + 8 * c); g1 = *(const f32x4*)(gk + k0 + 8 * c + 4); }
; #pragma unroll
;     for (int j = 0; j < 4; ++j) { const int n = (lane >> 3) + 8 * j; const LAS float* s = scr + (8 * c) * 33 + n;
;         u32x4 o; o.x = pk2(s[0 * 33] * g0[0], s[1 * 33] * g0[1]); o.y = pk2(s[2 * 33] * g0[2], s[3 * 33] * g0[3]); o.z = pk2(s[4 * 33] * g1[0], s[5 * 33] * g1[1]); o.w = pk2(s[6 * 33] * g1[2], s[7 * 33] * g1[3]);
;         const int wr_ = rowmap<MAP>(n0 + n), slot_ = PERMW ? ((wr_ & ~31) + invperm32(wr_ & 31)) : wr_;
;         *(u32x4*)((char*)WT + tiled_off(slot_, k0 + 8 * c, K / 64)) = o; }
;     asm volatile("s_waitcnt lgkmcnt(0)" ::: "memory");
; template <int MAP, bool HASG = false, bool PERMW = false>
; __device__ __forceinline__ void transpose_mat(const float* W, int K, int N, bf16_t* WT, LAS float* scr, int gw, int ngw, int lane, const float* gk = nullptr) {
;     ...
;         for (int i = 0; i < 32; ++i) { const int kk = 2 * i + (lane >> 5); scr[kk * 33 + (lane & 31)] = wv[i]; }
	ds_write_b32 v4, v88
	ds_write_b32 v4, v89 offset:264
	ds_write_b32 v4, v90 offset:528
	ds_write_b32 v4, v91 offset:792
	ds_write_b32 v4, v92 offset:1056
	ds_write_b32 v4, v93 offset:1320
	ds_write_b32 v4, v94 offset:1584
	ds_write_b32 v4, v95 offset:1848
	ds_write_b32 v4, v96 offset:2112
	ds_write_b32 v4, v97 offset:2376
	ds_write_b32 v4, v98 offset:2640
	ds_write_b32 v4, v99 offset:2904
	ds_write_b32 v4, v100 offset:3168
	ds_write_b32 v4, v101 offset:3432
	ds_write_b32 v4, v102 offset:3696
	ds_write_b32 v4, v103 offset:3960
	ds_write_b32 v4, v104 offset:4224
	ds_write_b32 v4, v105 offset:4488
	ds_write_b32 v4, v106 offset:4752
	ds_write_b32 v4, v107 offset:5016
	ds_write_b32 v4, v108 offset:5280
	ds_write_b32 v4, v109 offset:5544
	ds_write_b32 v4, v110 offset:5808
	ds_write_b32 v4, v111 offset:6072
	ds_write_b32 v4, v112 offset:6336
	ds_write_b32 v4, v113 offset:6600
	ds_write_b32 v4, v114 offset:6864
	ds_write_b32 v4, v115 offset:7128
	ds_write_b32 v4, v116 offset:7392
	ds_write_b32 v4, v117 offset:7656
	ds_write_b32 v4, v118 offset:7920
	ds_write_b32 v4, v119 offset:8184
	s_waitcnt lgkmcnt(0)
	ds_read_b32 v48, v7
	ds_read_b32 v49, v7 offset:132
	ds_read_b32 v50, v7 offset:264
	ds_read_b32 v51, v7 offset:396
	ds_read_b32 v52, v7 offset:528
	ds_read_b32 v53, v7 offset:660
	ds_read_b32 v54, v7 offset:792
	ds_read_b32 v55, v7 offset:924
	ds_read_b32 v56, v7 offset:32
	ds_read_b32 v57, v7 offset:164
	ds_read_b32 v58, v7 offset:296
	ds_read_b32 v59, v7 offset:428
	ds_read_b32 v60, v7 offset:560
	ds_read_b32 v61, v7 offset:692
	ds_read_b32 v62, v7 offset:824
	ds_read_b32 v63, v7 offset:956
	ds_read_b32 v64, v7 offset:64
	ds_read_b32 v65, v7 offset:196
	ds_read_b32 v66, v7 offset:328
	ds_read_b32 v67, v7 offset:460
	ds_read_b32 v68, v7 offset:592
	ds_read_b32 v69, v7 offset:724
	ds_read_b32 v70, v7 offset:856
	ds_read_b32 v71, v7 offset:988
	ds_read_b32 v72, v7 offset:96
	ds_read_b32 v73, v7 offset:228
	ds_read_b32 v74, v7 offset:360
	ds_read_b32 v75, v7 offset:492
	ds_read_b32 v76, v7 offset:624
	ds_read_b32 v77, v7 offset:756
	ds_read_b32 v78, v7 offset:888
	ds_read_b32 v79, v7 offset:1020
	s_waitcnt lgkmcnt(0)
	v_mul_f32_e32 v48, v48, v120
	v_mul_f32_e32 v49, v49, v121
	v_mul_f32_e32 v50, v50, v122
	v_mul_f32_e32 v51, v51, v123
	v_mul_f32_e32 v52, v52, v124
	v_mul_f32_e32 v53, v53, v125
	v_mul_f32_e32 v54, v54, v126
	v_mul_f32_e32 v55, v55, v127
	v_cvt_pk_bf16_f32 v48, v48, v49
	v_cvt_pk_bf16_f32 v49, v50, v51
	v_cvt_pk_bf16_f32 v50, v52, v53
	v_cvt_pk_bf16_f32 v51, v54, v55
	v_mul_f32_e32 v56, v56, v120
	v_mul_f32_e32 v57, v57, v121
	v_mul_f32_e32 v58, v58, v122
	v_mul_f32_e32 v59, v59, v123
	v_mul_f32_e32 v60, v60, v124
	v_mul_f32_e32 v61, v61, v125
	v_mul_f32_e32 v62, v62, v126
	v_mul_f32_e32 v63, v63, v127
	v_cvt_pk_bf16_f32 v56, v56, v57
	v_cvt_pk_bf16_f32 v57, v58, v59
	v_cvt_pk_bf16_f32 v58, v60, v61
	v_cvt_pk_bf16_f32 v59, v62, v63
	v_mul_f32_e32 v64, v64, v120
	v_mul_f32_e32 v65, v65, v121
	v_mul_f32_e32 v66, v66, v122
	v_mul_f32_e32 v67, v67, v123
	v_mul_f32_e32 v68, v68, v124
	v_mul_f32_e32 v69, v69, v125
	v_mul_f32_e32 v70, v70, v126
	v_mul_f32_e32 v71, v71, v127
	v_cvt_pk_bf16_f32 v64, v64, v65
	v_cvt_pk_bf16_f32 v65, v66, v67
	v_cvt_pk_bf16_f32 v66, v68, v69
	v_cvt_pk_bf16_f32 v67, v70, v71
	v_mul_f32_e32 v72, v72, v120
	v_mul_f32_e32 v73, v73, v121
	v_mul_f32_e32 v74, v74, v122
	v_mul_f32_e32 v75, v75, v123
	v_mul_f32_e32 v76, v76, v124
	v_mul_f32_e32 v77, v77, v125
	v_mul_f32_e32 v78, v78, v126
	v_mul_f32_e32 v79, v79, v127
	v_cvt_pk_bf16_f32 v72, v72, v73
	v_cvt_pk_bf16_f32 v73, v74, v75
	v_cvt_pk_bf16_f32 v74, v76, v77
	v_cvt_pk_bf16_f32 v75, v78, v79
	s_cmp_lg_u32 s29, 0
	s_cbranch_scc1 .Ltcw2_rot
	global_store_dwordx4 v10, v[48:51], s[24:25]
	global_store_dwordx4 v10, v[56:59], s[24:25] offset:256
	global_store_dwordx4 v11, v[64:67], s[24:25] offset:512
	global_store_dwordx4 v11, v[72:75], s[24:25] offset:768
	s_branch .Ltcw2_done

; #define LAS __attribute__((address_space(3)))
; __device__ __forceinline__ void tr_load(const float* W, int N, int item, int lane, float (&wv)[32]) {
;     const int nblk = N / 32, kb = item / nblk, nb = item % nblk, k0 = 64 * kb, n0 = 32 * nb;
; #pragma unroll
;     for (int i = 0; i < 32; ++i) { const int kk = 2 * i + (lane >> 5); wv[i] = __builtin_nontemporal_load(W + (size_t)(k0 + kk) * N + n0 + (lane & 31)); }
; }
; template <int MAP, bool HASG, bool PERMW>
; __device__ __forceinline__ void tr_store(int K, int N, bf16_t* WT, LAS float* scr, int item, int lane, const float* gk) {
;     const int nblk = N / 32, kb = item / nblk, nb = item % nblk, k0 = 64 * kb, n0 = 32 * nb;
; template <int MAP, bool HASG = false, bool PERMW = false>
; __device__ __forceinline__ void transpose_mat(const float* W, int K, int N, bf16_t* WT, LAS float* scr, int gw, int ngw, int lane, const float* gk = nullptr) {
;     const int nitems = (K / 64) * (N / 32);
;     int it = gw;
;     if (it >= nitems) return;
;     float wv[32];
;     tr_load(W, N, it, lane, wv);
.LBB0_378:
	s_lshr_b32 vcc_lo, s78, 1
	s_cmp_lt_u32 s2, vcc_lo
	s_cbranch_scc1 .Ltc3_done
	v_writelane_b32 v255, s4, 24
	v_writelane_b32 v255, s5, 25
	v_writelane_b32 v255, s6, 26
	v_writelane_b32 v255, s7, 27
	v_writelane_b32 v255, s8, 28
	v_writelane_b32 v255, s9, 29
	v_writelane_b32 v255, s10, 30
	v_writelane_b32 v255, s11, 31
	v_writelane_b32 v255, s12, 32
	v_writelane_b32 v255, s13, 33
	v_writelane_b32 v255, s14, 34
	v_writelane_b32 v255, s15, 35
	v_writelane_b32 v255, s16, 36
	v_writelane_b32 v255, s17, 37
	v_writelane_b32 v255, s18, 38
	v_writelane_b32 v255, s19, 39
	v_writelane_b32 v255, s20, 40
	v_writelane_b32 v255, s21, 41
	v_writelane_b32 v255, s22, 42
	v_writelane_b32 v255, s23, 43
	v_writelane_b32 v255, s24, 44
	v_writelane_b32 v255, s25, 45
	v_writelane_b32 v255, s26, 46
	v_writelane_b32 v255, s27, 47
	v_writelane_b32 v255, s28, 48
	v_writelane_b32 v255, s29, 49
	v_readfirstlane_b32 s8, v234
	s_nop 3
	s_lshr_b32 s8, s8, 6
	s_lshr_b32 s19, s78, 1
	s_sub_u32 s18, s2, s19
	s_lshl_b32 s18, s18, 3
	s_add_u32 s18, s18, s8
	s_sub_u32 s19, s78, s19
	s_lshl_b32 s19, s19, 3
	s_mul_i32 s10, s8, 0x2100
	v_and_b32_e32 v0, 63, v234
	v_and_b32_e32 v1, 31, v0
	v_lshrrev_b32_e32 v2, 5, v0
	v_lshlrev_b32_e32 v3, 13, v2
	v_lshl_add_u32 v3, v1, 2, v3
	v_mul_u32_u24_e32 v4, 33, v2
	v_add_u32_e32 v4, v4, v1
	v_lshl_add_u32 v4, v4, 2, s10
	v_and_b32_e32 v5, 7, v0
	v_lshrrev_b32_e32 v6, 3, v0
	v_mul_u32_u24_e32 v7, 0x108, v5
	v_add_u32_e32 v7, v7, v6
	v_lshl_add_u32 v7, v7, 2, s10
	v_lshrrev_b32_e32 v12, 2, v5
	v_lshlrev_b32_e32 v12, 10, v12
	v_and_b32_e32 v13, 3, v5
	v_lshl_add_u32 v12, v13, 4, v12
	v_lshl_add_u32 v8, v6, 6, v12
	v_xor_b32_e32 v9, 32, v8
	v_add_u32_e32 v9, 0x200, v9
	v_and_b32_e32 v13, 3, v6
	v_lshl_add_u32 v10, v13, 6, v12
	v_bfe_u32 v13, v6, 2, 1
	v_lshl_add_u32 v10, v13, 11, v10
	v_xor_b32_e32 v11, 32, v10
	v_lshlrev_b32_e32 v14, 5, v5
	v_mul_u32_u24_e32 v15, 0x5800, v2
	v_lshl_add_u32 v15, v1, 2, v15
	v_mul_u32_u24_e32 v12, 0xd000, v2
	v_lshl_add_u32 v12, v1, 2, v12
	v_readlane_b32 s4, v255, 10
	v_readlane_b32 s5, v255, 11
	s_nop 3
	s_and_b32 s6, s60, 0x800000
	s_add_u32 s4, s4, s6
	s_addc_u32 s5, s5, 0
	s_add_u32 s6, s76, 0x7600000
	s_addc_u32 s7, s77, 0
	s_mov_b32 s9, s18
	s_cmpk_ge_u32 s9, 0x400
	s_cbranch_scc1 .Ltc3a_exit
	s_lshr_b32 s11, s9, 6
	s_and_b32 s12, s9, 63
	s_lshl_b32 s13, s11, 19
	s_lshl_b32 s14, s12, 7
	s_add_u32 s13, s13, s14
	s_add_u32 s14, s4, s13
	s_addc_u32 s15, s5, 0
	global_load_dword v16, v3, s[14:15] nt
	s_add_u32 s14, s14, 0x4000
	s_addc_u32 s15, s15, 0
	global_load_dword v17, v3, s[14:15] nt
	s_add_u32 s14, s14, 0x4000
	s_addc_u32 s15, s15, 0
	global_load_dword v18, v3, s[14:15] nt
	s_add_u32 s14, s14, 0x4000
	s_addc_u32 s15, s15, 0
	global_load_dword v19, v3, s[14:15] nt
	s_add_u32 s14, s14, 0x4000
	s_addc_u32 s15, s15, 0
	global_load_dword v20, v3, s[14:15] nt
	s_add_u32 s14, s14, 0x4000
	s_addc_u32 s15, s15, 0
	global_load_dword v21, v3, s[14:15] nt
	s_add_u32 s14, s14, 0x4000
	s_addc_u32 s15, s15, 0
	global_load_dword v22, v3, s[14:15] nt
	s_add_u32 s14, s14, 0x4000
	s_addc_u32 s15, s15, 0
	global_load_dword v23, v3, s[14:15] nt
	s_add_u32 s14, s14, 0x4000
	s_addc_u32 s15, s15, 0
	global_load_dword v24, v3, s[14:15] nt
	s_add_u32 s14, s14, 0x4000
	s_addc_u32 s15, s15, 0
	global_load_dword v25, v3, s[14:15] nt
	s_add_u32 s14, s14, 0x4000
	s_addc_u32 s15, s15, 0
	global_load_dword v26, v3, s[14:15] nt
	s_add_u32 s14, s14, 0x4000
	s_addc_u32 s15, s15, 0
	global_load_dword v27, v3, s[14:15] nt
	s_add_u32 s14, s14, 0x4000
	s_addc_u32 s15, s15, 0
	global_load_dword v28, v3, s[14:15] nt
	s_add_u32 s14, s14, 0x4000
	s_addc_u32 s15, s15, 0
	global_load_dword v29, v3, s[14:15] nt
	s_add_u32 s14, s14, 0x4000
	s_addc_u32 s15, s15, 0
	global_load_dword v30, v3, s[14:15] nt
	s_add_u32 s14, s14, 0x4000
	s_addc_u32 s15, s15, 0
	global_load_dword v31, v3, s[14:15] nt
	s_add_u32 s14, s14, 0x4000
	s_addc_u32 s15, s15, 0
	global_load_dword v32, v3, s[14:15] nt
	s_add_u32 s14, s14, 0x4000
	s_addc_u32 s15, s15, 0
	global_load_dword v33, v3, s[14:15] nt
	s_add_u32 s14, s14, 0x4000
	s_addc_u32 s15, s15, 0
	global_load_dword v34, v3, s[14:15] nt
	s_add_u32 s14, s14, 0x4000
	s_addc_u32 s15, s15, 0
	global_load_dword v35, v3, s[14:15] nt
	s_add_u32 s14, s14, 0x4000
	s_addc_u32 s15, s15, 0
	global_load_dword v36, v3, s[14:15] nt
	s_add_u32 s14, s14, 0x4000
	s_addc_u32 s15, s15, 0
	global_load_dword v37, v3, s[14:15] nt
	s_add_u32 s14, s14, 0x4000
	s_addc_u32 s15, s15, 0
	global_load_dword v38, v3, s[14:15] nt
	s_add_u32 s14, s14, 0x4000
	s_addc_u32 s15, s15, 0
	global_load_dword v39, v3, s[14:15] nt
	s_add_u32 s14, s14, 0x4000
	s_addc_u32 s15, s15, 0
	global_load_dword v40, v3, s[14:15] nt
	s_add_u32 s14, s14, 0x4000
	s_addc_u32 s15, s15, 0
	global_load_dword v41, v3, s[14:15] nt
	s_add_u32 s14, s14, 0x4000
	s_addc_u32 s15, s15, 0
	global_load_dword v42, v3, s[14:15] nt
	s_add_u32 s14, s14, 0x4000
	s_addc_u32 s15, s15, 0
	global_load_dword v43, v3, s[14:15] nt
	s_add_u32 s14, s14, 0x4000
	s_addc_u32 s15, s15, 0
	global_load_dword v44, v3, s[14:15] nt
	s_add_u32 s14, s14, 0x4000
	s_addc_u32 s15, s15, 0
	global_load_dword v45, v3, s[14:15] nt
	s_add_u32 s14, s14, 0x4000
	s_addc_u32 s15, s15, 0
	global_load_dword v46, v3, s[14:15] nt
	s_add_u32 s14, s14, 0x4000
	s_addc_u32 s15, s15, 0
	global_load_dword v47, v3, s[14:15] nt
	s_lshr_b32 s16, s12, 2
	s_mul_i32 s16, s16, 0x10
	s_add_u32 s16, s16, s11
	s_lshl_b32 s16, s16, 14
	s_and_b32 s17, s12, 3
	s_lshl_b32 s17, s17, 12
	s_add_u32 s16, s16, s17
	s_add_u32 s16, s6, s16
	s_addc_u32 s17, s7, 0
; #define LAS __attribute__((address_space(3)))
; __device__ __forceinline__ void tr_load(const float* W, int N, int item, int lane, float (&wv)[32]) {
;     const int nblk = N / 32, kb = item / nblk, nb = item % nblk, k0 = 64 * kb, n0 = 32 * nb;
; #pragma unroll
;     for (int i = 0; i < 32; ++i) { const int kk = 2 * i + (lane >> 5); wv[i] = __builtin_nontemporal_load(W + (size_t)(k0 + kk) * N + n0 + (lane & 31)); }
; }
; template <int MAP, bool HASG, bool PERMW>
; __device__ __forceinline__ void tr_store(int K, int N, bf16_t* WT, LAS float* scr, int item, int lane, const float* gk) {
;     const int nblk = N / 32, kb = item / nblk, nb = item % nblk, k0 = 64 * kb, n0 = 32 * nb;
;     asm volatile("s_waitcnt lgkmcnt(0)" ::: "memory");
;     const int c = lane & 7;
;     f32x4 g0 = {1.f, 1.f, 1.f, 1.f}, g1 = {1.f, 1.f, 1.f, 1.f};
;     if (HASG) { g0 = *(const f32x4*)(gk + k0 + 8 * c); g1 = *(const f32x4*)(gk + k0 + 8 * c + 4); }
; #pragma unroll
;     for (int j = 0; j < 4; ++j) { const int n = (lane >> 3) + 8 * j; const LAS float* s = scr + (8 * c) * 33 + n;
;         u32x4 o; o.x = pk2(s[0 * 33] * g0[0], s[1 * 33] * g0[1]); o.y = pk2(s[2 * 33] * g0[2], s[3 * 33] * g0[3]); o.z = pk2(s[4 * 33] * g1[0], s[5 * 33] * g1[1]); o.w = pk2(s[6 * 33] * g1[2], s[7 * 33] * g1[3]);
;         const int wr_ = rowmap<MAP>(n0 + n), slot_ = PERMW ? ((wr_ & ~31) + invperm32(wr_ & 31)) : wr_;
;         *(u32x4*)((char*)WT + tiled_off(slot_, k0 + 8 * c, K / 64)) = o; }
;     asm volatile("s_waitcnt lgkmcnt(0)" ::: "memory");
; }
; template <int MAP, bool HASG = false, bool PERMW = false>
; __device__ __forceinline__ void transpose_mat(const float* W, int K, int N, bf16_t* WT, LAS float* scr, int gw, int ngw, int lane, const float* gk = nullptr) {
;     ...
;     for (;;) {
;         __builtin_amdgcn_sched_barrier(0);
; #pragma unroll
;         for (int i = 0; i < 32; ++i) { const int kk = 2 * i + (lane >> 5); scr[kk * 33 + (lane & 31)] = wv[i]; }
;         __builtin_amdgcn_sched_barrier(0);
;         const int nx = it + ngw;
;         if (nx < nitems) tr_load(W, N, nx, lane, wv);
;         __builtin_amdgcn_sched_barrier(0);
;         tr_store<MAP, HASG, PERMW>(K, N, WT, scr, it, lane, gk);
;         if (nx >= nitems) break;
;         it = nx;
;     }
.Ltc3a_loop:
	s_add_u32 s9, s9, s19
	s_cmpk_ge_u32 s9, 0x400
	s_cbranch_scc1 .Ltc3a_lastA
	s_lshr_b32 s11, s9, 6
	s_and_b32 s12, s9, 63
	s_lshl_b32 s13, s11, 19
	s_lshl_b32 s14, s12, 7
	s_add_u32 s13, s13, s14
	s_add_u32 s14, s4, s13
	s_addc_u32 s15, s5, 0
	global_load_dword v88, v3, s[14:15] nt
	s_add_u32 s14, s14, 0x4000
	s_addc_u32 s15, s15, 0
	global_load_dword v89, v3, s[14:15] nt
	s_add_u32 s14, s14, 0x4000
	s_addc_u32 s15, s15, 0
	global_load_dword v90, v3, s[14:15] nt
	s_add_u32 s14, s14, 0x4000
	s_addc_u32 s15, s15, 0
	global_load_dword v91, v3, s[14:15] nt
	s_add_u32 s14, s14, 0x4000
	s_addc_u32 s15, s15, 0
	global_load_dword v92, v3, s[14:15] nt
	s_add_u32 s14, s14, 0x4000
	s_addc_u32 s15, s15, 0
	global_load_dword v93, v3, s[14:15] nt
	s_add_u32 s14, s14, 0x4000
	s_addc_u32 s15, s15, 0
	global_load_dword v94, v3, s[14:15] nt
	s_add_u32 s14, s14, 0x4000
	s_addc_u32 s15, s15, 0
	global_load_dword v95, v3, s[14:15] nt
	s_add_u32 s14, s14, 0x4000
	s_addc_u32 s15, s15, 0
	global_load_dword v96, v3, s[14:15] nt
	s_add_u32 s14, s14, 0x4000
	s_addc_u32 s15, s15, 0
	global_load_dword v97, v3, s[14:15] nt
	s_add_u32 s14, s14, 0x4000
	s_addc_u32 s15, s15, 0
	global_load_dword v98, v3, s[14:15] nt
	s_add_u32 s14, s14, 0x4000
	s_addc_u32 s15, s15, 0
	global_load_dword v99, v3, s[14:15] nt
	s_add_u32 s14, s14, 0x4000
	s_addc_u32 s15, s15, 0
	global_load_dword v100, v3, s[14:15] nt
	s_add_u32 s14, s14, 0x4000
	s_addc_u32 s15, s15, 0
	global_load_dword v101, v3, s[14:15] nt
	s_add_u32 s14, s14, 0x4000
	s_addc_u32 s15, s15, 0
	global_load_dword v102, v3, s[14:15] nt
	s_add_u32 s14, s14, 0x4000
	s_addc_u32 s15, s15, 0
	global_load_dword v103, v3, s[14:15] nt
	s_add_u32 s14, s14, 0x4000
	s_addc_u32 s15, s15, 0
	global_load_dword v104, v3, s[14:15] nt
	s_add_u32 s14, s14, 0x4000
	s_addc_u32 s15, s15, 0
	global_load_dword v105, v3, s[14:15] nt
	s_add_u32 s14, s14, 0x4000
	s_addc_u32 s15, s15, 0
	global_load_dword v106, v3, s[14:15] nt
	s_add_u32 s14, s14, 0x4000
	s_addc_u32 s15, s15, 0
	global_load_dword v107, v3, s[14:15] nt
	s_add_u32 s14, s14, 0x4000
	s_addc_u32 s15, s15, 0
	global_load_dword v108, v3, s[14:15] nt
	s_add_u32 s14, s14, 0x4000
	s_addc_u32 s15, s15, 0
	global_load_dword v109, v3, s[14:15] nt
	s_add_u32 s14, s14, 0x4000
	s_addc_u32 s15, s15, 0
	global_load_dword v110, v3, s[14:15] nt
	s_add_u32 s14, s14, 0x4000
	s_addc_u32 s15, s15, 0
	global_load_dword v111, v3, s[14:15] nt
	s_add_u32 s14, s14, 0x4000
	s_addc_u32 s15, s15, 0
	global_load_dword v112, v3, s[14:15] nt
	s_add_u32 s14, s14, 0x4000
	s_addc_u32 s15, s15, 0
	global_load_dword v113, v3, s[14:15] nt
	s_add_u32 s14, s14, 0x4000
	s_addc_u32 s15, s15, 0
	global_load_dword v114, v3, s[14:15] nt
	s_add_u32 s14, s14, 0x4000
	s_addc_u32 s15, s15, 0
	global_load_dword v115, v3, s[14:15] nt
	s_add_u32 s14, s14, 0x4000
	s_addc_u32 s15, s15, 0
	global_load_dword v116, v3, s[14:15] nt
	s_add_u32 s14, s14, 0x4000
	s_addc_u32 s15, s15, 0
	global_load_dword v117, v3, s[14:15] nt
	s_add_u32 s14, s14, 0x4000
	s_addc_u32 s15, s15, 0
	global_load_dword v118, v3, s[14:15] nt
	s_add_u32 s14, s14, 0x4000
	s_addc_u32 s15, s15, 0
	global_load_dword v119, v3, s[14:15] nt
	s_lshr_b32 s24, s12, 2
	s_mul_i32 s24, s24, 0x10
	s_add_u32 s24, s24, s11
	s_lshl_b32 s24, s24, 14
	s_and_b32 s25, s12, 3
	s_lshl_b32 s25, s25, 12
	s_add_u32 s24, s24, s25
	s_add_u32 s24, s6, s24
	s_addc_u32 s25, s7, 0
	s_waitcnt vmcnt(32)
	ds_write_b32 v4, v16
	ds_write_b32 v4, v17 offset:264
	ds_write_b32 v4, v18 offset:528
	ds_write_b32 v4, v19 offset:792
	ds_write_b32 v4, v20 offset:1056
	ds_write_b32 v4, v21 offset:1320
	ds_write_b32 v4, v22 offset:1584
	ds_write_b32 v4, v23 offset:1848
	ds_write_b32 v4, v24 offset:2112
	ds_write_b32 v4, v25 offset:2376
	ds_write_b32 v4, v26 offset:2640
	ds_write_b32 v4, v27 offset:2904
	ds_write_b32 v4, v28 offset:3168
	ds_write_b32 v4, v29 offset:3432
	ds_write_b32 v4, v30 offset:3696
	ds_write_b32 v4, v31 offset:3960
	ds_write_b32 v4, v32 offset:4224
	ds_write_b32 v4, v33 offset:4488
	ds_write_b32 v4, v34 offset:4752
	ds_write_b32 v4, v35 offset:5016
	ds_write_b32 v4, v36 offset:5280
	ds_write_b32 v4, v37 offset:5544
	ds_write_b32 v4, v38 offset:5808
	ds_write_b32 v4, v39 offset:6072
	ds_write_b32 v4, v40 offset:6336
	ds_write_b32 v4, v41 offset:6600
	ds_write_b32 v4, v42 offset:6864
	ds_write_b32 v4, v43 offset:7128
	ds_write_b32 v4, v44 offset:7392
	ds_write_b32 v4, v45 offset:7656
	ds_write_b32 v4, v46 offset:7920
	ds_write_b32 v4, v47 offset:8184
	s_waitcnt lgkmcnt(0)
	ds_read_b32 v48, v7
	ds_read_b32 v49, v7 offset:132
	ds_read_b32 v50, v7 offset:264
	ds_read_b32 v51, v7 offset:396
	ds_read_b32 v52, v7 offset:528
	ds_read_b32 v53, v7 offset:660
	ds_read_b32 v54, v7 offset:792
	ds_read_b32 v55, v7 offset:924
	ds_read_b32 v56, v7 offset:32
	ds_read_b32 v57, v7 offset:164
	ds_read_b32 v58, v7 offset:296
	ds_read_b32 v59, v7 offset:428
	ds_read_b32 v60, v7 offset:560
	ds_read_b32 v61, v7 offset:692
	ds_read_b32 v62, v7 offset:824
	ds_read_b32 v63, v7 offset:956
	ds_read_b32 v64, v7 offset:64
	ds_read_b32 v65, v7 offset:196
	ds_read_b32 v66, v7 offset:328
	ds_read_b32 v67, v7 offset:460
	ds_read_b32 v68, v7 offset:592
	ds_read_b32 v69, v7 offset:724
	ds_read_b32 v70, v7 offset:856
	ds_read_b32 v71, v7 offset:988
	ds_read_b32 v72, v7 offset:96
	ds_read_b32 v73, v7 offset:228
	ds_read_b32 v74, v7 offset:360
	ds_read_b32 v75, v7 offset:492
	ds_read_b32 v76, v7 offset:624
	ds_read_b32 v77, v7 offset:756
	ds_read_b32 v78, v7 offset:888
	ds_read_b32 v79, v7 offset:1020
	s_waitcnt lgkmcnt(0)
	v_cvt_pk_bf16_f32 v48, v48, v49
	v_cvt_pk_bf16_f32 v49, v50, v51
	v_cvt_pk_bf16_f32 v50, v52, v53
	v_cvt_pk_bf16_f32 v51, v54, v55
	global_store_dwordx4 v10, v[48:51], s[16:17]
	v_cvt_pk_bf16_f32 v56, v56, v57
	v_cvt_pk_bf16_f32 v57, v58, v59
	v_cvt_pk_bf16_f32 v58, v60, v61
	v_cvt_pk_bf16_f32 v59, v62, v63
	global_store_dwordx4 v10, v[56:59], s[16:17] offset:256
	v_cvt_pk_bf16_f32 v64, v64, v65
	v_cvt_pk_bf16_f32 v65, v66, v67
	v_cvt_pk_bf16_f32 v66, v68, v69
	v_cvt_pk_bf16_f32 v67, v70, v71
	global_store_dwordx4 v11, v[64:67], s[16:17] offset:512
	v_cvt_pk_bf16_f32 v72, v72, v73
	v_cvt_pk_bf16_f32 v73, v74, v75
	v_cvt_pk_bf16_f32 v74, v76, v77
	v_cvt_pk_bf16_f32 v75, v78, v79
	global_store_dwordx4 v11, v[72:75], s[16:17] offset:768
	s_add_u32 s9, s9, s19
	s_cmpk_ge_u32 s9, 0x400
	s_cbranch_scc1 .Ltc3a_lastB
; #define LAS __attribute__((address_space(3)))
; __device__ __forceinline__ void tr_load(const float* W, int N, int item, int lane, float (&wv)[32]) {
;     const int nblk = N / 32, kb = item / nblk, nb = item % nblk, k0 = 64 * kb, n0 = 32 * nb;
; #pragma unroll
;     for (int i = 0; i < 32; ++i) { const int kk = 2 * i + (lane >> 5); wv[i] = __builtin_nontemporal_load(W + (size_t)(k0 + kk) * N + n0 + (lane & 31)); }
; }
; template <int MAP, bool HASG, bool PERMW>
; __device__ __forceinline__ void tr_store(int K, int N, bf16_t* WT, LAS float* scr, int item, int lane, const float* gk) {
;     const int nblk = N / 32, kb = item / nblk, nb = item % nblk, k0 = 64 * kb, n0 = 32 * nb;
;     asm volatile("s_waitcnt lgkmcnt(0)" ::: "memory");
;     const int c = lane & 7;
;     f32x4 g0 = {1.f, 1.f, 1.f, 1.f}, g1 = {1.f, 1.f, 1.f, 1.f};
;     if (HASG) { g0 = *(const f32x4*)(gk + k0 + 8 * c); g1 = *(const f32x4*)(gk + k0 + 8 * c + 4); }
; #pragma unroll
;     for (int j = 0; j < 4; ++j) { const int n = (lane >> 3) + 8 * j; const LAS float* s = scr + (8 * c) * 33 + n;
;         u32x4 o; o.x = pk2(s[0 * 33] * g0[0], s[1 * 33] * g0[1]); o.y = pk2(s[2 * 33] * g0[2], s[3 * 33] * g0[3]); o.z = pk2(s[4 * 33] * g1[0], s[5 * 33] * g1[1]); o.w = pk2(s[6 * 33] * g1[2], s[7 * 33] * g1[3]);
;         const int wr_ = rowmap<MAP>(n0 + n), slot_ = PERMW ? ((wr_ & ~31) + invperm32(wr_ & 31)) : wr_;
;         *(u32x4*)((char*)WT + tiled_off(slot_, k0 + 8 * c, K / 64)) = o; }
;     asm volatile("s_waitcnt lgkmcnt(0)" ::: "memory");
; }
; template <int MAP, bool HASG = false, bool PERMW = false>
; __device__ __forceinline__ void transpose_mat(const float* W, int K, int N, bf16_t* WT, LAS float* scr, int gw, int ngw, int lane, const float* gk = nullptr) {
;     ...
;     for (;;) {
;         __builtin_amdgcn_sched_barrier(0);
; #pragma unroll
;         for (int i = 0; i < 32; ++i) { const int kk = 2 * i + (lane >> 5); scr[kk * 33 + (lane & 31)] = wv[i]; }
;         __builtin_amdgcn_sched_barrier(0);
;         const int nx = it + ngw;
;         if (nx < nitems) tr_load(W, N, nx, lane, wv);
;         __builtin_amdgcn_sched_barrier(0);
;         tr_store<MAP, HASG, PERMW>(K, N, WT, scr, it, lane, gk);
;         if (nx >= nitems) break;
;         it = nx;
;     }
	s_lshr_b32 s11, s9, 6
	s_and_b32 s12, s9, 63
	s_lshl_b32 s13, s11, 19
	s_lshl_b32 s14, s12, 7
	s_add_u32 s13, s13, s14
	s_add_u32 s14, s4, s13
	s_addc_u32 s15, s5, 0
	global_load_dword v16, v3, s[14:15] nt
	s_add_u32 s14, s14, 0x4000
	s_addc_u32 s15, s15, 0
	global_load_dword v17, v3, s[14:15] nt
	s_add_u32 s14, s14, 0x4000
	s_addc_u32 s15, s15, 0
	global_load_dword v18, v3, s[14:15] nt
	s_add_u32 s14, s14, 0x4000
	s_addc_u32 s15, s15, 0
	global_load_dword v19, v3, s[14:15] nt
	s_add_u32 s14, s14, 0x4000
	s_addc_u32 s15, s15, 0
	global_load_dword v20, v3, s[14:15] nt
	s_add_u32 s14, s14, 0x4000
	s_addc_u32 s15, s15, 0
	global_load_dword v21, v3, s[14:15] nt
	s_add_u32 s14, s14, 0x4000
	s_addc_u32 s15, s15, 0
	global_load_dword v22, v3, s[14:15] nt
	s_add_u32 s14, s14, 0x4000
	s_addc_u32 s15, s15, 0
	global_load_dword v23, v3, s[14:15] nt
	s_add_u32 s14, s14, 0x4000
	s_addc_u32 s15, s15, 0
	global_load_dword v24, v3, s[14:15] nt
	s_add_u32 s14, s14, 0x4000
	s_addc_u32 s15, s15, 0
	global_load_dword v25, v3, s[14:15] nt
	s_add_u32 s14, s14, 0x4000
	s_addc_u32 s15, s15, 0
	global_load_dword v26, v3, s[14:15] nt
	s_add_u32 s14, s14, 0x4000
	s_addc_u32 s15, s15, 0
	global_load_dword v27, v3, s[14:15] nt
	s_add_u32 s14, s14, 0x4000
	s_addc_u32 s15, s15, 0
	global_load_dword v28, v3, s[14:15] nt
	s_add_u32 s14, s14, 0x4000
	s_addc_u32 s15, s15, 0
	global_load_dword v29, v3, s[14:15] nt
	s_add_u32 s14, s14, 0x4000
	s_addc_u32 s15, s15, 0
	global_load_dword v30, v3, s[14:15] nt
	s_add_u32 s14, s14, 0x4000
	s_addc_u32 s15, s15, 0
	global_load_dword v31, v3, s[14:15] nt
	s_add_u32 s14, s14, 0x4000
	s_addc_u32 s15, s15, 0
	global_load_dword v32, v3, s[14:15] nt
	s_add_u32 s14, s14, 0x4000
	s_addc_u32 s15, s15, 0
	global_load_dword v33, v3, s[14:15] nt
	s_add_u32 s14, s14, 0x4000
	s_addc_u32 s15, s15, 0
	global_load_dword v34, v3, s[14:15] nt
	s_add_u32 s14, s14, 0x4000
	s_addc_u32 s15, s15, 0
	global_load_dword v35, v3, s[14:15] nt
	s_add_u32 s14, s14, 0x4000
	s_addc_u32 s15, s15, 0
	global_load_dword v36, v3, s[14:15] nt
	s_add_u32 s14, s14, 0x4000
	s_addc_u32 s15, s15, 0
	global_load_dword v37, v3, s[14:15] nt
	s_add_u32 s14, s14, 0x4000
	s_addc_u32 s15, s15, 0
	global_load_dword v38, v3, s[14:15] nt
	s_add_u32 s14, s14, 0x4000
	s_addc_u32 s15, s15, 0
	global_load_dword v39, v3, s[14:15] nt
	s_add_u32 s14, s14, 0x4000
	s_addc_u32 s15, s15, 0
	global_load_dword v40, v3, s[14:15] nt
	s_add_u32 s14, s14, 0x4000
	s_addc_u32 s15, s15, 0
	global_load_dword v41, v3, s[14:15] nt
	s_add_u32 s14, s14, 0x4000
	s_addc_u32 s15, s15, 0
	global_load_dword v42, v3, s[14:15] nt
	s_add_u32 s14, s14, 0x4000
	s_addc_u32 s15, s15, 0
	global_load_dword v43, v3, s[14:15] nt
	s_add_u32 s14, s14, 0x4000
	s_addc_u32 s15, s15, 0
	global_load_dword v44, v3, s[14:15] nt
	s_add_u32 s14, s14, 0x4000
	s_addc_u32 s15, s15, 0
	global_load_dword v45, v3, s[14:15] nt
	s_add_u32 s14, s14, 0x4000
	s_addc_u32 s15, s15, 0
	global_load_dword v46, v3, s[14:15] nt
	s_add_u32 s14, s14, 0x4000
	s_addc_u32 s15, s15, 0
	global_load_dword v47, v3, s[14:15] nt
	s_lshr_b32 s16, s12, 2
	s_mul_i32 s16, s16, 0x10
	s_add_u32 s16, s16, s11
	s_lshl_b32 s16, s16, 14
	s_and_b32 s17, s12, 3
	s_lshl_b32 s17, s17, 12
	s_add_u32 s16, s16, s17
	s_add_u32 s16, s6, s16
	s_addc_u32 s17, s7, 0
	s_waitcnt vmcnt(32)
	ds_write_b32 v4, v88
	ds_write_b32 v4, v89 offset:264
	ds_write_b32 v4, v90 offset:528
	ds_write_b32 v4, v91 offset:792
	ds_write_b32 v4, v92 offset:1056
	ds_write_b32 v4, v93 offset:1320
	ds_write_b32 v4, v94 offset:1584
	ds_write_b32 v4, v95 offset:1848
	ds_write_b32 v4, v96 offset:2112
	ds_write_b32 v4, v97 offset:2376
	ds_write_b32 v4, v98 offset:2640
	ds_write_b32 v4, v99 offset:2904
	ds_write_b32 v4, v100 offset:3168
	ds_write_b32 v4, v101 offset:3432
	ds_write_b32 v4, v102 offset:3696
	ds_write_b32 v4, v103 offset:3960
	ds_write_b32 v4, v104 offset:4224
	ds_write_b32 v4, v105 offset:4488
	ds_write_b32 v4, v106 offset:4752
	ds_write_b32 v4, v107 offset:5016
	ds_write_b32 v4, v108 offset:5280
	ds_write_b32 v4, v109 offset:5544
	ds_write_b32 v4, v110 offset:5808
	ds_write_b32 v4, v111 offset:6072
	ds_write_b32 v4, v112 offset:6336
	ds_write_b32 v4, v113 offset:6600
	ds_write_b32 v4, v114 offset:6864
	ds_write_b32 v4, v115 offset:7128
	ds_write_b32 v4, v116 offset:7392
	ds_write_b32 v4, v117 offset:7656
	ds_write_b32 v4, v118 offset:7920
	ds_write_b32 v4, v119 offset:8184
	s_waitcnt lgkmcnt(0)
	ds_read_b32 v48, v7
	ds_read_b32 v49, v7 offset:132
	ds_read_b32 v50, v7 offset:264
	ds_read_b32 v51, v7 offset:396
	ds_read_b32 v52, v7 offset:528
	ds_read_b32 v53, v7 offset:660
	ds_read_b32 v54, v7 offset:792
	ds_read_b32 v55, v7 offset:924
	ds_read_b32 v56, v7 offset:32
	ds_read_b32 v57, v7 offset:164
	ds_read_b32 v58, v7 offset:296
	ds_read_b32 v59, v7 offset:428
	ds_read_b32 v60, v7 offset:560
	ds_read_b32 v61, v7 offset:692
	ds_read_b32 v62, v7 offset:824
	ds_read_b32 v63, v7 offset:956
	ds_read_b32 v64, v7 offset:64
	ds_read_b32 v65, v7 offset:196
	ds_read_b32 v66, v7 offset:328
	ds_read_b32 v67, v7 offset:460
	ds_read_b32 v68, v7 offset:592
	ds_read_b32 v69, v7 offset:724
	ds_read_b32 v70, v7 offset:856
	ds_read_b32 v71, v7 offset:988
	ds_read_b32 v72, v7 offset:96
	ds_read_b32 v73, v7 offset:228
	ds_read_b32 v74, v7 offset:360
	ds_read_b32 v75, v7 offset:492
	ds_read_b32 v76, v7 offset:624
	ds_read_b32 v77, v7 offset:756
	ds_read_b32 v78, v7 offset:888
	ds_read_b32 v79, v7 offset:1020
	s_waitcnt lgkmcnt(0)
	v_cvt_pk_bf16_f32 v48, v48, v49
	v_cvt_pk_bf16_f32 v49, v50, v51
	v_cvt_pk_bf16_f32 v50, v52, v53
	v_cvt_pk_bf16_f32 v51, v54, v55
	global_store_dwordx4 v10, v[48:51], s[24:25]
	v_cvt_pk_bf16_f32 v56, v56, v57
	v_cvt_pk_bf16_f32 v57, v58, v59
	v_cvt_pk_bf16_f32 v58, v60, v61
	v_cvt_pk_bf16_f32 v59, v62, v63
	global_store_dwordx4 v10, v[56:59], s[24:25] offset:256
	v_cvt_pk_bf16_f32 v64, v64, v65
	v_cvt_pk_bf16_f32 v65, v66, v67
	v_cvt_pk_bf16_f32 v66, v68, v69
	v_cvt_pk_bf16_f32 v67, v70, v71
	global_store_dwordx4 v11, v[64:67], s[24:25] offset:512
	v_cvt_pk_bf16_f32 v72, v72, v73
	v_cvt_pk_bf16_f32 v73, v74, v75
	v_cvt_pk_bf16_f32 v74, v76, v77
	v_cvt_pk_bf16_f32 v75, v78, v79
	global_store_dwordx4 v11, v[72:75], s[24:25] offset:768
	s_branch .Ltc3a_loop

; #define LAS __attribute__((address_space(3)))
; __device__ __forceinline__ void tr_load(const float* W, int N, int item, int lane, float (&wv)[32]) {
;     const int nblk = N / 32, kb = item / nblk, nb = item % nblk, k0 = 64 * kb, n0 = 32 * nb;
; #pragma unroll
;     for (int i = 0; i < 32; ++i) { const int kk = 2 * i + (lane >> 5); wv[i] = __builtin_nontemporal_load(W + (size_t)(k0 + kk) * N + n0 + (lane & 31)); }
; }
; template <int MAP, bool HASG, bool PERMW>
; __device__ __forceinline__ void tr_store(int K, int N, bf16_t* WT, LAS float* scr, int item, int lane, const float* gk) {
;     const int nblk = N / 32, kb = item / nblk, nb = item % nblk, k0 = 64 * kb, n0 = 32 * nb;
;     asm volatile("s_waitcnt lgkmcnt(0)" ::: "memory");
;     const int c = lane & 7;
;     f32x4 g0 = {1.f, 1.f, 1.f, 1.f}, g1 = {1.f, 1.f, 1.f, 1.f};
;     if (HASG) { g0 = *(const f32x4*)(gk + k0 + 8 * c); g1 = *(const f32x4*)(gk + k0 + 8 * c + 4); }
; #pragma unroll
;     for (int j = 0; j < 4; ++j) { const int n = (lane >> 3) + 8 * j; const LAS float* s = scr + (8 * c) * 33 + n;
;         u32x4 o; o.x = pk2(s[0 * 33] * g0[0], s[1 * 33] * g0[1]); o.y = pk2(s[2 * 33] * g0[2], s[3 * 33] * g0[3]); o.z = pk2(s[4 * 33] * g1[0], s[5 * 33] * g1[1]); o.w = pk2(s[6 * 33] * g1[2], s[7 * 33] * g1[3]);
;         const int wr_ = rowmap<MAP>(n0 + n), slot_ = PERMW ? ((wr_ & ~31) + invperm32(wr_ & 31)) : wr_;
;         *(u32x4*)((char*)WT + tiled_off(slot_, k0 + 8 * c, K / 64)) = o; }
;     asm volatile("s_waitcnt lgkmcnt(0)" ::: "memory");
; }
; template <int MAP, bool HASG = false, bool PERMW = false>
; __device__ __forceinline__ void transpose_mat(const float* W, int K, int N, bf16_t* WT, LAS float* scr, int gw, int ngw, int lane, const float* gk = nullptr) {
;     ...
;     for (;;) {
;         __builtin_amdgcn_sched_barrier(0);
; #pragma unroll
;         for (int i = 0; i < 32; ++i) { const int kk = 2 * i + (lane >> 5); scr[kk * 33 + (lane & 31)] = wv[i]; }
;         __builtin_amdgcn_sched_barrier(0);
;         const int nx = it + ngw;
;         if (nx < nitems) tr_load(W, N, nx, lane, wv);
;         __builtin_amdgcn_sched_barrier(0);
;         tr_store<MAP, HASG, PERMW>(K, N, WT, scr, it, lane, gk);
;         if (nx >= nitems) break;
;         it = nx;
;     }
.Ltc3b_loop:
	s_add_u32 s9, s9, s19
	s_cmpk_ge_u32 s9, 0x800
	s_cbranch_scc1 .Ltc3b_lastA
	s_lshr_b32 s11, s9, 6
	s_and_b32 s12, s9, 63
	s_lshl_b32 s13, s11, 19
	s_lshl_b32 s14, s12, 7
	s_add_u32 s13, s13, s14
	s_add_u32 s14, s4, s13
	s_addc_u32 s15, s5, 0
	global_load_dword v88, v3, s[14:15] nt
	s_add_u32 s14, s14, 0x4000
	s_addc_u32 s15, s15, 0
	global_load_dword v89, v3, s[14:15] nt
	s_add_u32 s14, s14, 0x4000
	s_addc_u32 s15, s15, 0
	global_load_dword v90, v3, s[14:15] nt
	s_add_u32 s14, s14, 0x4000
	s_addc_u32 s15, s15, 0
	global_load_dword v91, v3, s[14:15] nt
	s_add_u32 s14, s14, 0x4000
	s_addc_u32 s15, s15, 0
	global_load_dword v92, v3, s[14:15] nt
	s_add_u32 s14, s14, 0x4000
	s_addc_u32 s15, s15, 0
	global_load_dword v93, v3, s[14:15] nt
	s_add_u32 s14, s14, 0x4000
	s_addc_u32 s15, s15, 0
	global_load_dword v94, v3, s[14:15] nt
	s_add_u32 s14, s14, 0x4000
	s_addc_u32 s15, s15, 0
	global_load_dword v95, v3, s[14:15] nt
	s_add_u32 s14, s14, 0x4000
	s_addc_u32 s15, s15, 0
	global_load_dword v96, v3, s[14:15] nt
	s_add_u32 s14, s14, 0x4000
	s_addc_u32 s15, s15, 0
	global_load_dword v97, v3, s[14:15] nt
	s_add_u32 s14, s14, 0x4000
	s_addc_u32 s15, s15, 0
	global_load_dword v98, v3, s[14:15] nt
	s_add_u32 s14, s14, 0x4000
	s_addc_u32 s15, s15, 0
	global_load_dword v99, v3, s[14:15] nt
	s_add_u32 s14, s14, 0x4000
	s_addc_u32 s15, s15, 0
	global_load_dword v100, v3, s[14:15] nt
	s_add_u32 s14, s14, 0x4000
	s_addc_u32 s15, s15, 0
	global_load_dword v101, v3, s[14:15] nt
	s_add_u32 s14, s14, 0x4000
	s_addc_u32 s15, s15, 0
	global_load_dword v102, v3, s[14:15] nt
	s_add_u32 s14, s14, 0x4000
	s_addc_u32 s15, s15, 0
	global_load_dword v103, v3, s[14:15] nt
	s_add_u32 s14, s14, 0x4000
	s_addc_u32 s15, s15, 0
	global_load_dword v104, v3, s[14:15] nt
	s_add_u32 s14, s14, 0x4000
	s_addc_u32 s15, s15, 0
	global_load_dword v105, v3, s[14:15] nt
	s_add_u32 s14, s14, 0x4000
	s_addc_u32 s15, s15, 0
	global_load_dword v106, v3, s[14:15] nt
	s_add_u32 s14, s14, 0x4000
	s_addc_u32 s15, s15, 0
	global_load_dword v107, v3, s[14:15] nt
	s_add_u32 s14, s14, 0x4000
	s_addc_u32 s15, s15, 0
	global_load_dword v108, v3, s[14:15] nt
	s_add_u32 s14, s14, 0x4000
	s_addc_u32 s15, s15, 0
	global_load_dword v109, v3, s[14:15] nt
	s_add_u32 s14, s14, 0x4000
	s_addc_u32 s15, s15, 0
	global_load_dword v110, v3, s[14:15] nt
	s_add_u32 s14, s14, 0x4000
	s_addc_u32 s15, s15, 0
	global_load_dword v111, v3, s[14:15] nt
	s_add_u32 s14, s14, 0x4000
	s_addc_u32 s15, s15, 0
	global_load_dword v112, v3, s[14:15] nt
	s_add_u32 s14, s14, 0x4000
	s_addc_u32 s15, s15, 0
	global_load_dword v113, v3, s[14:15] nt
	s_add_u32 s14, s14, 0x4000
	s_addc_u32 s15, s15, 0
	global_load_dword v114, v3, s[14:15] nt
	s_add_u32 s14, s14, 0x4000
	s_addc_u32 s15, s15, 0
	global_load_dword v115, v3, s[14:15] nt
	s_add_u32 s14, s14, 0x4000
	s_addc_u32 s15, s15, 0
	global_load_dword v116, v3, s[14:15] nt
	s_add_u32 s14, s14, 0x4000
	s_addc_u32 s15, s15, 0
	global_load_dword v117, v3, s[14:15] nt
	s_add_u32 s14, s14, 0x4000
	s_addc_u32 s15, s15, 0
	global_load_dword v118, v3, s[14:15] nt
	s_add_u32 s14, s14, 0x4000
	s_addc_u32 s15, s15, 0
	global_load_dword v119, v3, s[14:15] nt
	s_lshr_b32 s24, s12, 2
	s_mul_i32 s24, s24, 0x20
	s_add_u32 s24, s24, s11
	s_lshl_b32 s24, s24, 14
	s_and_b32 s25, s12, 3
	s_lshl_b32 s25, s25, 12
	s_add_u32 s24, s24, s25
	s_add_u32 s24, s6, s24
	s_addc_u32 s25, s7, 0
	s_waitcnt vmcnt(32)
	ds_write_b32 v4, v16
	ds_write_b32 v4, v17 offset:264
	ds_write_b32 v4, v18 offset:528
	ds_write_b32 v4, v19 offset:792
	ds_write_b32 v4, v20 offset:1056
	ds_write_b32 v4, v21 offset:1320
	ds_write_b32 v4, v22 offset:1584
	ds_write_b32 v4, v23 offset:1848
	ds_write_b32 v4, v24 offset:2112
	ds_write_b32 v4, v25 offset:2376
	ds_write_b32 v4, v26 offset:2640
	ds_write_b32 v4, v27 offset:2904
	ds_write_b32 v4, v28 offset:3168
	ds_write_b32 v4, v29 offset:3432
	ds_write_b32 v4, v30 offset:3696
	ds_write_b32 v4, v31 offset:3960
	ds_write_b32 v4, v32 offset:4224
	ds_write_b32 v4, v33 offset:4488
	ds_write_b32 v4, v34 offset:4752
	ds_write_b32 v4, v35 offset:5016
	ds_write_b32 v4, v36 offset:5280
	ds_write_b32 v4, v37 offset:5544
	ds_write_b32 v4, v38 offset:5808
	ds_write_b32 v4, v39 offset:6072
	ds_write_b32 v4, v40 offset:6336
	ds_write_b32 v4, v41 offset:6600
	ds_write_b32 v4, v42 offset:6864
	ds_write_b32 v4, v43 offset:7128
	ds_write_b32 v4, v44 offset:7392
	ds_write_b32 v4, v45 offset:7656
	ds_write_b32 v4, v46 offset:7920
	ds_write_b32 v4, v47 offset:8184
	s_waitcnt lgkmcnt(0)
	ds_read_b32 v48, v7
	ds_read_b32 v49, v7 offset:132
	ds_read_b32 v50, v7 offset:264
	ds_read_b32 v51, v7 offset:396
	ds_read_b32 v52, v7 offset:528
	ds_read_b32 v53, v7 offset:660
	ds_read_b32 v54, v7 offset:792
	ds_read_b32 v55, v7 offset:924
	ds_read_b32 v56, v7 offset:32
	ds_read_b32 v57, v7 offset:164
	ds_read_b32 v58, v7 offset:296
	ds_read_b32 v59, v7 offset:428
	ds_read_b32 v60, v7 offset:560
	ds_read_b32 v61, v7 offset:692
	ds_read_b32 v62, v7 offset:824
	ds_read_b32 v63, v7 offset:956
	ds_read_b32 v64, v7 offset:64
	ds_read_b32 v65, v7 offset:196
	ds_read_b32 v66, v7 offset:328
	ds_read_b32 v67, v7 offset:460
	ds_read_b32 v68, v7 offset:592
	ds_read_b32 v69, v7 offset:724
	ds_read_b32 v70, v7 offset:856
	ds_read_b32 v71, v7 offset:988
	ds_read_b32 v72, v7 offset:96
	ds_read_b32 v73, v7 offset:228
	ds_read_b32 v74, v7 offset:360
	ds_read_b32 v75, v7 offset:492
	ds_read_b32 v76, v7 offset:624
	ds_read_b32 v77, v7 offset:756
	ds_read_b32 v78, v7 offset:888
	ds_read_b32 v79, v7 offset:1020
	s_waitcnt lgkmcnt(0)
	v_cvt_pk_bf16_f32 v48, v48, v49
	v_cvt_pk_bf16_f32 v49, v50, v51
	v_cvt_pk_bf16_f32 v50, v52, v53
	v_cvt_pk_bf16_f32 v51, v54, v55
	global_store_dwordx4 v10, v[48:51], s[16:17]
	v_cvt_pk_bf16_f32 v56, v56, v57
	v_cvt_pk_bf16_f32 v57, v58, v59
	v_cvt_pk_bf16_f32 v58, v60, v61
	v_cvt_pk_bf16_f32 v59, v62, v63
	global_store_dwordx4 v10, v[56:59], s[16:17] offset:256
	v_cvt_pk_bf16_f32 v64, v64, v65
	v_cvt_pk_bf16_f32 v65, v66, v67
	v_cvt_pk_bf16_f32 v66, v68, v69
	v_cvt_pk_bf16_f32 v67, v70, v71
	global_store_dwordx4 v11, v[64:67], s[16:17] offset:512
	v_cvt_pk_bf16_f32 v72, v72, v73
	v_cvt_pk_bf16_f32 v73, v74, v75
	v_cvt_pk_bf16_f32 v74, v76, v77
	v_cvt_pk_bf16_f32 v75, v78, v79
	global_store_dwordx4 v11, v[72:75], s[16:17] offset:768
	s_add_u32 s9, s9, s19
	s_cmpk_ge_u32 s9, 0x800
	s_cbranch_scc1 .Ltc3b_lastB
; #define LAS __attribute__((address_space(3)))
; __device__ __forceinline__ void tr_load(const float* W, int N, int item, int lane, float (&wv)[32]) {
;     const int nblk = N / 32, kb = item / nblk, nb = item % nblk, k0 = 64 * kb, n0 = 32 * nb;
; #pragma unroll
;     for (int i = 0; i < 32; ++i) { const int kk = 2 * i + (lane >> 5); wv[i] = __builtin_nontemporal_load(W + (size_t)(k0 + kk) * N + n0 + (lane & 31)); }
; }
; template <int MAP, bool HASG, bool PERMW>
; __device__ __forceinline__ void tr_store(int K, int N, bf16_t* WT, LAS float* scr, int item, int lane, const float* gk) {
;     const int nblk = N / 32, kb = item / nblk, nb = item % nblk, k0 = 64 * kb, n0 = 32 * nb;
;     asm volatile("s_waitcnt lgkmcnt(0)" ::: "memory");
;     const int c = lane & 7;
;     f32x4 g0 = {1.f, 1.f, 1.f, 1.f}, g1 = {1.f, 1.f, 1.f, 1.f};
;     if (HASG) { g0 = *(const f32x4*)(gk + k0 + 8 * c); g1 = *(const f32x4*)(gk + k0 + 8 * c + 4); }
; #pragma unroll
;     for (int j = 0; j < 4; ++j) { const int n = (lane >> 3) + 8 * j; const LAS float* s = scr + (8 * c) * 33 + n;
;         u32x4 o; o.x = pk2(s[0 * 33] * g0[0], s[1 * 33] * g0[1]); o.y = pk2(s[2 * 33] * g0[2], s[3 * 33] * g0[3]); o.z = pk2(s[4 * 33] * g1[0], s[5 * 33] * g1[1]); o.w = pk2(s[6 * 33] * g1[2], s[7 * 33] * g1[3]);
;         const int wr_ = rowmap<MAP>(n0 + n), slot_ = PERMW ? ((wr_ & ~31) + invperm32(wr_ & 31)) : wr_;
;         *(u32x4*)((char*)WT + tiled_off(slot_, k0 + 8 * c, K / 64)) = o; }
;     asm volatile("s_waitcnt lgkmcnt(0)" ::: "memory");
; }
; template <int MAP, bool HASG = false, bool PERMW = false>
; __device__ __forceinline__ void transpose_mat(const float* W, int K, int N, bf16_t* WT, LAS float* scr, int gw, int ngw, int lane, const float* gk = nullptr) {
;     ...
;     for (;;) {
;         __builtin_amdgcn_sched_barrier(0);
; #pragma unroll
;         for (int i = 0; i < 32; ++i) { const int kk = 2 * i + (lane >> 5); scr[kk * 33 + (lane & 31)] = wv[i]; }
;         __builtin_amdgcn_sched_barrier(0);
;         const int nx = it + ngw;
;         if (nx < nitems) tr_load(W, N, nx, lane, wv);
;         __builtin_amdgcn_sched_barrier(0);
;         tr_store<MAP, HASG, PERMW>(K, N, WT, scr, it, lane, gk);
;         if (nx >= nitems) break;
;         it = nx;
;     }
	s_lshr_b32 s11, s9, 6
	s_and_b32 s12, s9, 63
	s_lshl_b32 s13, s11, 19
	s_lshl_b32 s14, s12, 7
	s_add_u32 s13, s13, s14
	s_add_u32 s14, s4, s13
	s_addc_u32 s15, s5, 0
	global_load_dword v16, v3, s[14:15] nt
	s_add_u32 s14, s14, 0x4000
	s_addc_u32 s15, s15, 0
	global_load_dword v17, v3, s[14:15] nt
	s_add_u32 s14, s14, 0x4000
	s_addc_u32 s15, s15, 0
	global_load_dword v18, v3, s[14:15] nt
	s_add_u32 s14, s14, 0x4000
	s_addc_u32 s15, s15, 0
	global_load_dword v19, v3, s[14:15] nt
	s_add_u32 s14, s14, 0x4000
	s_addc_u32 s15, s15, 0
	global_load_dword v20, v3, s[14:15] nt
	s_add_u32 s14, s14, 0x4000
	s_addc_u32 s15, s15, 0
	global_load_dword v21, v3, s[14:15] nt
	s_add_u32 s14, s14, 0x4000
	s_addc_u32 s15, s15, 0
	global_load_dword v22, v3, s[14:15] nt
	s_add_u32 s14, s14, 0x4000
	s_addc_u32 s15, s15, 0
	global_load_dword v23, v3, s[14:15] nt
	s_add_u32 s14, s14, 0x4000
	s_addc_u32 s15, s15, 0
	global_load_dword v24, v3, s[14:15] nt
	s_add_u32 s14, s14, 0x4000
	s_addc_u32 s15, s15, 0
	global_load_dword v25, v3, s[14:15] nt
	s_add_u32 s14, s14, 0x4000
	s_addc_u32 s15, s15, 0
	global_load_dword v26, v3, s[14:15] nt
	s_add_u32 s14, s14, 0x4000
	s_addc_u32 s15, s15, 0
	global_load_dword v27, v3, s[14:15] nt
	s_add_u32 s14, s14, 0x4000
	s_addc_u32 s15, s15, 0
	global_load_dword v28, v3, s[14:15] nt
	s_add_u32 s14, s14, 0x4000
	s_addc_u32 s15, s15, 0
	global_load_dword v29, v3, s[14:15] nt
	s_add_u32 s14, s14, 0x4000
	s_addc_u32 s15, s15, 0
	global_load_dword v30, v3, s[14:15] nt
	s_add_u32 s14, s14, 0x4000
	s_addc_u32 s15, s15, 0
	global_load_dword v31, v3, s[14:15] nt
	s_add_u32 s14, s14, 0x4000
	s_addc_u32 s15, s15, 0
	global_load_dword v32, v3, s[14:15] nt
	s_add_u32 s14, s14, 0x4000
	s_addc_u32 s15, s15, 0
	global_load_dword v33, v3, s[14:15] nt
	s_add_u32 s14, s14, 0x4000
	s_addc_u32 s15, s15, 0
	global_load_dword v34, v3, s[14:15] nt
	s_add_u32 s14, s14, 0x4000
	s_addc_u32 s15, s15, 0
	global_load_dword v35, v3, s[14:15] nt
	s_add_u32 s14, s14, 0x4000
	s_addc_u32 s15, s15, 0
	global_load_dword v36, v3, s[14:15] nt
	s_add_u32 s14, s14, 0x4000
	s_addc_u32 s15, s15, 0
	global_load_dword v37, v3, s[14:15] nt
	s_add_u32 s14, s14, 0x4000
	s_addc_u32 s15, s15, 0
	global_load_dword v38, v3, s[14:15] nt
	s_add_u32 s14, s14, 0x4000
	s_addc_u32 s15, s15, 0
	global_load_dword v39, v3, s[14:15] nt
	s_add_u32 s14, s14, 0x4000
	s_addc_u32 s15, s15, 0
	global_load_dword v40, v3, s[14:15] nt
	s_add_u32 s14, s14, 0x4000
	s_addc_u32 s15, s15, 0
	global_load_dword v41, v3, s[14:15] nt
	s_add_u32 s14, s14, 0x4000
	s_addc_u32 s15, s15, 0
	global_load_dword v42, v3, s[14:15] nt
	s_add_u32 s14, s14, 0x4000
	s_addc_u32 s15, s15, 0
	global_load_dword v43, v3, s[14:15] nt
	s_add_u32 s14, s14, 0x4000
	s_addc_u32 s15, s15, 0
	global_load_dword v44, v3, s[14:15] nt
	s_add_u32 s14, s14, 0x4000
	s_addc_u32 s15, s15, 0
	global_load_dword v45, v3, s[14:15] nt
	s_add_u32 s14, s14, 0x4000
	s_addc_u32 s15, s15, 0
	global_load_dword v46, v3, s[14:15] nt
	s_add_u32 s14, s14, 0x4000
	s_addc_u32 s15, s15, 0
	global_load_dword v47, v3, s[14:15] nt
	s_lshr_b32 s16, s12, 2
	s_mul_i32 s16, s16, 0x20
	s_add_u32 s16, s16, s11
	s_lshl_b32 s16, s16, 14
	s_and_b32 s17, s12, 3
	s_lshl_b32 s17, s17, 12
	s_add_u32 s16, s16, s17
	s_add_u32 s16, s6, s16
	s_addc_u32 s17, s7, 0
	s_waitcnt vmcnt(32)
	ds_write_b32 v4, v88
	ds_write_b32 v4, v89 offset:264
	ds_write_b32 v4, v90 offset:528
	ds_write_b32 v4, v91 offset:792
	ds_write_b32 v4, v92 offset:1056
	ds_write_b32 v4, v93 offset:1320
	ds_write_b32 v4, v94 offset:1584
	ds_write_b32 v4, v95 offset:1848
	ds_write_b32 v4, v96 offset:2112
	ds_write_b32 v4, v97 offset:2376
	ds_write_b32 v4, v98 offset:2640
	ds_write_b32 v4, v99 offset:2904
	ds_write_b32 v4, v100 offset:3168
	ds_write_b32 v4, v101 offset:3432
	ds_write_b32 v4, v102 offset:3696
	ds_write_b32 v4, v103 offset:3960
	ds_write_b32 v4, v104 offset:4224
	ds_write_b32 v4, v105 offset:4488
	ds_write_b32 v4, v106 offset:4752
	ds_write_b32 v4, v107 offset:5016
	ds_write_b32 v4, v108 offset:5280
	ds_write_b32 v4, v109 offset:5544
	ds_write_b32 v4, v110 offset:5808
	ds_write_b32 v4, v111 offset:6072
	ds_write_b32 v4, v112 offset:6336
	ds_write_b32 v4, v113 offset:6600
	ds_write_b32 v4, v114 offset:6864
	ds_write_b32 v4, v115 offset:7128
	ds_write_b32 v4, v116 offset:7392
	ds_write_b32 v4, v117 offset:7656
	ds_write_b32 v4, v118 offset:7920
	ds_write_b32 v4, v119 offset:8184
	s_waitcnt lgkmcnt(0)
	ds_read_b32 v48, v7
	ds_read_b32 v49, v7 offset:132
	ds_read_b32 v50, v7 offset:264
	ds_read_b32 v51, v7 offset:396
	ds_read_b32 v52, v7 offset:528
	ds_read_b32 v53, v7 offset:660
	ds_read_b32 v54, v7 offset:792
	ds_read_b32 v55, v7 offset:924
	ds_read_b32 v56, v7 offset:32
	ds_read_b32 v57, v7 offset:164
	ds_read_b32 v58, v7 offset:296
	ds_read_b32 v59, v7 offset:428
	ds_read_b32 v60, v7 offset:560
	ds_read_b32 v61, v7 offset:692
	ds_read_b32 v62, v7 offset:824
	ds_read_b32 v63, v7 offset:956
	ds_read_b32 v64, v7 offset:64
	ds_read_b32 v65, v7 offset:196
	ds_read_b32 v66, v7 offset:328
	ds_read_b32 v67, v7 offset:460
	ds_read_b32 v68, v7 offset:592
	ds_read_b32 v69, v7 offset:724
	ds_read_b32 v70, v7 offset:856
	ds_read_b32 v71, v7 offset:988
	ds_read_b32 v72, v7 offset:96
	ds_read_b32 v73, v7 offset:228
	ds_read_b32 v74, v7 offset:360
	ds_read_b32 v75, v7 offset:492
	ds_read_b32 v76, v7 offset:624
	ds_read_b32 v77, v7 offset:756
	ds_read_b32 v78, v7 offset:888
	ds_read_b32 v79, v7 offset:1020
	s_waitcnt lgkmcnt(0)
	v_cvt_pk_bf16_f32 v48, v48, v49
	v_cvt_pk_bf16_f32 v49, v50, v51
	v_cvt_pk_bf16_f32 v50, v52, v53
	v_cvt_pk_bf16_f32 v51, v54, v55
	global_store_dwordx4 v10, v[48:51], s[24:25]
	v_cvt_pk_bf16_f32 v56, v56, v57
	v_cvt_pk_bf16_f32 v57, v58, v59
	v_cvt_pk_bf16_f32 v58, v60, v61
	v_cvt_pk_bf16_f32 v59, v62, v63
	global_store_dwordx4 v10, v[56:59], s[24:25] offset:256
	v_cvt_pk_bf16_f32 v64, v64, v65
	v_cvt_pk_bf16_f32 v65, v66, v67
	v_cvt_pk_bf16_f32 v66, v68, v69
	v_cvt_pk_bf16_f32 v67, v70, v71
	global_store_dwordx4 v11, v[64:67], s[24:25] offset:512
	v_cvt_pk_bf16_f32 v72, v72, v73
	v_cvt_pk_bf16_f32 v73, v74, v75
	v_cvt_pk_bf16_f32 v74, v76, v77
	v_cvt_pk_bf16_f32 v75, v78, v79
	global_store_dwordx4 v11, v[72:75], s[24:25] offset:768
	s_branch .Ltc3b_loop

; #define LAS __attribute__((address_space(3)))
; __device__ __forceinline__ void tr_load(const float* W, int N, int item, int lane, float (&wv)[32]) {
;     const int nblk = N / 32, kb = item / nblk, nb = item % nblk, k0 = 64 * kb, n0 = 32 * nb;
; #pragma unroll
;     for (int i = 0; i < 32; ++i) { const int kk = 2 * i + (lane >> 5); wv[i] = __builtin_nontemporal_load(W + (size_t)(k0 + kk) * N + n0 + (lane & 31)); }
; }
; template <int MAP, bool HASG, bool PERMW>
; __device__ __forceinline__ void tr_store(int K, int N, bf16_t* WT, LAS float* scr, int item, int lane, const float* gk) {
;     const int nblk = N / 32, kb = item / nblk, nb = item % nblk, k0 = 64 * kb, n0 = 32 * nb;
;     asm volatile("s_waitcnt lgkmcnt(0)" ::: "memory");
;     const int c = lane & 7;
;     f32x4 g0 = {1.f, 1.f, 1.f, 1.f}, g1 = {1.f, 1.f, 1.f, 1.f};
;     if (HASG) { g0 = *(const f32x4*)(gk + k0 + 8 * c); g1 = *(const f32x4*)(gk + k0 + 8 * c + 4); }
; #pragma unroll
;     for (int j = 0; j < 4; ++j) { const int n = (lane >> 3) + 8 * j; const LAS float* s = scr + (8 * c) * 33 + n;
;         u32x4 o; o.x = pk2(s[0 * 33] * g0[0], s[1 * 33] * g0[1]); o.y = pk2(s[2 * 33] * g0[2], s[3 * 33] * g0[3]); o.z = pk2(s[4 * 33] * g1[0], s[5 * 33] * g1[1]); o.w = pk2(s[6 * 33] * g1[2], s[7 * 33] * g1[3]);
;         const int wr_ = rowmap<MAP>(n0 + n), slot_ = PERMW ? ((wr_ & ~31) + invperm32(wr_ & 31)) : wr_;
;         *(u32x4*)((char*)WT + tiled_off(slot_, k0 + 8 * c, K / 64)) = o; }
;     asm volatile("s_waitcnt lgkmcnt(0)" ::: "memory");
; }
; template <int MAP, bool HASG = false, bool PERMW = false>
; __device__ __forceinline__ void transpose_mat(const float* W, int K, int N, bf16_t* WT, LAS float* scr, int gw, int ngw, int lane, const float* gk = nullptr) {
;     ...
;     for (;;) {
;         __builtin_amdgcn_sched_barrier(0);
; #pragma unroll
;         for (int i = 0; i < 32; ++i) { const int kk = 2 * i + (lane >> 5); scr[kk * 33 + (lane & 31)] = wv[i]; }
;         __builtin_amdgcn_sched_barrier(0);
;         const int nx = it + ngw;
;         if (nx < nitems) tr_load(W, N, nx, lane, wv);
;         __builtin_amdgcn_sched_barrier(0);
;         tr_store<MAP, HASG, PERMW>(K, N, WT, scr, it, lane, gk);
;         if (nx >= nitems) break;
;         it = nx;
;     }
.Ltc3c_loop:
	s_add_u32 s9, s9, s19
	s_cmpk_ge_u32 s9, 0x800
	s_cbranch_scc1 .Ltc3c_lastA
	s_lshr_b32 s11, s9, 6
	s_and_b32 s12, s9, 63
	s_lshl_b32 s13, s11, 19
	s_lshl_b32 s14, s12, 7
	s_add_u32 s13, s13, s14
	s_add_u32 s14, s4, s13
	s_addc_u32 s15, s5, 0
	global_load_dword v88, v3, s[14:15] nt
	s_add_u32 s14, s14, 0x4000
	s_addc_u32 s15, s15, 0
	global_load_dword v89, v3, s[14:15] nt
	s_add_u32 s14, s14, 0x4000
	s_addc_u32 s15, s15, 0
	global_load_dword v90, v3, s[14:15] nt
	s_add_u32 s14, s14, 0x4000
	s_addc_u32 s15, s15, 0
	global_load_dword v91, v3, s[14:15] nt
	s_add_u32 s14, s14, 0x4000
	s_addc_u32 s15, s15, 0
	global_load_dword v92, v3, s[14:15] nt
	s_add_u32 s14, s14, 0x4000
	s_addc_u32 s15, s15, 0
	global_load_dword v93, v3, s[14:15] nt
	s_add_u32 s14, s14, 0x4000
	s_addc_u32 s15, s15, 0
	global_load_dword v94, v3, s[14:15] nt
	s_add_u32 s14, s14, 0x4000
	s_addc_u32 s15, s15, 0
	global_load_dword v95, v3, s[14:15] nt
	s_add_u32 s14, s14, 0x4000
	s_addc_u32 s15, s15, 0
	global_load_dword v96, v3, s[14:15] nt
	s_add_u32 s14, s14, 0x4000
	s_addc_u32 s15, s15, 0
	global_load_dword v97, v3, s[14:15] nt
	s_add_u32 s14, s14, 0x4000
	s_addc_u32 s15, s15, 0
	global_load_dword v98, v3, s[14:15] nt
	s_add_u32 s14, s14, 0x4000
	s_addc_u32 s15, s15, 0
	global_load_dword v99, v3, s[14:15] nt
	s_add_u32 s14, s14, 0x4000
	s_addc_u32 s15, s15, 0
	global_load_dword v100, v3, s[14:15] nt
	s_add_u32 s14, s14, 0x4000
	s_addc_u32 s15, s15, 0
	global_load_dword v101, v3, s[14:15] nt
	s_add_u32 s14, s14, 0x4000
	s_addc_u32 s15, s15, 0
	global_load_dword v102, v3, s[14:15] nt
	s_add_u32 s14, s14, 0x4000
	s_addc_u32 s15, s15, 0
	global_load_dword v103, v3, s[14:15] nt
	s_add_u32 s14, s14, 0x4000
	s_addc_u32 s15, s15, 0
	global_load_dword v104, v3, s[14:15] nt
	s_add_u32 s14, s14, 0x4000
	s_addc_u32 s15, s15, 0
	global_load_dword v105, v3, s[14:15] nt
	s_add_u32 s14, s14, 0x4000
	s_addc_u32 s15, s15, 0
	global_load_dword v106, v3, s[14:15] nt
	s_add_u32 s14, s14, 0x4000
	s_addc_u32 s15, s15, 0
	global_load_dword v107, v3, s[14:15] nt
	s_add_u32 s14, s14, 0x4000
	s_addc_u32 s15, s15, 0
	global_load_dword v108, v3, s[14:15] nt
	s_add_u32 s14, s14, 0x4000
	s_addc_u32 s15, s15, 0
	global_load_dword v109, v3, s[14:15] nt
	s_add_u32 s14, s14, 0x4000
	s_addc_u32 s15, s15, 0
	global_load_dword v110, v3, s[14:15] nt
	s_add_u32 s14, s14, 0x4000
	s_addc_u32 s15, s15, 0
	global_load_dword v111, v3, s[14:15] nt
	s_add_u32 s14, s14, 0x4000
	s_addc_u32 s15, s15, 0
	global_load_dword v112, v3, s[14:15] nt
	s_add_u32 s14, s14, 0x4000
	s_addc_u32 s15, s15, 0
	global_load_dword v113, v3, s[14:15] nt
	s_add_u32 s14, s14, 0x4000
	s_addc_u32 s15, s15, 0
	global_load_dword v114, v3, s[14:15] nt
	s_add_u32 s14, s14, 0x4000
	s_addc_u32 s15, s15, 0
	global_load_dword v115, v3, s[14:15] nt
	s_add_u32 s14, s14, 0x4000
	s_addc_u32 s15, s15, 0
	global_load_dword v116, v3, s[14:15] nt
	s_add_u32 s14, s14, 0x4000
	s_addc_u32 s15, s15, 0
	global_load_dword v117, v3, s[14:15] nt
	s_add_u32 s14, s14, 0x4000
	s_addc_u32 s15, s15, 0
	global_load_dword v118, v3, s[14:15] nt
	s_add_u32 s14, s14, 0x4000
	s_addc_u32 s15, s15, 0
	global_load_dword v119, v3, s[14:15] nt
	s_lshr_b32 s24, s12, 2
	s_mul_i32 s24, s24, 0x20
	s_add_u32 s24, s24, s11
	s_lshl_b32 s24, s24, 14
	s_and_b32 s25, s12, 3
	s_lshl_b32 s25, s25, 12
	s_add_u32 s24, s24, s25
	s_add_u32 s24, s6, s24
	s_addc_u32 s25, s7, 0
	s_waitcnt vmcnt(32)
	ds_write_b32 v4, v16
	ds_write_b32 v4, v17 offset:264
	ds_write_b32 v4, v18 offset:528
	ds_write_b32 v4, v19 offset:792
	ds_write_b32 v4, v20 offset:1056
	ds_write_b32 v4, v21 offset:1320
	ds_write_b32 v4, v22 offset:1584
	ds_write_b32 v4, v23 offset:1848
	ds_write_b32 v4, v24 offset:2112
	ds_write_b32 v4, v25 offset:2376
	ds_write_b32 v4, v26 offset:2640
	ds_write_b32 v4, v27 offset:2904
	ds_write_b32 v4, v28 offset:3168
	ds_write_b32 v4, v29 offset:3432
	ds_write_b32 v4, v30 offset:3696
	ds_write_b32 v4, v31 offset:3960
	ds_write_b32 v4, v32 offset:4224
	ds_write_b32 v4, v33 offset:4488
	ds_write_b32 v4, v34 offset:4752
	ds_write_b32 v4, v35 offset:5016
	ds_write_b32 v4, v36 offset:5280
	ds_write_b32 v4, v37 offset:5544
	ds_write_b32 v4, v38 offset:5808
	ds_write_b32 v4, v39 offset:6072
	ds_write_b32 v4, v40 offset:6336
	ds_write_b32 v4, v41 offset:6600
	ds_write_b32 v4, v42 offset:6864
	ds_write_b32 v4, v43 offset:7128
	ds_write_b32 v4, v44 offset:7392
	ds_write_b32 v4, v45 offset:7656
	ds_write_b32 v4, v46 offset:7920
	ds_write_b32 v4, v47 offset:8184
	s_waitcnt lgkmcnt(0)
	ds_read_b32 v48, v7
	ds_read_b32 v49, v7 offset:132
	ds_read_b32 v50, v7 offset:264
	ds_read_b32 v51, v7 offset:396
	ds_read_b32 v52, v7 offset:528
	ds_read_b32 v53, v7 offset:660
	ds_read_b32 v54, v7 offset:792
	ds_read_b32 v55, v7 offset:924
	ds_read_b32 v56, v7 offset:32
	ds_read_b32 v57, v7 offset:164
	ds_read_b32 v58, v7 offset:296
	ds_read_b32 v59, v7 offset:428
	ds_read_b32 v60, v7 offset:560
	ds_read_b32 v61, v7 offset:692
	ds_read_b32 v62, v7 offset:824
	ds_read_b32 v63, v7 offset:956
	ds_read_b32 v64, v7 offset:64
	ds_read_b32 v65, v7 offset:196
	ds_read_b32 v66, v7 offset:328
	ds_read_b32 v67, v7 offset:460
	ds_read_b32 v68, v7 offset:592
	ds_read_b32 v69, v7 offset:724
	ds_read_b32 v70, v7 offset:856
	ds_read_b32 v71, v7 offset:988
	ds_read_b32 v72, v7 offset:96
	ds_read_b32 v73, v7 offset:228
	ds_read_b32 v74, v7 offset:360
	ds_read_b32 v75, v7 offset:492
	ds_read_b32 v76, v7 offset:624
	ds_read_b32 v77, v7 offset:756
	ds_read_b32 v78, v7 offset:888
	ds_read_b32 v79, v7 offset:1020
	s_waitcnt lgkmcnt(0)
	v_cvt_pk_bf16_f32 v48, v48, v49
	v_cvt_pk_bf16_f32 v49, v50, v51
	v_cvt_pk_bf16_f32 v50, v52, v53
	v_cvt_pk_bf16_f32 v51, v54, v55
	global_store_dwordx4 v8, v[48:51], s[16:17]
	v_cvt_pk_bf16_f32 v56, v56, v57
	v_cvt_pk_bf16_f32 v57, v58, v59
	v_cvt_pk_bf16_f32 v58, v60, v61
	v_cvt_pk_bf16_f32 v59, v62, v63
	global_store_dwordx4 v9, v[56:59], s[16:17]
	v_cvt_pk_bf16_f32 v64, v64, v65
	v_cvt_pk_bf16_f32 v65, v66, v67
	v_cvt_pk_bf16_f32 v66, v68, v69
	v_cvt_pk_bf16_f32 v67, v70, v71
	global_store_dwordx4 v8, v[64:67], s[16:17] offset:2048
	v_cvt_pk_bf16_f32 v72, v72, v73
	v_cvt_pk_bf16_f32 v73, v74, v75
	v_cvt_pk_bf16_f32 v74, v76, v77
	v_cvt_pk_bf16_f32 v75, v78, v79
	global_store_dwordx4 v9, v[72:75], s[16:17] offset:2048
	s_add_u32 s9, s9, s19
	s_cmpk_ge_u32 s9, 0x800
	s_cbranch_scc1 .Ltc3c_lastB
; #define LAS __attribute__((address_space(3)))
; __device__ __forceinline__ void tr_load(const float* W, int N, int item, int lane, float (&wv)[32]) {
;     const int nblk = N / 32, kb = item / nblk, nb = item % nblk, k0 = 64 * kb, n0 = 32 * nb;
; #pragma unroll
;     for (int i = 0; i < 32; ++i) { const int kk = 2 * i + (lane >> 5); wv[i] = __builtin_nontemporal_load(W + (size_t)(k0 + kk) * N + n0 + (lane & 31)); }
; }
; template <int MAP, bool HASG, bool PERMW>
; __device__ __forceinline__ void tr_store(int K, int N, bf16_t* WT, LAS float* scr, int item, int lane, const float* gk) {
;     const int nblk = N / 32, kb = item / nblk, nb = item % nblk, k0 = 64 * kb, n0 = 32 * nb;
;     asm volatile("s_waitcnt lgkmcnt(0)" ::: "memory");
;     const int c = lane & 7;
;     f32x4 g0 = {1.f, 1.f, 1.f, 1.f}, g1 = {1.f, 1.f, 1.f, 1.f};
;     if (HASG) { g0 = *(const f32x4*)(gk + k0 + 8 * c); g1 = *(const f32x4*)(gk + k0 + 8 * c + 4); }
; #pragma unroll
;     for (int j = 0; j < 4; ++j) { const int n = (lane >> 3) + 8 * j; const LAS float* s = scr + (8 * c) * 33 + n;
;         u32x4 o; o.x = pk2(s[0 * 33] * g0[0], s[1 * 33] * g0[1]); o.y = pk2(s[2 * 33] * g0[2], s[3 * 33] * g0[3]); o.z = pk2(s[4 * 33] * g1[0], s[5 * 33] * g1[1]); o.w = pk2(s[6 * 33] * g1[2], s[7 * 33] * g1[3]);
;         const int wr_ = rowmap<MAP>(n0 + n), slot_ = PERMW ? ((wr_ & ~31) + invperm32(wr_ & 31)) : wr_;
;         *(u32x4*)((char*)WT + tiled_off(slot_, k0 + 8 * c, K / 64)) = o; }
;     asm volatile("s_waitcnt lgkmcnt(0)" ::: "memory");
; }
; template <int MAP, bool HASG = false, bool PERMW = false>
; __device__ __forceinline__ void transpose_mat(const float* W, int K, int N, bf16_t* WT, LAS float* scr, int gw, int ngw, int lane, const float* gk = nullptr) {
;     ...
;     for (;;) {
;         __builtin_amdgcn_sched_barrier(0);
; #pragma unroll
;         for (int i = 0; i < 32; ++i) { const int kk = 2 * i + (lane >> 5); scr[kk * 33 + (lane & 31)] = wv[i]; }
;         __builtin_amdgcn_sched_barrier(0);
;         const int nx = it + ngw;
;         if (nx < nitems) tr_load(W, N, nx, lane, wv);
;         __builtin_amdgcn_sched_barrier(0);
;         tr_store<MAP, HASG, PERMW>(K, N, WT, scr, it, lane, gk);
;         if (nx >= nitems) break;
;         it = nx;
;     }
	s_lshr_b32 s11, s9, 6
	s_and_b32 s12, s9, 63
	s_lshl_b32 s13, s11, 19
	s_lshl_b32 s14, s12, 7
	s_add_u32 s13, s13, s14
	s_add_u32 s14, s4, s13
	s_addc_u32 s15, s5, 0
	global_load_dword v16, v3, s[14:15] nt
	s_add_u32 s14, s14, 0x4000
	s_addc_u32 s15, s15, 0
	global_load_dword v17, v3, s[14:15] nt
	s_add_u32 s14, s14, 0x4000
	s_addc_u32 s15, s15, 0
	global_load_dword v18, v3, s[14:15] nt
	s_add_u32 s14, s14, 0x4000
	s_addc_u32 s15, s15, 0
	global_load_dword v19, v3, s[14:15] nt
	s_add_u32 s14, s14, 0x4000
	s_addc_u32 s15, s15, 0
	global_load_dword v20, v3, s[14:15] nt
	s_add_u32 s14, s14, 0x4000
	s_addc_u32 s15, s15, 0
	global_load_dword v21, v3, s[14:15] nt
	s_add_u32 s14, s14, 0x4000
	s_addc_u32 s15, s15, 0
	global_load_dword v22, v3, s[14:15] nt
	s_add_u32 s14, s14, 0x4000
	s_addc_u32 s15, s15, 0
	global_load_dword v23, v3, s[14:15] nt
	s_add_u32 s14, s14, 0x4000
	s_addc_u32 s15, s15, 0
	global_load_dword v24, v3, s[14:15] nt
	s_add_u32 s14, s14, 0x4000
	s_addc_u32 s15, s15, 0
	global_load_dword v25, v3, s[14:15] nt
	s_add_u32 s14, s14, 0x4000
	s_addc_u32 s15, s15, 0
	global_load_dword v26, v3, s[14:15] nt
	s_add_u32 s14, s14, 0x4000
	s_addc_u32 s15, s15, 0
	global_load_dword v27, v3, s[14:15] nt
	s_add_u32 s14, s14, 0x4000
	s_addc_u32 s15, s15, 0
	global_load_dword v28, v3, s[14:15] nt
	s_add_u32 s14, s14, 0x4000
	s_addc_u32 s15, s15, 0
	global_load_dword v29, v3, s[14:15] nt
	s_add_u32 s14, s14, 0x4000
	s_addc_u32 s15, s15, 0
	global_load_dword v30, v3, s[14:15] nt
	s_add_u32 s14, s14, 0x4000
	s_addc_u32 s15, s15, 0
	global_load_dword v31, v3, s[14:15] nt
	s_add_u32 s14, s14, 0x4000
	s_addc_u32 s15, s15, 0
	global_load_dword v32, v3, s[14:15] nt
	s_add_u32 s14, s14, 0x4000
	s_addc_u32 s15, s15, 0
	global_load_dword v33, v3, s[14:15] nt
	s_add_u32 s14, s14, 0x4000
	s_addc_u32 s15, s15, 0
	global_load_dword v34, v3, s[14:15] nt
	s_add_u32 s14, s14, 0x4000
	s_addc_u32 s15, s15, 0
	global_load_dword v35, v3, s[14:15] nt
	s_add_u32 s14, s14, 0x4000
	s_addc_u32 s15, s15, 0
	global_load_dword v36, v3, s[14:15] nt
	s_add_u32 s14, s14, 0x4000
	s_addc_u32 s15, s15, 0
	global_load_dword v37, v3, s[14:15] nt
	s_add_u32 s14, s14, 0x4000
	s_addc_u32 s15, s15, 0
	global_load_dword v38, v3, s[14:15] nt
	s_add_u32 s14, s14, 0x4000
	s_addc_u32 s15, s15, 0
	global_load_dword v39, v3, s[14:15] nt
	s_add_u32 s14, s14, 0x4000
	s_addc_u32 s15, s15, 0
	global_load_dword v40, v3, s[14:15] nt
	s_add_u32 s14, s14, 0x4000
	s_addc_u32 s15, s15, 0
	global_load_dword v41, v3, s[14:15] nt
	s_add_u32 s14, s14, 0x4000
	s_addc_u32 s15, s15, 0
	global_load_dword v42, v3, s[14:15] nt
	s_add_u32 s14, s14, 0x4000
	s_addc_u32 s15, s15, 0
	global_load_dword v43, v3, s[14:15] nt
	s_add_u32 s14, s14, 0x4000
	s_addc_u32 s15, s15, 0
	global_load_dword v44, v3, s[14:15] nt
	s_add_u32 s14, s14, 0x4000
	s_addc_u32 s15, s15, 0
	global_load_dword v45, v3, s[14:15] nt
	s_add_u32 s14, s14, 0x4000
	s_addc_u32 s15, s15, 0
	global_load_dword v46, v3, s[14:15] nt
	s_add_u32 s14, s14, 0x4000
	s_addc_u32 s15, s15, 0
	global_load_dword v47, v3, s[14:15] nt
	s_lshr_b32 s16, s12, 2
	s_mul_i32 s16, s16, 0x20
	s_add_u32 s16, s16, s11
	s_lshl_b32 s16, s16, 14
	s_and_b32 s17, s12, 3
	s_lshl_b32 s17, s17, 12
	s_add_u32 s16, s16, s17
	s_add_u32 s16, s6, s16
	s_addc_u32 s17, s7, 0
	s_waitcnt vmcnt(32)
	ds_write_b32 v4, v88
	ds_write_b32 v4, v89 offset:264
	ds_write_b32 v4, v90 offset:528
	ds_write_b32 v4, v91 offset:792
	ds_write_b32 v4, v92 offset:1056
	ds_write_b32 v4, v93 offset:1320
	ds_write_b32 v4, v94 offset:1584
	ds_write_b32 v4, v95 offset:1848
	ds_write_b32 v4, v96 offset:2112
	ds_write_b32 v4, v97 offset:2376
	ds_write_b32 v4, v98 offset:2640
	ds_write_b32 v4, v99 offset:2904
	ds_write_b32 v4, v100 offset:3168
	ds_write_b32 v4, v101 offset:3432
	ds_write_b32 v4, v102 offset:3696
	ds_write_b32 v4, v103 offset:3960
	ds_write_b32 v4, v104 offset:4224
	ds_write_b32 v4, v105 offset:4488
	ds_write_b32 v4, v106 offset:4752
	ds_write_b32 v4, v107 offset:5016
	ds_write_b32 v4, v108 offset:5280
	ds_write_b32 v4, v109 offset:5544
	ds_write_b32 v4, v110 offset:5808
	ds_write_b32 v4, v111 offset:6072
	ds_write_b32 v4, v112 offset:6336
	ds_write_b32 v4, v113 offset:6600
	ds_write_b32 v4, v114 offset:6864
	ds_write_b32 v4, v115 offset:7128
	ds_write_b32 v4, v116 offset:7392
	ds_write_b32 v4, v117 offset:7656
	ds_write_b32 v4, v118 offset:7920
	ds_write_b32 v4, v119 offset:8184
	s_waitcnt lgkmcnt(0)
	ds_read_b32 v48, v7
	ds_read_b32 v49, v7 offset:132
	ds_read_b32 v50, v7 offset:264
	ds_read_b32 v51, v7 offset:396
	ds_read_b32 v52, v7 offset:528
	ds_read_b32 v53, v7 offset:660
	ds_read_b32 v54, v7 offset:792
	ds_read_b32 v55, v7 offset:924
	ds_read_b32 v56, v7 offset:32
	ds_read_b32 v57, v7 offset:164
	ds_read_b32 v58, v7 offset:296
	ds_read_b32 v59, v7 offset:428
	ds_read_b32 v60, v7 offset:560
	ds_read_b32 v61, v7 offset:692
	ds_read_b32 v62, v7 offset:824
	ds_read_b32 v63, v7 offset:956
	ds_read_b32 v64, v7 offset:64
	ds_read_b32 v65, v7 offset:196
	ds_read_b32 v66, v7 offset:328
	ds_read_b32 v67, v7 offset:460
	ds_read_b32 v68, v7 offset:592
	ds_read_b32 v69, v7 offset:724
	ds_read_b32 v70, v7 offset:856
	ds_read_b32 v71, v7 offset:988
	ds_read_b32 v72, v7 offset:96
	ds_read_b32 v73, v7 offset:228
	ds_read_b32 v74, v7 offset:360
	ds_read_b32 v75, v7 offset:492
	ds_read_b32 v76, v7 offset:624
	ds_read_b32 v77, v7 offset:756
	ds_read_b32 v78, v7 offset:888
	ds_read_b32 v79, v7 offset:1020
	s_waitcnt lgkmcnt(0)
	v_cvt_pk_bf16_f32 v48, v48, v49
	v_cvt_pk_bf16_f32 v49, v50, v51
	v_cvt_pk_bf16_f32 v50, v52, v53
	v_cvt_pk_bf16_f32 v51, v54, v55
	global_store_dwordx4 v8, v[48:51], s[24:25]
	v_cvt_pk_bf16_f32 v56, v56, v57
	v_cvt_pk_bf16_f32 v57, v58, v59
	v_cvt_pk_bf16_f32 v58, v60, v61
	v_cvt_pk_bf16_f32 v59, v62, v63
	global_store_dwordx4 v9, v[56:59], s[24:25]
	v_cvt_pk_bf16_f32 v64, v64, v65
	v_cvt_pk_bf16_f32 v65, v66, v67
	v_cvt_pk_bf16_f32 v66, v68, v69
	v_cvt_pk_bf16_f32 v67, v70, v71
	global_store_dwordx4 v8, v[64:67], s[24:25] offset:2048
	v_cvt_pk_bf16_f32 v72, v72, v73
	v_cvt_pk_bf16_f32 v73, v74, v75
	v_cvt_pk_bf16_f32 v74, v76, v77
	v_cvt_pk_bf16_f32 v75, v78, v79
	global_store_dwordx4 v9, v[72:75], s[24:25] offset:2048
	s_branch .Ltc3c_loop

; #define LAS __attribute__((address_space(3)))
; __device__ __forceinline__ void tr_load(const float* W, int N, int item, int lane, float (&wv)[32]) {
;     const int nblk = N / 32, kb = item / nblk, nb = item % nblk, k0 = 64 * kb, n0 = 32 * nb;
; #pragma unroll
;     for (int i = 0; i < 32; ++i) { const int kk = 2 * i + (lane >> 5); wv[i] = __builtin_nontemporal_load(W + (size_t)(k0 + kk) * N + n0 + (lane & 31)); }
; }
; template <int MAP, bool HASG, bool PERMW>
; __device__ __forceinline__ void tr_store(int K, int N, bf16_t* WT, LAS float* scr, int item, int lane, const float* gk) {
;     const int nblk = N / 32, kb = item / nblk, nb = item % nblk, k0 = 64 * kb, n0 = 32 * nb;
;     asm volatile("s_waitcnt lgkmcnt(0)" ::: "memory");
;     const int c = lane & 7;
;     f32x4 g0 = {1.f, 1.f, 1.f, 1.f}, g1 = {1.f, 1.f, 1.f, 1.f};
;     if (HASG) { g0 = *(const f32x4*)(gk + k0 + 8 * c); g1 = *(const f32x4*)(gk + k0 + 8 * c + 4); }
; template <int MAP, bool HASG = false, bool PERMW = false>
; __device__ __forceinline__ void transpose_mat(const float* W, int K, int N, bf16_t* WT, LAS float* scr, int gw, int ngw, int lane, const float* gk = nullptr) {
;     ...
;     for (;;) {
;         __builtin_amdgcn_sched_barrier(0);
; #pragma unroll
;         for (int i = 0; i < 32; ++i) { const int kk = 2 * i + (lane >> 5); scr[kk * 33 + (lane & 31)] = wv[i]; }
;         __builtin_amdgcn_sched_barrier(0);
;         const int nx = it + ngw;
;         if (nx < nitems) tr_load(W, N, nx, lane, wv);
;         __builtin_amdgcn_sched_barrier(0);
;         tr_store<MAP, HASG, PERMW>(K, N, WT, scr, it, lane, gk);
;         if (nx >= nitems) break;
;         it = nx;
;     }
.Ltc3d_loop:
	s_add_u32 s9, s9, s19
	s_cmpk_ge_u32 s9, 0x1600
	s_cbranch_scc1 .Ltc3d_lastA
	s_mul_hi_u32 s11, s9, 0x2e8ba2e9
	s_lshr_b32 s11, s11, 5
	s_mul_i32 s12, s11, 0xb0
	s_sub_u32 s12, s9, s12
	s_mul_i32 s13, s11, 0x160000
	s_lshl_b32 s14, s12, 7
	s_add_u32 s13, s13, s14
	s_add_u32 s14, s4, s13
	s_addc_u32 s15, s5, 0
	global_load_dword v88, v15, s[14:15] nt
	s_add_u32 s14, s14, 0xb000
	s_addc_u32 s15, s15, 0
	global_load_dword v89, v15, s[14:15] nt
	s_add_u32 s14, s14, 0xb000
	s_addc_u32 s15, s15, 0
	global_load_dword v90, v15, s[14:15] nt
	s_add_u32 s14, s14, 0xb000
	s_addc_u32 s15, s15, 0
	global_load_dword v91, v15, s[14:15] nt
	s_add_u32 s14, s14, 0xb000
	s_addc_u32 s15, s15, 0
	global_load_dword v92, v15, s[14:15] nt
	s_add_u32 s14, s14, 0xb000
	s_addc_u32 s15, s15, 0
	global_load_dword v93, v15, s[14:15] nt
	s_add_u32 s14, s14, 0xb000
	s_addc_u32 s15, s15, 0
	global_load_dword v94, v15, s[14:15] nt
	s_add_u32 s14, s14, 0xb000
	s_addc_u32 s15, s15, 0
	global_load_dword v95, v15, s[14:15] nt
	s_add_u32 s14, s14, 0xb000
	s_addc_u32 s15, s15, 0
	global_load_dword v96, v15, s[14:15] nt
	s_add_u32 s14, s14, 0xb000
	s_addc_u32 s15, s15, 0
	global_load_dword v97, v15, s[14:15] nt
	s_add_u32 s14, s14, 0xb000
	s_addc_u32 s15, s15, 0
	global_load_dword v98, v15, s[14:15] nt
	s_add_u32 s14, s14, 0xb000
	s_addc_u32 s15, s15, 0
	global_load_dword v99, v15, s[14:15] nt
	s_add_u32 s14, s14, 0xb000
	s_addc_u32 s15, s15, 0
	global_load_dword v100, v15, s[14:15] nt
	s_add_u32 s14, s14, 0xb000
	s_addc_u32 s15, s15, 0
	global_load_dword v101, v15, s[14:15] nt
	s_add_u32 s14, s14, 0xb000
	s_addc_u32 s15, s15, 0
	global_load_dword v102, v15, s[14:15] nt
	s_add_u32 s14, s14, 0xb000
	s_addc_u32 s15, s15, 0
	global_load_dword v103, v15, s[14:15] nt
	s_add_u32 s14, s14, 0xb000
	s_addc_u32 s15, s15, 0
	global_load_dword v104, v15, s[14:15] nt
	s_add_u32 s14, s14, 0xb000
	s_addc_u32 s15, s15, 0
	global_load_dword v105, v15, s[14:15] nt
	s_add_u32 s14, s14, 0xb000
	s_addc_u32 s15, s15, 0
	global_load_dword v106, v15, s[14:15] nt
	s_add_u32 s14, s14, 0xb000
	s_addc_u32 s15, s15, 0
	global_load_dword v107, v15, s[14:15] nt
	s_add_u32 s14, s14, 0xb000
	s_addc_u32 s15, s15, 0
	global_load_dword v108, v15, s[14:15] nt
	s_add_u32 s14, s14, 0xb000
	s_addc_u32 s15, s15, 0
	global_load_dword v109, v15, s[14:15] nt
	s_add_u32 s14, s14, 0xb000
	s_addc_u32 s15, s15, 0
	global_load_dword v110, v15, s[14:15] nt
	s_add_u32 s14, s14, 0xb000
	s_addc_u32 s15, s15, 0
	global_load_dword v111, v15, s[14:15] nt
	s_add_u32 s14, s14, 0xb000
	s_addc_u32 s15, s15, 0
	global_load_dword v112, v15, s[14:15] nt
	s_add_u32 s14, s14, 0xb000
	s_addc_u32 s15, s15, 0
	global_load_dword v113, v15, s[14:15] nt
	s_add_u32 s14, s14, 0xb000
	s_addc_u32 s15, s15, 0
	global_load_dword v114, v15, s[14:15] nt
	s_add_u32 s14, s14, 0xb000
	s_addc_u32 s15, s15, 0
	global_load_dword v115, v15, s[14:15] nt
	s_add_u32 s14, s14, 0xb000
	s_addc_u32 s15, s15, 0
	global_load_dword v116, v15, s[14:15] nt
	s_add_u32 s14, s14, 0xb000
	s_addc_u32 s15, s15, 0
	global_load_dword v117, v15, s[14:15] nt
	s_add_u32 s14, s14, 0xb000
	s_addc_u32 s15, s15, 0
	global_load_dword v118, v15, s[14:15] nt
	s_add_u32 s14, s14, 0xb000
	s_addc_u32 s15, s15, 0
	global_load_dword v119, v15, s[14:15] nt
	s_lshl_b32 s14, s11, 8
	s_add_u32 s14, s20, s14
	s_addc_u32 s15, s21, 0
	global_load_dwordx4 v[120:123], v14, s[14:15]
	global_load_dwordx4 v[124:127], v14, s[14:15] offset:16
	s_lshr_b32 s24, s12, 2
	s_lshl_b32 s24, s24, 1
	s_add_u32 s24, s24, 1
	s_lshl_b32 s24, s24, 5
	s_add_u32 s24, s24, s11
	s_lshl_b32 s24, s24, 14
	s_and_b32 s25, s12, 3
	s_lshl_b32 s25, s25, 12
	s_add_u32 s24, s24, s25
	s_add_u32 s24, s6, s24
	s_addc_u32 s25, s7, 0
	s_waitcnt vmcnt(34)
	ds_write_b32 v4, v16
	ds_write_b32 v4, v17 offset:264
	ds_write_b32 v4, v18 offset:528
	ds_write_b32 v4, v19 offset:792
	ds_write_b32 v4, v20 offset:1056
	ds_write_b32 v4, v21 offset:1320
	ds_write_b32 v4, v22 offset:1584
	ds_write_b32 v4, v23 offset:1848
	ds_write_b32 v4, v24 offset:2112
	ds_write_b32 v4, v25 offset:2376
	ds_write_b32 v4, v26 offset:2640
	ds_write_b32 v4, v27 offset:2904
	ds_write_b32 v4, v28 offset:3168
	ds_write_b32 v4, v29 offset:3432
	ds_write_b32 v4, v30 offset:3696
	ds_write_b32 v4, v31 offset:3960
	ds_write_b32 v4, v32 offset:4224
	ds_write_b32 v4, v33 offset:4488
	ds_write_b32 v4, v34 offset:4752
	ds_write_b32 v4, v35 offset:5016
	ds_write_b32 v4, v36 offset:5280
	ds_write_b32 v4, v37 offset:5544
	ds_write_b32 v4, v38 offset:5808
	ds_write_b32 v4, v39 offset:6072
	ds_write_b32 v4, v40 offset:6336
	ds_write_b32 v4, v41 offset:6600
	ds_write_b32 v4, v42 offset:6864
	ds_write_b32 v4, v43 offset:7128
	ds_write_b32 v4, v44 offset:7392
	ds_write_b32 v4, v45 offset:7656
	ds_write_b32 v4, v46 offset:7920
	ds_write_b32 v4, v47 offset:8184
	s_waitcnt lgkmcnt(0)
	ds_read_b32 v48, v7
	ds_read_b32 v49, v7 offset:132
	ds_read_b32 v50, v7 offset:264
	ds_read_b32 v51, v7 offset:396
	ds_read_b32 v52, v7 offset:528
	ds_read_b32 v53, v7 offset:660
	ds_read_b32 v54, v7 offset:792
	ds_read_b32 v55, v7 offset:924
	ds_read_b32 v56, v7 offset:32
	ds_read_b32 v57, v7 offset:164
	ds_read_b32 v58, v7 offset:296
	ds_read_b32 v59, v7 offset:428
	ds_read_b32 v60, v7 offset:560
	ds_read_b32 v61, v7 offset:692
	ds_read_b32 v62, v7 offset:824
	ds_read_b32 v63, v7 offset:956
	ds_read_b32 v64, v7 offset:64
	ds_read_b32 v65, v7 offset:196
	ds_read_b32 v66, v7 offset:328
	ds_read_b32 v67, v7 offset:460
	ds_read_b32 v68, v7 offset:592
	ds_read_b32 v69, v7 offset:724
	ds_read_b32 v70, v7 offset:856
	ds_read_b32 v71, v7 offset:988
	ds_read_b32 v72, v7 offset:96
	ds_read_b32 v73, v7 offset:228
	ds_read_b32 v74, v7 offset:360
	ds_read_b32 v75, v7 offset:492
	ds_read_b32 v76, v7 offset:624
	ds_read_b32 v77, v7 offset:756
	ds_read_b32 v78, v7 offset:888
	ds_read_b32 v79, v7 offset:1020
	s_waitcnt lgkmcnt(0)
; #define LAS __attribute__((address_space(3)))
; __device__ __forceinline__ unsigned pk2(float lo, float hi) { f32x2 f = {lo, hi}; bf16x2_t b = __builtin_convertvector(f, bf16x2_t); return __builtin_bit_cast(unsigned, b); }
; template <int MAP, bool HASG, bool PERMW>
; __device__ __forceinline__ void tr_store(int K, int N, bf16_t* WT, LAS float* scr, int item, int lane, const float* gk) {
;     ...
;     for (int j = 0; j < 4; ++j) { const int n = (lane >> 3) + 8 * j; const LAS float* s = scr + (8 * c) * 33 + n;
;         u32x4 o; o.x = pk2(s[0 * 33] * g0[0], s[1 * 33] * g0[1]); o.y = pk2(s[2 * 33] * g0[2], s[3 * 33] * g0[3]); o.z = pk2(s[4 * 33] * g1[0], s[5 * 33] * g1[1]); o.w = pk2(s[6 * 33] * g1[2], s[7 * 33] * g1[3]);
;         const int wr_ = rowmap<MAP>(n0 + n), slot_ = PERMW ? ((wr_ & ~31) + invperm32(wr_ & 31)) : wr_;
;         *(u32x4*)((char*)WT + tiled_off(slot_, k0 + 8 * c, K / 64)) = o; }
; template <int MAP, bool HASG = false, bool PERMW = false>
; __device__ __forceinline__ void transpose_mat(const float* W, int K, int N, bf16_t* WT, LAS float* scr, int gw, int ngw, int lane, const float* gk = nullptr) {
;     ...
;         if (nx < nitems) tr_load(W, N, nx, lane, wv);
;         __builtin_amdgcn_sched_barrier(0);
;         tr_store<MAP, HASG, PERMW>(K, N, WT, scr, it, lane, gk);
	v_mul_f32_e32 v48, v48, v80
	v_mul_f32_e32 v49, v49, v81
	v_mul_f32_e32 v50, v50, v82
	v_mul_f32_e32 v51, v51, v83
	v_mul_f32_e32 v52, v52, v84
	v_mul_f32_e32 v53, v53, v85
	v_mul_f32_e32 v54, v54, v86
	v_mul_f32_e32 v55, v55, v87
	v_cvt_pk_bf16_f32 v48, v48, v49
	v_cvt_pk_bf16_f32 v49, v50, v51
	v_cvt_pk_bf16_f32 v50, v52, v53
	v_cvt_pk_bf16_f32 v51, v54, v55
	global_store_dwordx4 v10, v[48:51], s[16:17]
	v_mul_f32_e32 v56, v56, v80
	v_mul_f32_e32 v57, v57, v81
	v_mul_f32_e32 v58, v58, v82
	v_mul_f32_e32 v59, v59, v83
	v_mul_f32_e32 v60, v60, v84
	v_mul_f32_e32 v61, v61, v85
	v_mul_f32_e32 v62, v62, v86
	v_mul_f32_e32 v63, v63, v87
	v_cvt_pk_bf16_f32 v56, v56, v57
	v_cvt_pk_bf16_f32 v57, v58, v59
	v_cvt_pk_bf16_f32 v58, v60, v61
	v_cvt_pk_bf16_f32 v59, v62, v63
	global_store_dwordx4 v10, v[56:59], s[16:17] offset:256
	v_mul_f32_e32 v64, v64, v80
	v_mul_f32_e32 v65, v65, v81
	v_mul_f32_e32 v66, v66, v82
	v_mul_f32_e32 v67, v67, v83
	v_mul_f32_e32 v68, v68, v84
	v_mul_f32_e32 v69, v69, v85
	v_mul_f32_e32 v70, v70, v86
	v_mul_f32_e32 v71, v71, v87
	v_cvt_pk_bf16_f32 v64, v64, v65
	v_cvt_pk_bf16_f32 v65, v66, v67
	v_cvt_pk_bf16_f32 v66, v68, v69
	v_cvt_pk_bf16_f32 v67, v70, v71
	global_store_dwordx4 v11, v[64:67], s[16:17] offset:512
	v_mul_f32_e32 v72, v72, v80
	v_mul_f32_e32 v73, v73, v81
	v_mul_f32_e32 v74, v74, v82
	v_mul_f32_e32 v75, v75, v83
	v_mul_f32_e32 v76, v76, v84
	v_mul_f32_e32 v77, v77, v85
	v_mul_f32_e32 v78, v78, v86
	v_mul_f32_e32 v79, v79, v87
	v_cvt_pk_bf16_f32 v72, v72, v73
	v_cvt_pk_bf16_f32 v73, v74, v75
	v_cvt_pk_bf16_f32 v74, v76, v77
	v_cvt_pk_bf16_f32 v75, v78, v79
	global_store_dwordx4 v11, v[72:75], s[16:17] offset:768
	s_add_u32 s9, s9, s19
	s_cmpk_ge_u32 s9, 0x1600
	s_cbranch_scc1 .Ltc3d_lastB
	s_mul_hi_u32 s11, s9, 0x2e8ba2e9
	s_lshr_b32 s11, s11, 5
	s_mul_i32 s12, s11, 0xb0
	s_sub_u32 s12, s9, s12
	s_mul_i32 s13, s11, 0x160000
	s_lshl_b32 s14, s12, 7
	s_add_u32 s13, s13, s14
	s_add_u32 s14, s4, s13
	s_addc_u32 s15, s5, 0
	global_load_dword v16, v15, s[14:15] nt
	s_add_u32 s14, s14, 0xb000
	s_addc_u32 s15, s15, 0
	global_load_dword v17, v15, s[14:15] nt
	s_add_u32 s14, s14, 0xb000
	s_addc_u32 s15, s15, 0
	global_load_dword v18, v15, s[14:15] nt
	s_add_u32 s14, s14, 0xb000
	s_addc_u32 s15, s15, 0
	global_load_dword v19, v15, s[14:15] nt
	s_add_u32 s14, s14, 0xb000
	s_addc_u32 s15, s15, 0
	global_load_dword v20, v15, s[14:15] nt
	s_add_u32 s14, s14, 0xb000
	s_addc_u32 s15, s15, 0
	global_load_dword v21, v15, s[14:15] nt
	s_add_u32 s14, s14, 0xb000
	s_addc_u32 s15, s15, 0
	global_load_dword v22, v15, s[14:15] nt
	s_add_u32 s14, s14, 0xb000
	s_addc_u32 s15, s15, 0
	global_load_dword v23, v15, s[14:15] nt
	s_add_u32 s14, s14, 0xb000
	s_addc_u32 s15, s15, 0
	global_load_dword v24, v15, s[14:15] nt
	s_add_u32 s14, s14, 0xb000
	s_addc_u32 s15, s15, 0
	global_load_dword v25, v15, s[14:15] nt
	s_add_u32 s14, s14, 0xb000
	s_addc_u32 s15, s15, 0
	global_load_dword v26, v15, s[14:15] nt
	s_add_u32 s14, s14, 0xb000
	s_addc_u32 s15, s15, 0
	global_load_dword v27, v15, s[14:15] nt
	s_add_u32 s14, s14, 0xb000
	s_addc_u32 s15, s15, 0
	global_load_dword v28, v15, s[14:15] nt
	s_add_u32 s14, s14, 0xb000
	s_addc_u32 s15, s15, 0
	global_load_dword v29, v15, s[14:15] nt
	s_add_u32 s14, s14, 0xb000
	s_addc_u32 s15, s15, 0
	global_load_dword v30, v15, s[14:15] nt
	s_add_u32 s14, s14, 0xb000
	s_addc_u32 s15, s15, 0
	global_load_dword v31, v15, s[14:15] nt
	s_add_u32 s14, s14, 0xb000
	s_addc_u32 s15, s15, 0
	global_load_dword v32, v15, s[14:15] nt
	s_add_u32 s14, s14, 0xb000
	s_addc_u32 s15, s15, 0
	global_load_dword v33, v15, s[14:15] nt
	s_add_u32 s14, s14, 0xb000
	s_addc_u32 s15, s15, 0
	global_load_dword v34, v15, s[14:15] nt
	s_add_u32 s14, s14, 0xb000
	s_addc_u32 s15, s15, 0
	global_load_dword v35, v15, s[14:15] nt
	s_add_u32 s14, s14, 0xb000
	s_addc_u32 s15, s15, 0
	global_load_dword v36, v15, s[14:15] nt
	s_add_u32 s14, s14, 0xb000
	s_addc_u32 s15, s15, 0
	global_load_dword v37, v15, s[14:15] nt
	s_add_u32 s14, s14, 0xb000
	s_addc_u32 s15, s15, 0
	global_load_dword v38, v15, s[14:15] nt
	s_add_u32 s14, s14, 0xb000
	s_addc_u32 s15, s15, 0
	global_load_dword v39, v15, s[14:15] nt
	s_add_u32 s14, s14, 0xb000
	s_addc_u32 s15, s15, 0
	global_load_dword v40, v15, s[14:15] nt
	s_add_u32 s14, s14, 0xb000
	s_addc_u32 s15, s15, 0
	global_load_dword v41, v15, s[14:15] nt
	s_add_u32 s14, s14, 0xb000
	s_addc_u32 s15, s15, 0
	global_load_dword v42, v15, s[14:15] nt
	s_add_u32 s14, s14, 0xb000
	s_addc_u32 s15, s15, 0
	global_load_dword v43, v15, s[14:15] nt
	s_add_u32 s14, s14, 0xb000
	s_addc_u32 s15, s15, 0
	global_load_dword v44, v15, s[14:15] nt
	s_add_u32 s14, s14, 0xb000
	s_addc_u32 s15, s15, 0
	global_load_dword v45, v15, s[14:15] nt
	s_add_u32 s14, s14, 0xb000
	s_addc_u32 s15, s15, 0
	global_load_dword v46, v15, s[14:15] nt
	s_add_u32 s14, s14, 0xb000
	s_addc_u32 s15, s15, 0
	global_load_dword v47, v15, s[14:15] nt
	s_lshl_b32 s14, s11, 8
	s_add_u32 s14, s20, s14
	s_addc_u32 s15, s21, 0
	global_load_dwordx4 v[80:83], v14, s[14:15]
	global_load_dwordx4 v[84:87], v14, s[14:15] offset:16
	s_lshr_b32 s16, s12, 2
	s_lshl_b32 s16, s16, 1
	s_add_u32 s16, s16, 1
	s_lshl_b32 s16, s16, 5
	s_add_u32 s16, s16, s11
	s_lshl_b32 s16, s16, 14
	s_and_b32 s17, s12, 3
	s_lshl_b32 s17, s17, 12
	s_add_u32 s16, s16, s17
	s_add_u32 s16, s6, s16
	s_addc_u32 s17, s7, 0
	s_waitcnt vmcnt(34)
; #define LAS __attribute__((address_space(3)))
; __device__ __forceinline__ unsigned pk2(float lo, float hi) { f32x2 f = {lo, hi}; bf16x2_t b = __builtin_convertvector(f, bf16x2_t); return __builtin_bit_cast(unsigned, b); }
; template <int MAP, bool HASG, bool PERMW>
; __device__ __forceinline__ void tr_store(int K, int N, bf16_t* WT, LAS float* scr, int item, int lane, const float* gk) {
;     ...
;     for (int j = 0; j < 4; ++j) { const int n = (lane >> 3) + 8 * j; const LAS float* s = scr + (8 * c) * 33 + n;
;         u32x4 o; o.x = pk2(s[0 * 33] * g0[0], s[1 * 33] * g0[1]); o.y = pk2(s[2 * 33] * g0[2], s[3 * 33] * g0[3]); o.z = pk2(s[4 * 33] * g1[0], s[5 * 33] * g1[1]); o.w = pk2(s[6 * 33] * g1[2], s[7 * 33] * g1[3]);
;         const int wr_ = rowmap<MAP>(n0 + n), slot_ = PERMW ? ((wr_ & ~31) + invperm32(wr_ & 31)) : wr_;
;         *(u32x4*)((char*)WT + tiled_off(slot_, k0 + 8 * c, K / 64)) = o; }
; template <int MAP, bool HASG = false, bool PERMW = false>
; __device__ __forceinline__ void transpose_mat(const float* W, int K, int N, bf16_t* WT, LAS float* scr, int gw, int ngw, int lane, const float* gk = nullptr) {
;     ...
;         for (int i = 0; i < 32; ++i) { const int kk = 2 * i + (lane >> 5); scr[kk * 33 + (lane & 31)] = wv[i]; }
	ds_write_b32 v4, v88
	ds_write_b32 v4, v89 offset:264
	ds_write_b32 v4, v90 offset:528
	ds_write_b32 v4, v91 offset:792
	ds_write_b32 v4, v92 offset:1056
	ds_write_b32 v4, v93 offset:1320
	ds_write_b32 v4, v94 offset:1584
	ds_write_b32 v4, v95 offset:1848
	ds_write_b32 v4, v96 offset:2112
	ds_write_b32 v4, v97 offset:2376
	ds_write_b32 v4, v98 offset:2640
	ds_write_b32 v4, v99 offset:2904
	ds_write_b32 v4, v100 offset:3168
	ds_write_b32 v4, v101 offset:3432
	ds_write_b32 v4, v102 offset:3696
	ds_write_b32 v4, v103 offset:3960
	ds_write_b32 v4, v104 offset:4224
	ds_write_b32 v4, v105 offset:4488
	ds_write_b32 v4, v106 offset:4752
	ds_write_b32 v4, v107 offset:5016
	ds_write_b32 v4, v108 offset:5280
	ds_write_b32 v4, v109 offset:5544
	ds_write_b32 v4, v110 offset:5808
	ds_write_b32 v4, v111 offset:6072
	ds_write_b32 v4, v112 offset:6336
	ds_write_b32 v4, v113 offset:6600
	ds_write_b32 v4, v114 offset:6864
	ds_write_b32 v4, v115 offset:7128
	ds_write_b32 v4, v116 offset:7392
	ds_write_b32 v4, v117 offset:7656
	ds_write_b32 v4, v118 offset:7920
	ds_write_b32 v4, v119 offset:8184
	s_waitcnt lgkmcnt(0)
	ds_read_b32 v48, v7
	ds_read_b32 v49, v7 offset:132
	ds_read_b32 v50, v7 offset:264
	ds_read_b32 v51, v7 offset:396
	ds_read_b32 v52, v7 offset:528
	ds_read_b32 v53, v7 offset:660
	ds_read_b32 v54, v7 offset:792
	ds_read_b32 v55, v7 offset:924
	ds_read_b32 v56, v7 offset:32
	ds_read_b32 v57, v7 offset:164
	ds_read_b32 v58, v7 offset:296
	ds_read_b32 v59, v7 offset:428
	ds_read_b32 v60, v7 offset:560
	ds_read_b32 v61, v7 offset:692
	ds_read_b32 v62, v7 offset:824
	ds_read_b32 v63, v7 offset:956
	ds_read_b32 v64, v7 offset:64
	ds_read_b32 v65, v7 offset:196
	ds_read_b32 v66, v7 offset:328
	ds_read_b32 v67, v7 offset:460
	ds_read_b32 v68, v7 offset:592
	ds_read_b32 v69, v7 offset:724
	ds_read_b32 v70, v7 offset:856
	ds_read_b32 v71, v7 offset:988
	ds_read_b32 v72, v7 offset:96
	ds_read_b32 v73, v7 offset:228
	ds_read_b32 v74, v7 offset:360
	ds_read_b32 v75, v7 offset:492
	ds_read_b32 v76, v7 offset:624
	ds_read_b32 v77, v7 offset:756
	ds_read_b32 v78, v7 offset:888
	ds_read_b32 v79, v7 offset:1020
	s_waitcnt lgkmcnt(0)
	v_mul_f32_e32 v48, v48, v120
	v_mul_f32_e32 v49, v49, v121
	v_mul_f32_e32 v50, v50, v122
	v_mul_f32_e32 v51, v51, v123
	v_mul_f32_e32 v52, v52, v124
	v_mul_f32_e32 v53, v53, v125
	v_mul_f32_e32 v54, v54, v126
	v_mul_f32_e32 v55, v55, v127
	v_cvt_pk_bf16_f32 v48, v48, v49
	v_cvt_pk_bf16_f32 v49, v50, v51
	v_cvt_pk_bf16_f32 v50, v52, v53
	v_cvt_pk_bf16_f32 v51, v54, v55
	global_store_dwordx4 v10, v[48:51], s[24:25]
	v_mul_f32_e32 v56, v56, v120
	v_mul_f32_e32 v57, v57, v121
	v_mul_f32_e32 v58, v58, v122
	v_mul_f32_e32 v59, v59, v123
	v_mul_f32_e32 v60, v60, v124
	v_mul_f32_e32 v61, v61, v125
	v_mul_f32_e32 v62, v62, v126
	v_mul_f32_e32 v63, v63, v127
	v_cvt_pk_bf16_f32 v56, v56, v57
	v_cvt_pk_bf16_f32 v57, v58, v59
	v_cvt_pk_bf16_f32 v58, v60, v61
	v_cvt_pk_bf16_f32 v59, v62, v63
	global_store_dwordx4 v10, v[56:59], s[24:25] offset:256
	v_mul_f32_e32 v64, v64, v120
	v_mul_f32_e32 v65, v65, v121
	v_mul_f32_e32 v66, v66, v122
	v_mul_f32_e32 v67, v67, v123
	v_mul_f32_e32 v68, v68, v124
	v_mul_f32_e32 v69, v69, v125
	v_mul_f32_e32 v70, v70, v126
	v_mul_f32_e32 v71, v71, v127
	v_cvt_pk_bf16_f32 v64, v64, v65
	v_cvt_pk_bf16_f32 v65, v66, v67
	v_cvt_pk_bf16_f32 v66, v68, v69
	v_cvt_pk_bf16_f32 v67, v70, v71
	global_store_dwordx4 v11, v[64:67], s[24:25] offset:512
	v_mul_f32_e32 v72, v72, v120
	v_mul_f32_e32 v73, v73, v121
	v_mul_f32_e32 v74, v74, v122
	v_mul_f32_e32 v75, v75, v123
	v_mul_f32_e32 v76, v76, v124
	v_mul_f32_e32 v77, v77, v125
	v_mul_f32_e32 v78, v78, v126
	v_mul_f32_e32 v79, v79, v127
	v_cvt_pk_bf16_f32 v72, v72, v73
	v_cvt_pk_bf16_f32 v73, v74, v75
	v_cvt_pk_bf16_f32 v74, v76, v77
	v_cvt_pk_bf16_f32 v75, v78, v79
	global_store_dwordx4 v11, v[72:75], s[24:25] offset:768
	s_branch .Ltc3d_loop

; #define LAS __attribute__((address_space(3)))
; __device__ __forceinline__ void tr_load(const float* W, int N, int item, int lane, float (&wv)[32]) {
;     const int nblk = N / 32, kb = item / nblk, nb = item % nblk, k0 = 64 * kb, n0 = 32 * nb;
; #pragma unroll
;     for (int i = 0; i < 32; ++i) { const int kk = 2 * i + (lane >> 5); wv[i] = __builtin_nontemporal_load(W + (size_t)(k0 + kk) * N + n0 + (lane & 31)); }
; }
; template <int MAP, bool HASG, bool PERMW>
; __device__ __forceinline__ void tr_store(int K, int N, bf16_t* WT, LAS float* scr, int item, int lane, const float* gk) {
;     const int nblk = N / 32, kb = item / nblk, nb = item % nblk, k0 = 64 * kb, n0 = 32 * nb;
; template <int MAP, bool HASG = false, bool PERMW = false>
; __device__ __forceinline__ void transpose_mat(const float* W, int K, int N, bf16_t* WT, LAS float* scr, int gw, int ngw, int lane, const float* gk = nullptr) {
;     const int nitems = (K / 64) * (N / 32);
;     int it = gw;
;     if (it >= nitems) return;
;     float wv[32];
;     tr_load(W, N, it, lane, wv);
.LBB0_826:
	s_lshr_b32 vcc_lo, s78, 1
	s_cmp_lt_u32 s2, vcc_lo
	s_cbranch_scc1 .Ltc2_done
	v_writelane_b32 v255, s4, 24
	v_writelane_b32 v255, s5, 25
	v_writelane_b32 v255, s6, 26
	v_writelane_b32 v255, s7, 27
	v_writelane_b32 v255, s8, 28
	v_writelane_b32 v255, s9, 29
	v_writelane_b32 v255, s10, 30
	v_writelane_b32 v255, s11, 31
	v_writelane_b32 v255, s12, 32
	v_writelane_b32 v255, s13, 33
	v_writelane_b32 v255, s14, 34
	v_writelane_b32 v255, s15, 35
	v_writelane_b32 v255, s16, 36
	v_writelane_b32 v255, s17, 37
	v_writelane_b32 v255, s18, 38
	v_writelane_b32 v255, s19, 39
	v_writelane_b32 v255, s20, 40
	v_writelane_b32 v255, s21, 41
	v_writelane_b32 v255, s22, 42
	v_writelane_b32 v255, s23, 43
	v_writelane_b32 v255, s24, 44
	v_writelane_b32 v255, s25, 45
	v_writelane_b32 v255, s26, 46
	v_writelane_b32 v255, s27, 47
	v_writelane_b32 v255, s28, 48
	v_writelane_b32 v255, s29, 49
	v_readfirstlane_b32 s8, v234
	s_nop 3
	s_lshr_b32 s8, s8, 6
	s_lshr_b32 s19, s78, 1
	s_sub_u32 s18, s2, s19
	s_lshl_b32 s18, s18, 3
	s_add_u32 s18, s18, s8
	s_sub_u32 s19, s78, s19
	s_lshl_b32 s19, s19, 3
	s_mul_i32 s10, s8, 0x2100
	v_and_b32_e32 v0, 63, v234
	v_and_b32_e32 v1, 31, v0
	v_lshrrev_b32_e32 v2, 5, v0
	v_lshlrev_b32_e32 v3, 13, v2
	v_lshl_add_u32 v3, v1, 2, v3
	v_mul_u32_u24_e32 v4, 33, v2
	v_add_u32_e32 v4, v4, v1
	v_lshl_add_u32 v4, v4, 2, s10
	v_and_b32_e32 v5, 7, v0
	v_lshrrev_b32_e32 v6, 3, v0
	v_mul_u32_u24_e32 v7, 0x108, v5
	v_add_u32_e32 v7, v7, v6
	v_lshl_add_u32 v7, v7, 2, s10
	v_lshrrev_b32_e32 v12, 2, v5
	v_lshlrev_b32_e32 v12, 10, v12
	v_and_b32_e32 v13, 3, v5
	v_lshl_add_u32 v12, v13, 4, v12
	v_lshl_add_u32 v8, v6, 6, v12
	v_xor_b32_e32 v9, 32, v8
	v_add_u32_e32 v9, 0x200, v9
	v_and_b32_e32 v13, 3, v6
	v_lshl_add_u32 v10, v13, 6, v12
	v_bfe_u32 v13, v6, 2, 1
	v_lshl_add_u32 v10, v13, 11, v10
	v_xor_b32_e32 v11, 32, v10
	v_lshlrev_b32_e32 v14, 5, v5
	v_mul_u32_u24_e32 v15, 0x5800, v2
	v_lshl_add_u32 v15, v1, 2, v15
	v_mul_u32_u24_e32 v12, 0xd000, v2
	v_lshl_add_u32 v12, v1, 2, v12
	v_readlane_b32 s4, v254, 10
	v_readlane_b32 s5, v254, 11
	s_nop 3
	s_and_b32 s6, s60, 0x2c00000
	s_add_u32 s4, s4, s6
	s_addc_u32 s5, s5, 0
	s_add_u32 s6, s76, 0xb600000
	s_addc_u32 s7, s77, 0
	s_mov_b32 s9, s18
	s_cmpk_ge_u32 s9, 0x1600
	s_cbranch_scc1 .Ltc2a_exit
	s_lshr_b32 s11, s9, 6
	s_and_b32 s12, s9, 63
	s_lshl_b32 s13, s11, 19
	s_lshl_b32 s14, s12, 7
	s_add_u32 s13, s13, s14
	s_add_u32 s14, s4, s13
	s_addc_u32 s15, s5, 0
	global_load_dword v16, v3, s[14:15] nt
	s_add_u32 s14, s14, 0x4000
	s_addc_u32 s15, s15, 0
	global_load_dword v17, v3, s[14:15] nt
	s_add_u32 s14, s14, 0x4000
	s_addc_u32 s15, s15, 0
	global_load_dword v18, v3, s[14:15] nt
	s_add_u32 s14, s14, 0x4000
	s_addc_u32 s15, s15, 0
	global_load_dword v19, v3, s[14:15] nt
	s_add_u32 s14, s14, 0x4000
	s_addc_u32 s15, s15, 0
	global_load_dword v20, v3, s[14:15] nt
	s_add_u32 s14, s14, 0x4000
	s_addc_u32 s15, s15, 0
	global_load_dword v21, v3, s[14:15] nt
	s_add_u32 s14, s14, 0x4000
	s_addc_u32 s15, s15, 0
	global_load_dword v22, v3, s[14:15] nt
	s_add_u32 s14, s14, 0x4000
	s_addc_u32 s15, s15, 0
	global_load_dword v23, v3, s[14:15] nt
	s_add_u32 s14, s14, 0x4000
	s_addc_u32 s15, s15, 0
	global_load_dword v24, v3, s[14:15] nt
	s_add_u32 s14, s14, 0x4000
	s_addc_u32 s15, s15, 0
	global_load_dword v25, v3, s[14:15] nt
	s_add_u32 s14, s14, 0x4000
	s_addc_u32 s15, s15, 0
	global_load_dword v26, v3, s[14:15] nt
	s_add_u32 s14, s14, 0x4000
	s_addc_u32 s15, s15, 0
	global_load_dword v27, v3, s[14:15] nt
	s_add_u32 s14, s14, 0x4000
	s_addc_u32 s15, s15, 0
	global_load_dword v28, v3, s[14:15] nt
	s_add_u32 s14, s14, 0x4000
	s_addc_u32 s15, s15, 0
	global_load_dword v29, v3, s[14:15] nt
	s_add_u32 s14, s14, 0x4000
	s_addc_u32 s15, s15, 0
	global_load_dword v30, v3, s[14:15] nt
	s_add_u32 s14, s14, 0x4000
	s_addc_u32 s15, s15, 0
	global_load_dword v31, v3, s[14:15] nt
	s_add_u32 s14, s14, 0x4000
	s_addc_u32 s15, s15, 0
	global_load_dword v32, v3, s[14:15] nt
	s_add_u32 s14, s14, 0x4000
	s_addc_u32 s15, s15, 0
	global_load_dword v33, v3, s[14:15] nt
	s_add_u32 s14, s14, 0x4000
	s_addc_u32 s15, s15, 0
	global_load_dword v34, v3, s[14:15] nt
	s_add_u32 s14, s14, 0x4000
	s_addc_u32 s15, s15, 0
	global_load_dword v35, v3, s[14:15] nt
	s_add_u32 s14, s14, 0x4000
	s_addc_u32 s15, s15, 0
	global_load_dword v36, v3, s[14:15] nt
	s_add_u32 s14, s14, 0x4000
	s_addc_u32 s15, s15, 0
	global_load_dword v37, v3, s[14:15] nt
	s_add_u32 s14, s14, 0x4000
	s_addc_u32 s15, s15, 0
	global_load_dword v38, v3, s[14:15] nt
	s_add_u32 s14, s14, 0x4000
	s_addc_u32 s15, s15, 0
	global_load_dword v39, v3, s[14:15] nt
	s_add_u32 s14, s14, 0x4000
	s_addc_u32 s15, s15, 0
	global_load_dword v40, v3, s[14:15] nt
	s_add_u32 s14, s14, 0x4000
	s_addc_u32 s15, s15, 0
	global_load_dword v41, v3, s[14:15] nt
	s_add_u32 s14, s14, 0x4000
	s_addc_u32 s15, s15, 0
	global_load_dword v42, v3, s[14:15] nt
	s_add_u32 s14, s14, 0x4000
	s_addc_u32 s15, s15, 0
	global_load_dword v43, v3, s[14:15] nt
	s_add_u32 s14, s14, 0x4000
	s_addc_u32 s15, s15, 0
	global_load_dword v44, v3, s[14:15] nt
	s_add_u32 s14, s14, 0x4000
	s_addc_u32 s15, s15, 0
	global_load_dword v45, v3, s[14:15] nt
	s_add_u32 s14, s14, 0x4000
	s_addc_u32 s15, s15, 0
	global_load_dword v46, v3, s[14:15] nt
	s_add_u32 s14, s14, 0x4000
	s_addc_u32 s15, s15, 0
	global_load_dword v47, v3, s[14:15] nt
	s_lshr_b32 s16, s12, 2
	s_mul_i32 s16, s16, 0x58
	s_add_u32 s16, s16, s11
	s_lshl_b32 s16, s16, 14
	s_and_b32 s17, s12, 3
	s_lshl_b32 s17, s17, 12
	s_add_u32 s16, s16, s17
	s_add_u32 s16, s6, s16
	s_addc_u32 s17, s7, 0
